# write-through (sc1) epilogue stores in the proj, merge, W_o and down GEMMs so the grid barrier's L2 write-back finds little dirty data
# baseline (speedup 1.0000x reference)
.LBB0_425:
	v_add_u32_e32 v176, s63, v205
	v_ashrrev_i32_e32 v177, 31, v176
	v_mul_lo_u32 v171, v171, s70
	v_mul_lo_u32 v189, v170, s71
	v_mad_u64_u32 v[202:203], s[2:3], v170, s70, 0
	v_lshl_add_u64 v[176:177], v[176:177], 1, s[48:49]
	v_add3_u32 v203, v203, v189, v171
	v_lshl_add_u64 v[202:203], v[202:203], 1, v[176:177]
	s_and_b64 vcc, exec, s[42:43]
	v_cvt_pk_bf16_f32 v156, v156, v157
	v_cvt_pk_bf16_f32 v157, v158, v159
	v_cvt_pk_bf16_f32 v158, v152, v153
	v_cvt_pk_bf16_f32 v159, v154, v155
	global_store_dwordx4 v[202:203], v[156:159], off sc1
	s_cbranch_vccnz .LBB0_427
	v_pk_fma_f32 v[150:151], v[66:67], v[188:189], v[150:151] op_sel_hi:[1,0,1] neg_lo:[1,0,0] neg_hi:[1,0,0]
	v_pk_fma_f32 v[144:145], v[68:69], v[188:189], v[144:145] op_sel_hi:[1,0,1] neg_lo:[1,0,0] neg_hi:[1,0,0]
	v_pk_fma_f32 v[146:147], v[70:71], v[188:189], v[146:147] op_sel_hi:[1,0,1] neg_lo:[1,0,0] neg_hi:[1,0,0]
	v_pk_fma_f32 v[148:149], v[64:65], v[188:189], v[148:149] op_sel_hi:[1,0,1] neg_lo:[1,0,0] neg_hi:[1,0,0]
	v_pk_fma_f32 v[146:147], v[190:191], v[146:147], v[78:79] op_sel_hi:[0,1,1]
	v_pk_fma_f32 v[148:149], v[190:191], v[148:149], v[72:73] op_sel_hi:[0,1,1]
	v_pk_fma_f32 v[144:145], v[190:191], v[144:145], v[76:77] op_sel_hi:[0,1,1]
	v_pk_fma_f32 v[150:151], v[190:191], v[150:151], v[74:75] op_sel_hi:[0,1,1]

.LBB0_429:
	s_and_b64 vcc, exec, s[42:43]
	v_cvt_pk_bf16_f32 v148, v148, v149
	v_cvt_pk_bf16_f32 v149, v150, v151
	v_cvt_pk_bf16_f32 v150, v144, v145
	v_cvt_pk_bf16_f32 v151, v146, v147
	global_store_dwordx4 v[202:203], v[148:151], off offset:256 sc1
	s_cbranch_vccnz .LBB0_431
	v_fma_f32 v144, -v186, v186, v187
	v_max_f32_e32 v144, 0, v144
	v_add_f32_e32 v144, 0x3727c5ac, v144
	v_mul_f32_e32 v145, 0x4b800000, v144
	v_cmp_gt_f32_e32 vcc, s13, v144
	s_nop 1
	v_cndmask_b32_e32 v144, v144, v145, vcc
	v_rsq_f32_e32 v144, v144
	s_nop 0
	v_mul_f32_e32 v145, 0x45800000, v144
	v_cndmask_b32_e32 v144, v144, v145, vcc
	s_and_b64 vcc, exec, s[42:43]
	s_cbranch_vccz .LBB0_432
	s_branch .LBB0_433

.LBB0_435:
	v_add_u32_e32 v145, 16, v170
	v_ashrrev_i32_e32 v146, 31, v145
	v_mul_lo_u32 v148, s70, v146
	v_mul_lo_u32 v149, s71, v145
	v_mad_u64_u32 v[146:147], s[2:3], s70, v145, 0
	v_add3_u32 v147, v147, v148, v149
	v_lshl_add_u64 v[146:147], v[146:147], 1, v[176:177]
	s_and_b64 vcc, exec, s[42:43]
	v_cvt_pk_bf16_f32 v140, v140, v141
	v_cvt_pk_bf16_f32 v141, v142, v143
	v_cvt_pk_bf16_f32 v142, v136, v137
	v_cvt_pk_bf16_f32 v143, v138, v139
	global_store_dwordx4 v[146:147], v[140:143], off sc1
	s_cbranch_vccnz .LBB0_437
	v_pk_fma_f32 v[134:135], v[66:67], v[186:187], v[134:135] op_sel_hi:[1,0,1] neg_lo:[1,0,0] neg_hi:[1,0,0]
	v_pk_fma_f32 v[128:129], v[68:69], v[186:187], v[128:129] op_sel_hi:[1,0,1] neg_lo:[1,0,0] neg_hi:[1,0,0]
	v_pk_fma_f32 v[130:131], v[70:71], v[186:187], v[130:131] op_sel_hi:[1,0,1] neg_lo:[1,0,0] neg_hi:[1,0,0]
	v_pk_fma_f32 v[132:133], v[64:65], v[186:187], v[132:133] op_sel_hi:[1,0,1] neg_lo:[1,0,0] neg_hi:[1,0,0]
	v_pk_fma_f32 v[130:131], v[144:145], v[130:131], v[78:79] op_sel_hi:[0,1,1]
	v_pk_fma_f32 v[132:133], v[144:145], v[132:133], v[72:73] op_sel_hi:[0,1,1]
	v_pk_fma_f32 v[128:129], v[144:145], v[128:129], v[76:77] op_sel_hi:[0,1,1]
	v_pk_fma_f32 v[134:135], v[144:145], v[134:135], v[74:75] op_sel_hi:[0,1,1]

.LBB0_439:
	s_and_b64 vcc, exec, s[42:43]
	v_cvt_pk_bf16_f32 v132, v132, v133
	v_cvt_pk_bf16_f32 v133, v134, v135
	v_cvt_pk_bf16_f32 v134, v128, v129
	v_cvt_pk_bf16_f32 v135, v130, v131
	global_store_dwordx4 v[146:147], v[132:135], off offset:256 sc1
	s_cbranch_vccnz .LBB0_441
	v_fma_f32 v128, -v184, v184, v185
	v_max_f32_e32 v128, 0, v128
	v_add_f32_e32 v128, 0x3727c5ac, v128
	v_mul_f32_e32 v129, 0x4b800000, v128
	v_cmp_gt_f32_e32 vcc, s13, v128
	s_nop 1
	v_cndmask_b32_e32 v128, v128, v129, vcc
	v_rsq_f32_e32 v128, v128
	s_nop 0
	v_mul_f32_e32 v129, 0x45800000, v128
	v_cndmask_b32_e32 v128, v128, v129, vcc
	s_and_b64 vcc, exec, s[42:43]
	s_cbranch_vccz .LBB0_442
	s_branch .LBB0_443

.LBB0_445:
	v_add_u32_e32 v129, 32, v170
	v_ashrrev_i32_e32 v130, 31, v129
	v_mul_lo_u32 v132, s70, v130
	v_mul_lo_u32 v133, s71, v129
	v_mad_u64_u32 v[130:131], s[2:3], s70, v129, 0
	v_add3_u32 v131, v131, v132, v133
	v_lshl_add_u64 v[130:131], v[130:131], 1, v[176:177]
	s_and_b64 vcc, exec, s[42:43]
	v_cvt_pk_bf16_f32 v124, v124, v125
	v_cvt_pk_bf16_f32 v125, v126, v127
	v_cvt_pk_bf16_f32 v126, v120, v121
	v_cvt_pk_bf16_f32 v127, v122, v123
	global_store_dwordx4 v[130:131], v[124:127], off sc1
	s_cbranch_vccnz .LBB0_447
	v_pk_fma_f32 v[118:119], v[66:67], v[184:185], v[118:119] op_sel_hi:[1,0,1] neg_lo:[1,0,0] neg_hi:[1,0,0]
	v_pk_fma_f32 v[112:113], v[68:69], v[184:185], v[112:113] op_sel_hi:[1,0,1] neg_lo:[1,0,0] neg_hi:[1,0,0]
	v_pk_fma_f32 v[114:115], v[70:71], v[184:185], v[114:115] op_sel_hi:[1,0,1] neg_lo:[1,0,0] neg_hi:[1,0,0]
	v_pk_fma_f32 v[116:117], v[64:65], v[184:185], v[116:117] op_sel_hi:[1,0,1] neg_lo:[1,0,0] neg_hi:[1,0,0]
	v_pk_fma_f32 v[114:115], v[128:129], v[114:115], v[78:79] op_sel_hi:[0,1,1]
	v_pk_fma_f32 v[116:117], v[128:129], v[116:117], v[72:73] op_sel_hi:[0,1,1]
	v_pk_fma_f32 v[112:113], v[128:129], v[112:113], v[76:77] op_sel_hi:[0,1,1]
	v_pk_fma_f32 v[118:119], v[128:129], v[118:119], v[74:75] op_sel_hi:[0,1,1]

.LBB0_449:
	s_and_b64 vcc, exec, s[42:43]
	v_cvt_pk_bf16_f32 v116, v116, v117
	v_cvt_pk_bf16_f32 v117, v118, v119
	v_cvt_pk_bf16_f32 v118, v112, v113
	v_cvt_pk_bf16_f32 v119, v114, v115
	global_store_dwordx4 v[130:131], v[116:119], off offset:256 sc1
	s_cbranch_vccnz .LBB0_451
	v_fma_f32 v112, -v182, v182, v183
	v_max_f32_e32 v112, 0, v112
	v_add_f32_e32 v112, 0x3727c5ac, v112
	v_mul_f32_e32 v113, 0x4b800000, v112
	v_cmp_gt_f32_e32 vcc, s13, v112
	s_nop 1
	v_cndmask_b32_e32 v112, v112, v113, vcc
	v_rsq_f32_e32 v112, v112
	s_nop 0
	v_mul_f32_e32 v113, 0x45800000, v112
	v_cndmask_b32_e32 v112, v112, v113, vcc
	s_and_b64 vcc, exec, s[42:43]
	s_cbranch_vccz .LBB0_452
	s_branch .LBB0_453

.LBB0_455:
	v_add_u32_e32 v113, 48, v170
	v_ashrrev_i32_e32 v114, 31, v113
	v_mul_lo_u32 v116, s70, v114
	v_mul_lo_u32 v117, s71, v113
	v_mad_u64_u32 v[114:115], s[2:3], s70, v113, 0
	v_add3_u32 v115, v115, v116, v117
	v_lshl_add_u64 v[114:115], v[114:115], 1, v[176:177]
	s_and_b64 vcc, exec, s[42:43]
	v_cvt_pk_bf16_f32 v108, v108, v109
	v_cvt_pk_bf16_f32 v109, v110, v111
	v_cvt_pk_bf16_f32 v110, v104, v105
	v_cvt_pk_bf16_f32 v111, v106, v107
	global_store_dwordx4 v[114:115], v[108:111], off sc1
	s_cbranch_vccnz .LBB0_457
	v_pk_fma_f32 v[102:103], v[66:67], v[182:183], v[102:103] op_sel_hi:[1,0,1] neg_lo:[1,0,0] neg_hi:[1,0,0]
	v_pk_fma_f32 v[80:81], v[68:69], v[182:183], v[80:81] op_sel_hi:[1,0,1] neg_lo:[1,0,0] neg_hi:[1,0,0]
	v_pk_fma_f32 v[82:83], v[70:71], v[182:183], v[82:83] op_sel_hi:[1,0,1] neg_lo:[1,0,0] neg_hi:[1,0,0]
	v_pk_fma_f32 v[100:101], v[64:65], v[182:183], v[100:101] op_sel_hi:[1,0,1] neg_lo:[1,0,0] neg_hi:[1,0,0]
	v_pk_fma_f32 v[82:83], v[112:113], v[82:83], v[78:79] op_sel_hi:[0,1,1]
	v_pk_fma_f32 v[100:101], v[112:113], v[100:101], v[72:73] op_sel_hi:[0,1,1]
	v_pk_fma_f32 v[80:81], v[112:113], v[80:81], v[76:77] op_sel_hi:[0,1,1]
	v_pk_fma_f32 v[102:103], v[112:113], v[102:103], v[74:75] op_sel_hi:[0,1,1]

.LBB0_459:
	s_and_b64 vcc, exec, s[42:43]
	v_cvt_pk_bf16_f32 v100, v100, v101
	v_cvt_pk_bf16_f32 v101, v102, v103
	v_cvt_pk_bf16_f32 v102, v80, v81
	v_cvt_pk_bf16_f32 v103, v82, v83
	global_store_dwordx4 v[114:115], v[100:103], off offset:256 sc1
	s_cbranch_vccnz .LBB0_461
	v_fma_f32 v80, -v180, v180, v181
	v_max_f32_e32 v80, 0, v80
	v_add_f32_e32 v80, 0x3727c5ac, v80
	v_mul_f32_e32 v81, 0x4b800000, v80
	v_cmp_gt_f32_e32 vcc, s13, v80
	s_nop 1
	v_cndmask_b32_e32 v80, v80, v81, vcc
	v_rsq_f32_e32 v80, v80
	s_nop 0
	v_mul_f32_e32 v81, 0x45800000, v80
	v_cndmask_b32_e32 v80, v80, v81, vcc
	s_and_b64 vcc, exec, s[42:43]
	s_cbranch_vccz .LBB0_462
	s_branch .LBB0_463

.LBB0_465:
	v_add_u32_e32 v81, 0x80, v170
	v_ashrrev_i32_e32 v82, 31, v81
	v_mul_lo_u32 v100, s70, v82
	v_mul_lo_u32 v101, s71, v81
	v_mad_u64_u32 v[82:83], s[2:3], s70, v81, 0
	v_add3_u32 v83, v83, v100, v101
	v_lshl_add_u64 v[82:83], v[82:83], 1, v[176:177]
	s_and_b64 vcc, exec, s[42:43]
	v_cvt_pk_bf16_f32 v60, v60, v61
	v_cvt_pk_bf16_f32 v61, v62, v63
	v_cvt_pk_bf16_f32 v62, v56, v57
	v_cvt_pk_bf16_f32 v63, v58, v59
	global_store_dwordx4 v[82:83], v[60:63], off sc1
	s_cbranch_vccnz .LBB0_467
	v_pk_fma_f32 v[54:55], v[66:67], v[180:181], v[54:55] op_sel_hi:[1,0,1] neg_lo:[1,0,0] neg_hi:[1,0,0]
	v_pk_fma_f32 v[48:49], v[68:69], v[180:181], v[48:49] op_sel_hi:[1,0,1] neg_lo:[1,0,0] neg_hi:[1,0,0]
	v_pk_fma_f32 v[50:51], v[70:71], v[180:181], v[50:51] op_sel_hi:[1,0,1] neg_lo:[1,0,0] neg_hi:[1,0,0]
	v_pk_fma_f32 v[52:53], v[64:65], v[180:181], v[52:53] op_sel_hi:[1,0,1] neg_lo:[1,0,0] neg_hi:[1,0,0]
	v_pk_fma_f32 v[50:51], v[80:81], v[50:51], v[78:79] op_sel_hi:[0,1,1]
	v_pk_fma_f32 v[52:53], v[80:81], v[52:53], v[72:73] op_sel_hi:[0,1,1]
	v_pk_fma_f32 v[48:49], v[80:81], v[48:49], v[76:77] op_sel_hi:[0,1,1]
	v_pk_fma_f32 v[54:55], v[80:81], v[54:55], v[74:75] op_sel_hi:[0,1,1]

.LBB0_469:
	s_and_b64 vcc, exec, s[42:43]
	v_cvt_pk_bf16_f32 v52, v52, v53
	v_cvt_pk_bf16_f32 v53, v54, v55
	v_cvt_pk_bf16_f32 v54, v48, v49
	v_cvt_pk_bf16_f32 v55, v50, v51
	global_store_dwordx4 v[82:83], v[52:55], off offset:256 sc1
	s_cbranch_vccnz .LBB0_471
	v_fma_f32 v48, -v178, v178, v179
	v_max_f32_e32 v48, 0, v48
	v_add_f32_e32 v48, 0x3727c5ac, v48
	v_mul_f32_e32 v49, 0x4b800000, v48
	v_cmp_gt_f32_e32 vcc, s13, v48
	s_nop 1
	v_cndmask_b32_e32 v48, v48, v49, vcc
	v_rsq_f32_e32 v48, v48
	s_nop 0
	v_mul_f32_e32 v49, 0x45800000, v48
	v_cndmask_b32_e32 v48, v48, v49, vcc
	s_and_b64 vcc, exec, s[42:43]
	s_cbranch_vccz .LBB0_472
	s_branch .LBB0_473

.LBB0_475:
	v_add_u32_e32 v49, 0x90, v170
	v_ashrrev_i32_e32 v50, 31, v49
	v_mul_lo_u32 v52, s70, v50
	v_mul_lo_u32 v53, s71, v49
	v_mad_u64_u32 v[50:51], s[2:3], s70, v49, 0
	v_add3_u32 v51, v51, v52, v53
	v_lshl_add_u64 v[50:51], v[50:51], 1, v[176:177]
	s_and_b64 vcc, exec, s[42:43]
	v_cvt_pk_bf16_f32 v44, v44, v45
	v_cvt_pk_bf16_f32 v45, v46, v47
	v_cvt_pk_bf16_f32 v46, v40, v41
	v_cvt_pk_bf16_f32 v47, v42, v43
	global_store_dwordx4 v[50:51], v[44:47], off sc1
	s_cbranch_vccnz .LBB0_477
	v_pk_fma_f32 v[38:39], v[66:67], v[178:179], v[38:39] op_sel_hi:[1,0,1] neg_lo:[1,0,0] neg_hi:[1,0,0]
	v_pk_fma_f32 v[32:33], v[68:69], v[178:179], v[32:33] op_sel_hi:[1,0,1] neg_lo:[1,0,0] neg_hi:[1,0,0]
	v_pk_fma_f32 v[34:35], v[70:71], v[178:179], v[34:35] op_sel_hi:[1,0,1] neg_lo:[1,0,0] neg_hi:[1,0,0]
	v_pk_fma_f32 v[36:37], v[64:65], v[178:179], v[36:37] op_sel_hi:[1,0,1] neg_lo:[1,0,0] neg_hi:[1,0,0]
	v_pk_fma_f32 v[34:35], v[48:49], v[34:35], v[78:79] op_sel_hi:[0,1,1]
	v_pk_fma_f32 v[36:37], v[48:49], v[36:37], v[72:73] op_sel_hi:[0,1,1]
	v_pk_fma_f32 v[32:33], v[48:49], v[32:33], v[76:77] op_sel_hi:[0,1,1]
	v_pk_fma_f32 v[38:39], v[48:49], v[38:39], v[74:75] op_sel_hi:[0,1,1]

.LBB0_479:
	s_and_b64 vcc, exec, s[42:43]
	v_cvt_pk_bf16_f32 v36, v36, v37
	v_cvt_pk_bf16_f32 v37, v38, v39
	v_cvt_pk_bf16_f32 v38, v32, v33
	v_cvt_pk_bf16_f32 v39, v34, v35
	global_store_dwordx4 v[50:51], v[36:39], off offset:256 sc1
	s_cbranch_vccnz .LBB0_481
	v_fma_f32 v32, -v174, v174, v175
	v_max_f32_e32 v32, 0, v32
	v_add_f32_e32 v32, 0x3727c5ac, v32
	v_mul_f32_e32 v33, 0x4b800000, v32
	v_cmp_gt_f32_e32 vcc, s13, v32
	s_nop 1
	v_cndmask_b32_e32 v32, v32, v33, vcc
	v_rsq_f32_e32 v32, v32
	s_nop 0
	v_mul_f32_e32 v33, 0x45800000, v32
	v_cndmask_b32_e32 v32, v32, v33, vcc
	s_and_b64 vcc, exec, s[42:43]
	s_cbranch_vccz .LBB0_482
	s_branch .LBB0_483

.LBB0_485:
	v_add_u32_e32 v33, 0xa0, v170
	v_ashrrev_i32_e32 v34, 31, v33
	v_mul_lo_u32 v36, s70, v34
	v_mul_lo_u32 v37, s71, v33
	v_mad_u64_u32 v[34:35], s[2:3], s70, v33, 0
	v_add3_u32 v35, v35, v36, v37
	v_lshl_add_u64 v[34:35], v[34:35], 1, v[176:177]
	s_and_b64 vcc, exec, s[42:43]
	v_cvt_pk_bf16_f32 v28, v28, v29
	v_cvt_pk_bf16_f32 v29, v30, v31
	v_cvt_pk_bf16_f32 v30, v24, v25
	v_cvt_pk_bf16_f32 v31, v26, v27
	global_store_dwordx4 v[34:35], v[28:31], off sc1
	s_cbranch_vccnz .LBB0_487
	v_pk_fma_f32 v[22:23], v[66:67], v[174:175], v[22:23] op_sel_hi:[1,0,1] neg_lo:[1,0,0] neg_hi:[1,0,0]
	v_pk_fma_f32 v[16:17], v[68:69], v[174:175], v[16:17] op_sel_hi:[1,0,1] neg_lo:[1,0,0] neg_hi:[1,0,0]
	v_pk_fma_f32 v[18:19], v[70:71], v[174:175], v[18:19] op_sel_hi:[1,0,1] neg_lo:[1,0,0] neg_hi:[1,0,0]
	v_pk_fma_f32 v[20:21], v[64:65], v[174:175], v[20:21] op_sel_hi:[1,0,1] neg_lo:[1,0,0] neg_hi:[1,0,0]
	v_pk_fma_f32 v[18:19], v[32:33], v[18:19], v[78:79] op_sel_hi:[0,1,1]
	v_pk_fma_f32 v[20:21], v[32:33], v[20:21], v[72:73] op_sel_hi:[0,1,1]
	v_pk_fma_f32 v[16:17], v[32:33], v[16:17], v[76:77] op_sel_hi:[0,1,1]
	v_pk_fma_f32 v[22:23], v[32:33], v[22:23], v[74:75] op_sel_hi:[0,1,1]

.LBB0_489:
	s_and_b64 vcc, exec, s[42:43]
	v_cvt_pk_bf16_f32 v20, v20, v21
	v_cvt_pk_bf16_f32 v21, v22, v23
	v_cvt_pk_bf16_f32 v22, v16, v17
	v_cvt_pk_bf16_f32 v23, v18, v19
	global_store_dwordx4 v[34:35], v[20:23], off offset:256 sc1
	s_cbranch_vccnz .LBB0_491
	v_fma_f32 v16, -v172, v172, v173
	v_max_f32_e32 v16, 0, v16
	v_add_f32_e32 v16, 0x3727c5ac, v16
	v_mul_f32_e32 v17, 0x4b800000, v16
	v_cmp_gt_f32_e32 vcc, s13, v16
	s_nop 1
	v_cndmask_b32_e32 v16, v16, v17, vcc
	v_rsq_f32_e32 v16, v16
	s_nop 0
	v_mul_f32_e32 v17, 0x45800000, v16
	v_cndmask_b32_e32 v16, v16, v17, vcc
	s_and_b64 vcc, exec, s[42:43]
	s_cbranch_vccz .LBB0_492
	s_branch .LBB0_493

.LBB0_495:
	v_add_u32_e32 v17, 0xb0, v170
	v_ashrrev_i32_e32 v18, 31, v17
	v_mul_lo_u32 v20, s70, v18
	v_mul_lo_u32 v21, s71, v17
	v_mad_u64_u32 v[18:19], s[2:3], s70, v17, 0
	v_add3_u32 v19, v19, v20, v21
	v_lshl_add_u64 v[18:19], v[18:19], 1, v[176:177]
	s_and_b64 vcc, exec, s[42:43]
	v_cvt_pk_bf16_f32 v12, v12, v13
	v_cvt_pk_bf16_f32 v13, v14, v15
	v_cvt_pk_bf16_f32 v14, v8, v9
	v_cvt_pk_bf16_f32 v15, v10, v11
	global_store_dwordx4 v[18:19], v[12:15], off sc1
	s_cbranch_vccnz .LBB0_497
	v_pk_fma_f32 v[6:7], v[66:67], v[172:173], v[6:7] op_sel_hi:[1,0,1] neg_lo:[1,0,0] neg_hi:[1,0,0]
	v_pk_fma_f32 v[0:1], v[68:69], v[172:173], v[0:1] op_sel_hi:[1,0,1] neg_lo:[1,0,0] neg_hi:[1,0,0]
	v_pk_fma_f32 v[2:3], v[70:71], v[172:173], v[2:3] op_sel_hi:[1,0,1] neg_lo:[1,0,0] neg_hi:[1,0,0]
	v_pk_fma_f32 v[4:5], v[64:65], v[172:173], v[4:5] op_sel_hi:[1,0,1] neg_lo:[1,0,0] neg_hi:[1,0,0]
	v_pk_fma_f32 v[2:3], v[16:17], v[2:3], v[78:79] op_sel_hi:[0,1,1]
	v_pk_fma_f32 v[4:5], v[16:17], v[4:5], v[72:73] op_sel_hi:[0,1,1]
	v_pk_fma_f32 v[0:1], v[16:17], v[0:1], v[76:77] op_sel_hi:[0,1,1]
	v_pk_fma_f32 v[6:7], v[16:17], v[6:7], v[74:75] op_sel_hi:[0,1,1]

.LBB0_504:
	s_add_i32 s2, s4, 0x80
	s_cmpk_lt_i32 s4, 0x480
	s_mov_b32 s4, s2
	s_waitcnt lgkmcnt(0)
	global_store_dwordx4 v[30:31], v[12:15], off offset:48 sc1
	s_cbranch_scc0 .LBB0_511

.LBB0_879:
	v_lshlrev_b64 v[128:129], 1, v[168:169]
	v_ashrrev_i32_e32 v167, 31, v166
	v_lshl_add_u64 v[152:153], s[46:47], 0, v[128:129]
	v_lshl_add_u64 v[154:155], s[54:55], 0, v[128:129]
	v_lshlrev_b64 v[128:129], 13, v[166:167]
	v_add_u32_e32 v168, 16, v166
	v_lshl_add_u64 v[128:129], v[154:155], 0, v[128:129]
	v_ashrrev_i32_e32 v169, 31, v168
	global_load_dwordx4 v[170:173], v[128:129], off
	global_load_dwordx4 v[178:181], v[128:129], off offset:256
	v_lshlrev_b64 v[128:129], 13, v[168:169]
	v_add_u32_e32 v158, 32, v166
	v_lshl_add_u64 v[128:129], v[154:155], 0, v[128:129]
	v_ashrrev_i32_e32 v159, 31, v158
	global_load_dwordx4 v[148:151], v[128:129], off
	global_load_dwordx4 v[144:147], v[128:129], off offset:256
	v_lshlrev_b64 v[128:129], 13, v[158:159]
	v_add_u32_e32 v156, 48, v166
	v_lshl_add_u64 v[128:129], v[154:155], 0, v[128:129]
	v_ashrrev_i32_e32 v157, 31, v156
	global_load_dwordx4 v[140:143], v[128:129], off
	global_load_dwordx4 v[136:139], v[128:129], off offset:256
	v_lshlrev_b64 v[128:129], 13, v[156:157]
	v_lshl_add_u64 v[128:129], v[154:155], 0, v[128:129]
	global_load_dwordx4 v[132:135], v[128:129], off
	s_nop 0
	global_load_dwordx4 v[128:131], v[128:129], off offset:256
	v_lshlrev_b64 v[182:183], 12, v[166:167]
	v_lshl_add_u64 v[182:183], v[152:153], 0, v[182:183]
	s_and_b64 vcc, exec, s[40:41]
	s_mov_b32 s3, s56
	s_mov_b32 s2, s58
	s_mov_b64 s[20:21], s[62:63]
	s_mov_b64 s[48:49], s[60:61]
	s_waitcnt vmcnt(0)
	s_nop 0
	v_lshlrev_b32_e32 v167, 16, v170
	v_mul_f32_e32 v124, v124, v167
	v_and_b32_e32 v167, 0xffff0000, v170
	v_mul_f32_e32 v125, v125, v167
	v_lshlrev_b32_e32 v167, 16, v171
	v_mul_f32_e32 v126, v126, v167
	v_and_b32_e32 v167, 0xffff0000, v171
	v_mul_f32_e32 v127, v127, v167
	v_lshlrev_b32_e32 v167, 16, v172
	v_mul_f32_e32 v167, v120, v167
	v_and_b32_e32 v120, 0xffff0000, v172
	v_mul_f32_e32 v170, v121, v120
	v_lshlrev_b32_e32 v120, 16, v173
	v_mul_f32_e32 v171, v122, v120
	v_and_b32_e32 v120, 0xffff0000, v173
	v_mul_f32_e32 v123, v123, v120
	v_cvt_pk_bf16_f32 v120, v124, v125
	v_cvt_pk_bf16_f32 v121, v126, v127
	v_cvt_pk_bf16_f32 v122, v167, v170
	v_cvt_pk_bf16_f32 v123, v171, v123
	global_store_dwordx4 v[182:183], v[120:123], off sc1
	s_nop 1
	v_lshlrev_b32_e32 v120, 16, v178
	v_mul_f32_e32 v116, v116, v120
	v_and_b32_e32 v120, 0xffff0000, v178
	v_mul_f32_e32 v117, v117, v120
	v_lshlrev_b32_e32 v120, 16, v179
	v_mul_f32_e32 v118, v118, v120
	v_and_b32_e32 v120, 0xffff0000, v179
	v_mul_f32_e32 v119, v119, v120
	v_lshlrev_b32_e32 v120, 16, v180
	v_mul_f32_e32 v120, v112, v120
	v_and_b32_e32 v112, 0xffff0000, v180
	v_mul_f32_e32 v121, v113, v112
	v_lshlrev_b32_e32 v112, 16, v181
	v_mul_f32_e32 v122, v114, v112
	v_and_b32_e32 v112, 0xffff0000, v181
	v_mul_f32_e32 v115, v115, v112
	v_cvt_pk_bf16_f32 v112, v116, v117
	v_cvt_pk_bf16_f32 v113, v118, v119
	v_cvt_pk_bf16_f32 v114, v120, v121
	v_cvt_pk_bf16_f32 v115, v122, v115
	global_store_dwordx4 v[182:183], v[112:115], off offset:256 sc1
	s_nop 1
	v_lshlrev_b32_e32 v114, 16, v148
	v_mul_f32_e32 v108, v108, v114
	v_and_b32_e32 v114, 0xffff0000, v148
	v_mul_f32_e32 v109, v109, v114
	v_lshlrev_b32_e32 v114, 16, v149
	v_mul_f32_e32 v110, v110, v114
	v_and_b32_e32 v114, 0xffff0000, v149
	v_mul_f32_e32 v111, v111, v114
	v_lshlrev_b32_e32 v114, 16, v150
	v_mul_f32_e32 v114, v104, v114
	v_and_b32_e32 v104, 0xffff0000, v150
	v_mul_f32_e32 v115, v105, v104
	v_lshlrev_b32_e32 v104, 16, v151
	v_lshlrev_b64 v[112:113], 12, v[168:169]
	v_mul_f32_e32 v116, v106, v104
	v_and_b32_e32 v104, 0xffff0000, v151
	v_lshl_add_u64 v[112:113], v[152:153], 0, v[112:113]
	v_mul_f32_e32 v107, v107, v104
	v_cvt_pk_bf16_f32 v104, v108, v109
	v_cvt_pk_bf16_f32 v105, v110, v111
	v_cvt_pk_bf16_f32 v106, v114, v115
	v_cvt_pk_bf16_f32 v107, v116, v107
	global_store_dwordx4 v[112:113], v[104:107], off sc1
	s_nop 1
	v_lshlrev_b32_e32 v104, 16, v144
	v_mul_f32_e32 v100, v100, v104
	v_and_b32_e32 v104, 0xffff0000, v144
	v_mul_f32_e32 v101, v101, v104
	v_lshlrev_b32_e32 v104, 16, v145
	v_mul_f32_e32 v102, v102, v104
	v_and_b32_e32 v104, 0xffff0000, v145
	v_mul_f32_e32 v103, v103, v104
	v_lshlrev_b32_e32 v104, 16, v146
	v_mul_f32_e32 v104, v92, v104
	v_and_b32_e32 v92, 0xffff0000, v146
	v_mul_f32_e32 v105, v93, v92
	v_lshlrev_b32_e32 v92, 16, v147
	v_mul_f32_e32 v106, v94, v92
	v_and_b32_e32 v92, 0xffff0000, v147
	v_mul_f32_e32 v95, v95, v92
	v_cvt_pk_bf16_f32 v92, v100, v101
	v_cvt_pk_bf16_f32 v93, v102, v103
	v_cvt_pk_bf16_f32 v94, v104, v105
	v_cvt_pk_bf16_f32 v95, v106, v95
	global_store_dwordx4 v[112:113], v[92:95], off offset:256 sc1
	v_add_u32_e32 v102, 0xb0, v166
	v_ashrrev_i32_e32 v103, 31, v102
	v_lshlrev_b32_e32 v94, 16, v140
	v_mul_f32_e32 v94, v96, v94
	v_lshlrev_b32_e32 v96, 16, v141
	v_and_b32_e32 v95, 0xffff0000, v140
	v_mul_f32_e32 v96, v98, v96
	v_lshlrev_b32_e32 v98, 16, v142
	v_mul_f32_e32 v95, v97, v95
	v_and_b32_e32 v97, 0xffff0000, v141
	v_mul_f32_e32 v98, v88, v98
	v_and_b32_e32 v88, 0xffff0000, v142
	v_mul_f32_e32 v97, v99, v97
	v_mul_f32_e32 v99, v89, v88
	v_lshlrev_b32_e32 v88, 16, v143
	v_lshlrev_b64 v[92:93], 12, v[158:159]
	v_mul_f32_e32 v100, v90, v88
	v_and_b32_e32 v88, 0xffff0000, v143
	v_lshl_add_u64 v[92:93], v[152:153], 0, v[92:93]
	v_mul_f32_e32 v91, v91, v88
	v_cvt_pk_bf16_f32 v88, v94, v95
	v_cvt_pk_bf16_f32 v89, v96, v97
	v_cvt_pk_bf16_f32 v90, v98, v99
	v_cvt_pk_bf16_f32 v91, v100, v91
	global_store_dwordx4 v[92:93], v[88:91], off sc1
	v_add_u32_e32 v96, 0x80, v166
	v_add_u32_e32 v98, 0x90, v166
	v_lshlrev_b32_e32 v88, 16, v136
	v_mul_f32_e32 v84, v84, v88
	v_and_b32_e32 v88, 0xffff0000, v136
	v_mul_f32_e32 v85, v85, v88
	v_lshlrev_b32_e32 v88, 16, v137
	v_mul_f32_e32 v86, v86, v88
	v_and_b32_e32 v88, 0xffff0000, v137
	v_mul_f32_e32 v87, v87, v88
	v_lshlrev_b32_e32 v88, 16, v138
	v_mul_f32_e32 v88, v76, v88
	v_and_b32_e32 v76, 0xffff0000, v138
	v_mul_f32_e32 v89, v77, v76
	v_lshlrev_b32_e32 v76, 16, v139
	v_mul_f32_e32 v90, v78, v76
	v_and_b32_e32 v76, 0xffff0000, v139
	v_mul_f32_e32 v79, v79, v76
	v_cvt_pk_bf16_f32 v76, v84, v85
	v_cvt_pk_bf16_f32 v77, v86, v87
	v_cvt_pk_bf16_f32 v78, v88, v89
	v_cvt_pk_bf16_f32 v79, v90, v79
	global_store_dwordx4 v[92:93], v[76:79], off offset:256 sc1
	v_add_u32_e32 v100, 0xa0, v166
	v_ashrrev_i32_e32 v97, 31, v96
	v_lshlrev_b32_e32 v78, 16, v132
	v_mul_f32_e32 v78, v80, v78
	v_lshlrev_b32_e32 v80, 16, v133
	v_and_b32_e32 v79, 0xffff0000, v132
	v_mul_f32_e32 v80, v82, v80
	v_lshlrev_b32_e32 v82, 16, v134
	v_mul_f32_e32 v79, v81, v79
	v_and_b32_e32 v81, 0xffff0000, v133
	v_mul_f32_e32 v82, v72, v82
	v_and_b32_e32 v72, 0xffff0000, v134
	v_mul_f32_e32 v81, v83, v81
	v_mul_f32_e32 v83, v73, v72
	v_lshlrev_b32_e32 v72, 16, v135
	v_lshlrev_b64 v[76:77], 12, v[156:157]
	v_mul_f32_e32 v84, v74, v72
	v_and_b32_e32 v72, 0xffff0000, v135
	v_lshl_add_u64 v[76:77], v[152:153], 0, v[76:77]
	v_mul_f32_e32 v75, v75, v72
	v_cvt_pk_bf16_f32 v72, v78, v79
	v_cvt_pk_bf16_f32 v73, v80, v81
	v_cvt_pk_bf16_f32 v74, v82, v83
	v_cvt_pk_bf16_f32 v75, v84, v75
	global_store_dwordx4 v[76:77], v[72:75], off sc1
	v_ashrrev_i32_e32 v99, 31, v98
	v_ashrrev_i32_e32 v101, 31, v100
	v_lshlrev_b32_e32 v72, 16, v128
	v_mul_f32_e32 v68, v68, v72
	v_and_b32_e32 v72, 0xffff0000, v128
	v_mul_f32_e32 v69, v69, v72
	v_lshlrev_b32_e32 v72, 16, v129
	v_mul_f32_e32 v70, v70, v72
	v_and_b32_e32 v72, 0xffff0000, v129
	v_mul_f32_e32 v71, v71, v72
	v_lshlrev_b32_e32 v72, 16, v130
	v_mul_f32_e32 v72, v64, v72
	v_and_b32_e32 v64, 0xffff0000, v130
	v_mul_f32_e32 v73, v65, v64
	v_lshlrev_b32_e32 v64, 16, v131
	v_mul_f32_e32 v74, v66, v64
	v_and_b32_e32 v64, 0xffff0000, v131
	v_mul_f32_e32 v67, v67, v64
	v_cvt_pk_bf16_f32 v64, v68, v69
	v_cvt_pk_bf16_f32 v65, v70, v71
	v_cvt_pk_bf16_f32 v66, v72, v73
	v_cvt_pk_bf16_f32 v67, v74, v67
	global_store_dwordx4 v[76:77], v[64:67], off offset:256 sc1
	v_lshlrev_b64 v[72:73], 13, v[98:99]
	v_lshlrev_b64 v[80:81], 13, v[100:101]
	v_lshlrev_b64 v[64:65], 13, v[96:97]
	v_lshlrev_b64 v[88:89], 13, v[102:103]
	v_lshl_add_u64 v[68:69], v[154:155], 0, v[64:65]
	v_lshl_add_u64 v[76:77], v[154:155], 0, v[72:73]
	v_lshl_add_u64 v[84:85], v[154:155], 0, v[80:81]
	v_lshl_add_u64 v[92:93], v[154:155], 0, v[88:89]
	global_load_dwordx4 v[64:67], v[68:69], off
	s_nop 0
	global_load_dwordx4 v[68:71], v[68:69], off offset:256
	s_nop 0
	global_load_dwordx4 v[72:75], v[76:77], off
	s_nop 0
	global_load_dwordx4 v[76:79], v[76:77], off offset:256
	s_nop 0
	global_load_dwordx4 v[80:83], v[84:85], off
	s_nop 0
	global_load_dwordx4 v[84:87], v[84:85], off offset:256
	s_nop 0
	global_load_dwordx4 v[88:91], v[92:93], off
	s_nop 0
	global_load_dwordx4 v[92:95], v[92:93], off offset:256
	s_waitcnt vmcnt(0)
	s_nop 0
	v_lshlrev_b32_e32 v104, 16, v64
	v_and_b32_e32 v64, 0xffff0000, v64
	v_mul_f32_e32 v61, v61, v64
	v_lshlrev_b32_e32 v64, 16, v65
	v_mul_f32_e32 v62, v62, v64
	v_and_b32_e32 v64, 0xffff0000, v65
	v_mul_f32_e32 v63, v63, v64
	v_lshlrev_b32_e32 v64, 16, v66
	v_mul_f32_e32 v64, v56, v64
	v_and_b32_e32 v56, 0xffff0000, v66
	v_mul_f32_e32 v65, v57, v56
	v_lshlrev_b32_e32 v56, 16, v67
	v_lshlrev_b64 v[96:97], 12, v[96:97]
	v_mul_f32_e32 v66, v58, v56
	v_and_b32_e32 v56, 0xffff0000, v67
	v_lshl_add_u64 v[96:97], v[152:153], 0, v[96:97]
	v_mul_f32_e32 v60, v60, v104
	v_mul_f32_e32 v59, v59, v56
	v_cvt_pk_bf16_f32 v56, v60, v61
	v_cvt_pk_bf16_f32 v57, v62, v63
	v_cvt_pk_bf16_f32 v58, v64, v65
	v_cvt_pk_bf16_f32 v59, v66, v59
	global_store_dwordx4 v[96:97], v[56:59], off sc1
	s_nop 1
	v_lshlrev_b32_e32 v56, 16, v68
	v_mul_f32_e32 v52, v52, v56
	v_and_b32_e32 v56, 0xffff0000, v68
	v_mul_f32_e32 v53, v53, v56
	v_lshlrev_b32_e32 v56, 16, v69
	v_mul_f32_e32 v54, v54, v56
	v_and_b32_e32 v56, 0xffff0000, v69
	v_mul_f32_e32 v55, v55, v56
	v_lshlrev_b32_e32 v56, 16, v70
	v_mul_f32_e32 v56, v44, v56
	v_and_b32_e32 v44, 0xffff0000, v70
	v_mul_f32_e32 v57, v45, v44
	v_lshlrev_b32_e32 v44, 16, v71
	v_mul_f32_e32 v58, v46, v44
	v_and_b32_e32 v44, 0xffff0000, v71
	v_mul_f32_e32 v47, v47, v44
	v_cvt_pk_bf16_f32 v44, v52, v53
	v_cvt_pk_bf16_f32 v45, v54, v55
	v_cvt_pk_bf16_f32 v46, v56, v57
	v_cvt_pk_bf16_f32 v47, v58, v47
	global_store_dwordx4 v[96:97], v[44:47], off offset:256 sc1
	s_nop 1
	v_lshlrev_b32_e32 v46, 16, v72
	v_mul_f32_e32 v46, v48, v46
	v_lshlrev_b32_e32 v48, 16, v73
	v_and_b32_e32 v47, 0xffff0000, v72
	v_mul_f32_e32 v48, v50, v48
	v_lshlrev_b32_e32 v50, 16, v74
	v_mul_f32_e32 v47, v49, v47
	v_and_b32_e32 v49, 0xffff0000, v73
	v_mul_f32_e32 v50, v40, v50
	v_and_b32_e32 v40, 0xffff0000, v74
	v_mul_f32_e32 v49, v51, v49
	v_mul_f32_e32 v51, v41, v40
	v_lshlrev_b32_e32 v40, 16, v75
	v_lshlrev_b64 v[44:45], 12, v[98:99]
	v_mul_f32_e32 v52, v42, v40
	v_and_b32_e32 v40, 0xffff0000, v75
	v_lshl_add_u64 v[44:45], v[152:153], 0, v[44:45]
	v_mul_f32_e32 v43, v43, v40
	v_cvt_pk_bf16_f32 v40, v46, v47
	v_cvt_pk_bf16_f32 v41, v48, v49
	v_cvt_pk_bf16_f32 v42, v50, v51
	v_cvt_pk_bf16_f32 v43, v52, v43
	global_store_dwordx4 v[44:45], v[40:43], off sc1
	s_nop 1
	v_lshlrev_b32_e32 v40, 16, v76
	v_mul_f32_e32 v36, v36, v40
	v_and_b32_e32 v40, 0xffff0000, v76
	v_mul_f32_e32 v37, v37, v40
	v_lshlrev_b32_e32 v40, 16, v77
	v_mul_f32_e32 v38, v38, v40
	v_and_b32_e32 v40, 0xffff0000, v77
	v_mul_f32_e32 v39, v39, v40
	v_lshlrev_b32_e32 v40, 16, v78
	v_mul_f32_e32 v40, v28, v40
	v_and_b32_e32 v28, 0xffff0000, v78
	v_mul_f32_e32 v41, v29, v28
	v_lshlrev_b32_e32 v28, 16, v79
	v_mul_f32_e32 v42, v30, v28
	v_and_b32_e32 v28, 0xffff0000, v79
	v_mul_f32_e32 v31, v31, v28
	v_cvt_pk_bf16_f32 v28, v36, v37
	v_cvt_pk_bf16_f32 v29, v38, v39
	v_cvt_pk_bf16_f32 v30, v40, v41
	v_cvt_pk_bf16_f32 v31, v42, v31
	global_store_dwordx4 v[44:45], v[28:31], off offset:256 sc1
	s_nop 1
	v_lshlrev_b32_e32 v30, 16, v80
	v_mul_f32_e32 v30, v32, v30
	v_lshlrev_b32_e32 v32, 16, v81
	v_and_b32_e32 v31, 0xffff0000, v80
	v_mul_f32_e32 v32, v34, v32
	v_lshlrev_b32_e32 v34, 16, v82
	v_mul_f32_e32 v31, v33, v31
	v_and_b32_e32 v33, 0xffff0000, v81
	v_mul_f32_e32 v34, v24, v34
	v_and_b32_e32 v24, 0xffff0000, v82
	v_mul_f32_e32 v33, v35, v33
	v_mul_f32_e32 v35, v25, v24
	v_lshlrev_b32_e32 v24, 16, v83
	v_lshlrev_b64 v[28:29], 12, v[100:101]
	v_mul_f32_e32 v36, v26, v24
	v_and_b32_e32 v24, 0xffff0000, v83
	v_lshl_add_u64 v[28:29], v[152:153], 0, v[28:29]
	v_mul_f32_e32 v27, v27, v24
	v_cvt_pk_bf16_f32 v24, v30, v31
	v_cvt_pk_bf16_f32 v25, v32, v33
	v_cvt_pk_bf16_f32 v26, v34, v35
	v_cvt_pk_bf16_f32 v27, v36, v27
	global_store_dwordx4 v[28:29], v[24:27], off sc1
	s_nop 1
	v_lshlrev_b32_e32 v24, 16, v84
	v_mul_f32_e32 v20, v20, v24
	v_and_b32_e32 v24, 0xffff0000, v84
	v_mul_f32_e32 v21, v21, v24
	v_lshlrev_b32_e32 v24, 16, v85
	v_mul_f32_e32 v22, v22, v24
	v_and_b32_e32 v24, 0xffff0000, v85
	v_mul_f32_e32 v23, v23, v24
	v_lshlrev_b32_e32 v24, 16, v86
	v_mul_f32_e32 v24, v12, v24
	v_and_b32_e32 v12, 0xffff0000, v86
	v_mul_f32_e32 v25, v13, v12
	v_lshlrev_b32_e32 v12, 16, v87
	v_mul_f32_e32 v26, v14, v12
	v_and_b32_e32 v12, 0xffff0000, v87
	v_mul_f32_e32 v15, v15, v12
	v_cvt_pk_bf16_f32 v12, v20, v21
	v_cvt_pk_bf16_f32 v13, v22, v23
	v_cvt_pk_bf16_f32 v14, v24, v25
	v_cvt_pk_bf16_f32 v15, v26, v15
	global_store_dwordx4 v[28:29], v[12:15], off offset:256 sc1
	s_nop 1
	v_lshlrev_b32_e32 v14, 16, v88
	v_mul_f32_e32 v14, v16, v14
	v_lshlrev_b32_e32 v16, 16, v89
	v_and_b32_e32 v15, 0xffff0000, v88
	v_mul_f32_e32 v16, v18, v16
	v_lshlrev_b32_e32 v18, 16, v90
	v_mul_f32_e32 v15, v17, v15
	v_and_b32_e32 v17, 0xffff0000, v89
	v_mul_f32_e32 v18, v8, v18
	v_and_b32_e32 v8, 0xffff0000, v90
	v_mul_f32_e32 v17, v19, v17
	v_mul_f32_e32 v19, v9, v8
	v_lshlrev_b32_e32 v8, 16, v91
	v_lshlrev_b64 v[12:13], 12, v[102:103]
	v_mul_f32_e32 v20, v10, v8
	v_and_b32_e32 v8, 0xffff0000, v91
	v_lshl_add_u64 v[12:13], v[152:153], 0, v[12:13]
	v_mul_f32_e32 v11, v11, v8
	v_cvt_pk_bf16_f32 v8, v14, v15
	v_cvt_pk_bf16_f32 v9, v16, v17
	v_cvt_pk_bf16_f32 v10, v18, v19
	v_cvt_pk_bf16_f32 v11, v20, v11
	global_store_dwordx4 v[12:13], v[8:11], off sc1
	s_nop 1
	v_lshlrev_b32_e32 v8, 16, v92
	v_mul_f32_e32 v4, v4, v8
	v_and_b32_e32 v8, 0xffff0000, v92
	v_mul_f32_e32 v5, v5, v8
	v_lshlrev_b32_e32 v8, 16, v93
	v_mul_f32_e32 v6, v6, v8
	v_and_b32_e32 v8, 0xffff0000, v93
	v_mul_f32_e32 v7, v7, v8
	v_lshlrev_b32_e32 v8, 16, v94
	v_mul_f32_e32 v8, v0, v8
	v_and_b32_e32 v0, 0xffff0000, v94
	v_mul_f32_e32 v9, v1, v0
	v_lshlrev_b32_e32 v0, 16, v95
	v_mul_f32_e32 v10, v2, v0
	v_and_b32_e32 v0, 0xffff0000, v95
	v_mul_f32_e32 v3, v3, v0
	v_cvt_pk_bf16_f32 v0, v4, v5
	v_cvt_pk_bf16_f32 v1, v6, v7
	v_cvt_pk_bf16_f32 v2, v8, v9
	v_cvt_pk_bf16_f32 v3, v10, v3
	global_store_dwordx4 v[12:13], v[0:3], off offset:256 sc1
	s_cbranch_vccnz .LBB0_900

.LBB0_982:
	v_lshlrev_b32_e32 v250, 16, v188
	v_sub_f32_e32 v240, v250, v236
	v_mul_f32_e32 v240, v237, v240
	v_fma_f32 v240, v88, v240, v92
	v_and_b32_e32 v188, 0xffff0000, v188
	v_cndmask_b32_e64 v240, v240, v250, s[38:39]
	v_fmamk_f32 v156, v240, 0x3fb504f3, v156
	v_sub_f32_e32 v240, v188, v236
	v_mul_f32_e32 v240, v237, v240
	v_fma_f32 v240, v89, v240, v93
	v_lshlrev_b32_e32 v251, 16, v189
	v_cndmask_b32_e64 v188, v240, v188, s[38:39]
	v_fmamk_f32 v157, v188, 0x3fb504f3, v157
	v_sub_f32_e32 v188, v251, v236
	v_mul_f32_e32 v188, v237, v188
	v_fma_f32 v188, v90, v188, v94
	v_and_b32_e32 v189, 0xffff0000, v189
	v_cndmask_b32_e64 v188, v188, v251, s[38:39]
	v_fmamk_f32 v158, v188, 0x3fb504f3, v158
	v_sub_f32_e32 v188, v189, v236
	v_mul_f32_e32 v188, v237, v188
	v_fma_f32 v188, v91, v188, v95
	v_lshlrev_b32_e32 v252, 16, v190
	v_cndmask_b32_e64 v188, v188, v189, s[38:39]
	v_fmac_f32_e32 v159, 0x3fb504f3, v188
	v_sub_f32_e32 v188, v252, v236
	v_mul_f32_e32 v188, v237, v188
	v_fma_f32 v188, v80, v188, v84
	v_and_b32_e32 v190, 0xffff0000, v190
	v_cndmask_b32_e64 v188, v188, v252, s[38:39]
	v_fmamk_f32 v152, v188, 0x3fb504f3, v152
	v_sub_f32_e32 v188, v190, v236
	v_mul_f32_e32 v188, v237, v188
	v_fma_f32 v188, v81, v188, v85
	v_lshlrev_b32_e32 v253, 16, v191
	v_cndmask_b32_e64 v188, v188, v190, s[38:39]
	v_fmamk_f32 v153, v188, 0x3fb504f3, v153
	v_sub_f32_e32 v188, v253, v236
	v_mul_f32_e32 v188, v237, v188
	v_fma_f32 v188, v82, v188, v86
	v_and_b32_e32 v191, 0xffff0000, v191
	v_cndmask_b32_e64 v188, v188, v253, s[38:39]
	v_fmamk_f32 v240, v188, 0x3fb504f3, v154
	v_sub_f32_e32 v154, v191, v236
	v_mul_f32_e32 v154, v237, v154
	v_fma_f32 v154, v83, v154, v87
	v_lshl_add_u64 v[212:213], v[212:213], 1, s[46:47]
	v_cndmask_b32_e64 v154, v154, v191, s[38:39]
	v_lshl_add_u64 v[238:239], v[212:213], 0, v[238:239]
	v_fmac_f32_e32 v155, 0x3fb504f3, v154
	v_cvt_pk_bf16_f32 v188, v156, v157
	v_cvt_pk_bf16_f32 v189, v158, v159
	v_cvt_pk_bf16_f32 v190, v152, v153
	v_cvt_pk_bf16_f32 v191, v240, v155
	v_lshlrev_b32_e32 v154, 16, v184
	global_store_dwordx4 v[238:239], v[188:191], off sc1
	v_and_b32_e32 v184, 0xffff0000, v184
	s_nop 0
	v_sub_f32_e32 v191, v154, v236
	v_mul_f32_e32 v191, v237, v191
	v_fma_f32 v191, v72, v191, v76
	v_cndmask_b32_e64 v154, v191, v154, s[38:39]
	v_fmamk_f32 v148, v154, 0x3fb504f3, v148
	v_sub_f32_e32 v154, v184, v236
	v_mul_f32_e32 v154, v237, v154
	v_fma_f32 v154, v73, v154, v77
	v_lshlrev_b32_e32 v188, 16, v185
	v_cndmask_b32_e64 v154, v154, v184, s[38:39]
	v_fmamk_f32 v149, v154, 0x3fb504f3, v149
	v_sub_f32_e32 v154, v188, v236
	v_mul_f32_e32 v154, v237, v154
	v_fma_f32 v154, v74, v154, v78
	v_and_b32_e32 v185, 0xffff0000, v185
	v_cndmask_b32_e64 v154, v154, v188, s[38:39]
	v_fmamk_f32 v150, v154, 0x3fb504f3, v150
	v_sub_f32_e32 v154, v185, v236
	v_mul_f32_e32 v154, v237, v154
	v_fma_f32 v154, v75, v154, v79
	v_lshlrev_b32_e32 v189, 16, v186
	v_cndmask_b32_e64 v154, v154, v185, s[38:39]
	v_fmac_f32_e32 v151, 0x3fb504f3, v154
	v_sub_f32_e32 v154, v189, v236
	v_mul_f32_e32 v154, v237, v154
	v_fma_f32 v154, v64, v154, v68
	v_and_b32_e32 v186, 0xffff0000, v186
	v_cndmask_b32_e64 v154, v154, v189, s[38:39]
	v_fmamk_f32 v184, v154, 0x3fb504f3, v144
	v_sub_f32_e32 v144, v186, v236
	v_mul_f32_e32 v144, v237, v144
	v_fma_f32 v144, v65, v144, v69
	v_lshlrev_b32_e32 v190, 16, v187
	v_cndmask_b32_e64 v144, v144, v186, s[38:39]
	v_fmamk_f32 v185, v144, 0x3fb504f3, v145
	v_sub_f32_e32 v144, v190, v236
	v_mul_f32_e32 v144, v237, v144
	v_fma_f32 v144, v66, v144, v70
	v_and_b32_e32 v187, 0xffff0000, v187
	v_cndmask_b32_e64 v144, v144, v190, s[38:39]
	v_fmamk_f32 v186, v144, 0x3fb504f3, v146
	v_sub_f32_e32 v144, v187, v236
	v_mul_f32_e32 v144, v237, v144
	v_fma_f32 v144, v67, v144, v71
	v_cndmask_b32_e64 v144, v144, v187, s[38:39]
	v_fmac_f32_e32 v147, 0x3fb504f3, v144
	v_add_f32_e32 v144, 0, v156
	v_add_f32_e32 v144, v157, v144
	v_add_f32_e32 v144, v158, v144
	v_mul_f32_e32 v146, v157, v157
	v_add_f32_e32 v144, v159, v144
	v_fmac_f32_e32 v146, v156, v156
	v_add_f32_e32 v144, v152, v144
	v_fmac_f32_e32 v146, v158, v158
	v_add_f32_e32 v144, v153, v144
	v_fmac_f32_e32 v146, v159, v159
	v_add_f32_e32 v144, v240, v144
	v_fmac_f32_e32 v146, v152, v152
	v_add_f32_e32 v144, v155, v144
	v_fmac_f32_e32 v146, v153, v153
	v_add_f32_e32 v144, v148, v144
	v_fmac_f32_e32 v146, v240, v240
	v_add_f32_e32 v144, v149, v144
	v_fmac_f32_e32 v146, v155, v155
	v_add_f32_e32 v144, v150, v144
	v_cvt_pk_bf16_f32 v154, v148, v149
	v_fmac_f32_e32 v146, v148, v148
	v_add_f32_e32 v144, v151, v144
	v_and_b32_e32 v148, 64, v242
	v_fmac_f32_e32 v146, v149, v149
	v_add_f32_e32 v144, v184, v144
	v_xor_b32_e32 v145, 16, v242
	v_add_u32_e32 v148, 64, v148
	v_fmac_f32_e32 v146, v150, v150
	v_add_f32_e32 v144, v185, v144
	v_cmp_lt_i32_e32 vcc, v145, v148
	v_fmac_f32_e32 v146, v151, v151
	v_add_f32_e32 v144, v186, v144
	v_cndmask_b32_e32 v145, v242, v145, vcc
	v_add_f32_e32 v144, v147, v144
	v_lshlrev_b32_e32 v152, 2, v145
	v_fmac_f32_e32 v146, v184, v184
	ds_bpermute_b32 v145, v152, v144
	v_fmac_f32_e32 v146, v185, v185
	v_fmac_f32_e32 v146, v186, v186
	v_fmac_f32_e32 v146, v147, v147
	ds_bpermute_b32 v149, v152, v146
	s_waitcnt lgkmcnt(0)
	v_add_f32_e32 v144, v144, v145
	v_xor_b32_e32 v145, 32, v242
	v_cmp_lt_i32_e32 vcc, v145, v148
	v_cvt_pk_bf16_f32 v155, v150, v151
	v_add_f32_e32 v146, v146, v149
	v_cvt_pk_bf16_f32 v156, v184, v185
	v_cvt_pk_bf16_f32 v157, v186, v147
	global_store_dwordx4 v[238:239], v[154:157], off offset:256 sc1
	v_cndmask_b32_e32 v145, v242, v145, vcc
	v_lshlrev_b32_e32 v153, 2, v145
	ds_bpermute_b32 v145, v153, v144
	ds_bpermute_b32 v148, v153, v146
	s_and_saveexec_b64 s[2:3], s[40:41]
	s_cbranch_execz .LBB0_984
	s_waitcnt lgkmcnt(1)
	v_add_f32_e32 v147, v144, v145
	v_lshl_add_u64 v[144:145], v[214:215], 3, s[54:55]
	s_waitcnt lgkmcnt(0)
	v_add_f32_e32 v146, v146, v148
	global_atomic_add_f32 v[144:145], v147, off
	global_atomic_add_f32 v[144:145], v146, off offset:4

.LBB0_987:
	s_waitcnt lgkmcnt(1)
	v_lshlrev_b32_e32 v145, 16, v180
	v_sub_f32_e32 v157, v145, v232
	v_mul_f32_e32 v157, v144, v157
	v_fma_f32 v157, v88, v157, v92
	v_and_b32_e32 v146, 0xffff0000, v180
	v_cndmask_b32_e64 v145, v157, v145, s[38:39]
	v_fmamk_f32 v140, v145, 0x3fb504f3, v140
	v_sub_f32_e32 v145, v146, v232
	v_mul_f32_e32 v145, v144, v145
	v_fma_f32 v145, v89, v145, v93
	v_lshlrev_b32_e32 v147, 16, v181
	v_cndmask_b32_e64 v145, v145, v146, s[38:39]
	v_fmamk_f32 v141, v145, 0x3fb504f3, v141
	v_sub_f32_e32 v145, v147, v232
	v_mul_f32_e32 v145, v144, v145
	v_fma_f32 v145, v90, v145, v94
	s_waitcnt lgkmcnt(0)
	v_and_b32_e32 v148, 0xffff0000, v181
	v_cndmask_b32_e64 v145, v145, v147, s[38:39]
	v_fmamk_f32 v142, v145, 0x3fb504f3, v142
	v_sub_f32_e32 v145, v148, v232
	v_mul_f32_e32 v145, v144, v145
	v_fma_f32 v145, v91, v145, v95
	v_lshlrev_b32_e32 v149, 16, v182
	v_cndmask_b32_e64 v145, v145, v148, s[38:39]
	v_fmac_f32_e32 v143, 0x3fb504f3, v145
	v_sub_f32_e32 v145, v149, v232
	v_mul_f32_e32 v145, v144, v145
	v_fma_f32 v145, v80, v145, v84
	v_and_b32_e32 v154, 0xffff0000, v182
	v_cndmask_b32_e64 v145, v145, v149, s[38:39]
	v_fmamk_f32 v136, v145, 0x3fb504f3, v136
	v_sub_f32_e32 v145, v154, v232
	v_mul_f32_e32 v145, v144, v145
	v_fma_f32 v145, v81, v145, v85
	v_lshlrev_b32_e32 v155, 16, v183
	v_cndmask_b32_e64 v145, v145, v154, s[38:39]
	v_fmamk_f32 v137, v145, 0x3fb504f3, v137
	v_sub_f32_e32 v145, v155, v232
	v_mul_f32_e32 v145, v144, v145
	v_fma_f32 v145, v82, v145, v86
	v_and_b32_e32 v156, 0xffff0000, v183
	v_cndmask_b32_e64 v145, v145, v155, s[38:39]
	v_fmamk_f32 v138, v145, 0x3fb504f3, v138
	v_sub_f32_e32 v145, v156, v232
	v_mul_f32_e32 v145, v144, v145
	v_fma_f32 v145, v83, v145, v87
	v_cndmask_b32_e64 v145, v145, v156, s[38:39]
	v_fmac_f32_e32 v139, 0x3fb504f3, v145
	v_lshlrev_b32_e32 v145, 16, v176
	v_lshlrev_b32_e32 v155, 16, v177
	v_and_b32_e32 v156, 0xffff0000, v177
	v_sub_f32_e32 v177, v145, v232
	v_mul_f32_e32 v177, v144, v177
	v_fma_f32 v177, v72, v177, v76
	v_and_b32_e32 v154, 0xffff0000, v176
	v_cndmask_b32_e64 v145, v177, v145, s[38:39]
	v_fmamk_f32 v132, v145, 0x3fb504f3, v132
	v_sub_f32_e32 v145, v154, v232
	v_mul_f32_e32 v145, v144, v145
	v_fma_f32 v145, v73, v145, v77
	v_cndmask_b32_e64 v145, v145, v154, s[38:39]
	v_fmamk_f32 v133, v145, 0x3fb504f3, v133
	v_sub_f32_e32 v145, v155, v232
	v_mul_f32_e32 v145, v144, v145
	v_fma_f32 v145, v74, v145, v78
	v_cndmask_b32_e64 v145, v145, v155, s[38:39]
	v_fmamk_f32 v145, v145, 0x3fb504f3, v134
	v_sub_f32_e32 v134, v156, v232
	v_mul_f32_e32 v134, v144, v134
	v_fma_f32 v134, v75, v134, v79
	v_lshlrev_b32_e32 v157, 16, v178
	v_cndmask_b32_e64 v134, v134, v156, s[38:39]
	v_fmac_f32_e32 v135, 0x3fb504f3, v134
	v_sub_f32_e32 v134, v157, v232
	v_mul_f32_e32 v134, v144, v134
	v_fma_f32 v134, v64, v134, v68
	v_and_b32_e32 v158, 0xffff0000, v178
	v_cndmask_b32_e64 v134, v134, v157, s[38:39]
	v_fmamk_f32 v154, v134, 0x3fb504f3, v128
	v_sub_f32_e32 v128, v158, v232
	v_mul_f32_e32 v128, v144, v128
	v_fma_f32 v128, v65, v128, v69
	v_lshlrev_b32_e32 v159, 16, v179
	v_cndmask_b32_e64 v128, v128, v158, s[38:39]
	v_fmamk_f32 v155, v128, 0x3fb504f3, v129
	v_sub_f32_e32 v128, v159, v232
	v_mul_f32_e32 v128, v144, v128
	v_fma_f32 v128, v66, v128, v70
	v_and_b32_e32 v176, 0xffff0000, v179
	v_cndmask_b32_e64 v128, v128, v159, s[38:39]
	v_fmamk_f32 v156, v128, 0x3fb504f3, v130
	v_sub_f32_e32 v128, v176, v232
	v_mul_f32_e32 v128, v144, v128
	v_fma_f32 v128, v67, v128, v71
	v_cndmask_b32_e64 v128, v128, v176, s[38:39]
	v_fmac_f32_e32 v131, 0x3fb504f3, v128
	v_mul_f32_e32 v130, v141, v141
	v_add_f32_e32 v128, 0, v140
	v_fmac_f32_e32 v130, v140, v140
	v_add_f32_e32 v128, v141, v128
	v_fmac_f32_e32 v130, v142, v142
	v_add_f32_e32 v128, v142, v128
	v_fmac_f32_e32 v130, v143, v143
	v_add_f32_e32 v128, v143, v128
	v_fmac_f32_e32 v130, v136, v136
	v_add_f32_e32 v128, v136, v128
	v_fmac_f32_e32 v130, v137, v137
	v_add_f32_e32 v128, v137, v128
	v_fmac_f32_e32 v130, v138, v138
	v_add_f32_e32 v128, v138, v128
	v_fmac_f32_e32 v130, v139, v139
	v_add_f32_e32 v128, v139, v128
	v_fmac_f32_e32 v130, v132, v132
	v_add_f32_e32 v128, v132, v128
	v_fmac_f32_e32 v130, v133, v133
	v_add_f32_e32 v128, v133, v128
	v_fmac_f32_e32 v130, v145, v145
	v_add_f32_e32 v128, v145, v128
	v_fmac_f32_e32 v130, v135, v135
	v_add_f32_e32 v128, v135, v128
	v_fmac_f32_e32 v130, v154, v154
	v_add_f32_e32 v128, v154, v128
	v_fmac_f32_e32 v130, v155, v155
	v_add_f32_e32 v128, v155, v128
	v_fmac_f32_e32 v130, v156, v156
	v_add_f32_e32 v128, v156, v128
	v_add_f32_e32 v128, v131, v128
	v_fmac_f32_e32 v130, v131, v131
	v_cvt_pk_bf16_f32 v146, v140, v141
	v_cvt_pk_bf16_f32 v147, v142, v143
	v_cvt_pk_bf16_f32 v148, v136, v137
	ds_bpermute_b32 v129, v152, v128
	ds_bpermute_b32 v136, v152, v130
	v_lshl_add_u64 v[150:151], v[212:213], 0, v[234:235]
	v_cvt_pk_bf16_f32 v149, v138, v139
	global_store_dwordx4 v[150:151], v[146:149], off sc1
	s_waitcnt lgkmcnt(1)
	v_add_f32_e32 v128, v128, v129
	s_waitcnt lgkmcnt(0)
	v_add_f32_e32 v130, v130, v136
	v_cvt_pk_bf16_f32 v134, v132, v133
	ds_bpermute_b32 v129, v153, v128
	ds_bpermute_b32 v132, v153, v130
	v_cvt_pk_bf16_f32 v135, v145, v135
	v_cvt_pk_bf16_f32 v136, v154, v155
	v_cvt_pk_bf16_f32 v137, v156, v131
	global_store_dwordx4 v[150:151], v[134:137], off offset:256 sc1
	s_and_saveexec_b64 s[2:3], s[40:41]
	s_cbranch_execz .LBB0_989
	s_waitcnt lgkmcnt(1)
	v_add_f32_e32 v131, v128, v129
	v_lshl_add_u64 v[128:129], v[230:231], 3, s[54:55]
	s_waitcnt lgkmcnt(0)
	v_add_f32_e32 v130, v130, v132
	global_atomic_add_f32 v[128:129], v131, off
	global_atomic_add_f32 v[128:129], v130, off offset:4

.LBB0_992:
	s_waitcnt lgkmcnt(1)
	v_lshlrev_b32_e32 v129, 16, v172
	v_sub_f32_e32 v139, v129, v226
	v_mul_f32_e32 v139, v128, v139
	v_fma_f32 v139, v88, v139, v92
	v_and_b32_e32 v130, 0xffff0000, v172
	v_cndmask_b32_e64 v129, v139, v129, s[38:39]
	v_fmamk_f32 v124, v129, 0x3fb504f3, v124
	v_sub_f32_e32 v129, v130, v226
	v_mul_f32_e32 v129, v128, v129
	v_fma_f32 v129, v89, v129, v93
	v_lshlrev_b32_e32 v131, 16, v173
	v_cndmask_b32_e64 v129, v129, v130, s[38:39]
	v_fmamk_f32 v125, v129, 0x3fb504f3, v125
	v_sub_f32_e32 v129, v131, v226
	v_mul_f32_e32 v129, v128, v129
	v_fma_f32 v129, v90, v129, v94
	s_waitcnt lgkmcnt(0)
	v_and_b32_e32 v132, 0xffff0000, v173
	v_cndmask_b32_e64 v129, v129, v131, s[38:39]
	v_fmamk_f32 v126, v129, 0x3fb504f3, v126
	v_sub_f32_e32 v129, v132, v226
	v_mul_f32_e32 v129, v128, v129
	v_fma_f32 v129, v91, v129, v95
	v_lshlrev_b32_e32 v133, 16, v174
	v_cndmask_b32_e64 v129, v129, v132, s[38:39]
	v_fmac_f32_e32 v127, 0x3fb504f3, v129
	v_sub_f32_e32 v129, v133, v226
	v_mul_f32_e32 v129, v128, v129
	v_fma_f32 v129, v80, v129, v84
	v_and_b32_e32 v136, 0xffff0000, v174
	v_cndmask_b32_e64 v129, v129, v133, s[38:39]
	v_fmamk_f32 v120, v129, 0x3fb504f3, v120
	v_sub_f32_e32 v129, v136, v226
	v_mul_f32_e32 v129, v128, v129
	v_fma_f32 v129, v81, v129, v85
	v_lshlrev_b32_e32 v137, 16, v175
	v_cndmask_b32_e64 v129, v129, v136, s[38:39]
	v_fmamk_f32 v121, v129, 0x3fb504f3, v121
	v_sub_f32_e32 v129, v137, v226
	v_mul_f32_e32 v129, v128, v129
	v_fma_f32 v129, v82, v129, v86
	v_and_b32_e32 v138, 0xffff0000, v175
	v_cndmask_b32_e64 v129, v129, v137, s[38:39]
	v_fmamk_f32 v122, v129, 0x3fb504f3, v122
	v_sub_f32_e32 v129, v138, v226
	v_mul_f32_e32 v129, v128, v129
	v_fma_f32 v129, v83, v129, v87
	v_cndmask_b32_e64 v129, v129, v138, s[38:39]
	v_fmac_f32_e32 v123, 0x3fb504f3, v129
	v_lshlrev_b32_e32 v129, 16, v168
	v_sub_f32_e32 v143, v129, v226
	v_mul_f32_e32 v143, v128, v143
	v_fma_f32 v143, v72, v143, v76
	v_and_b32_e32 v136, 0xffff0000, v168
	v_cndmask_b32_e64 v129, v143, v129, s[38:39]
	v_fmamk_f32 v116, v129, 0x3fb504f3, v116
	v_sub_f32_e32 v129, v136, v226
	v_mul_f32_e32 v129, v128, v129
	v_fma_f32 v129, v73, v129, v77
	v_lshlrev_b32_e32 v137, 16, v169
	v_cndmask_b32_e64 v129, v129, v136, s[38:39]
	v_fmamk_f32 v117, v129, 0x3fb504f3, v117
	v_sub_f32_e32 v129, v137, v226
	v_mul_f32_e32 v129, v128, v129
	v_fma_f32 v129, v74, v129, v78
	v_and_b32_e32 v138, 0xffff0000, v169
	v_cndmask_b32_e64 v129, v129, v137, s[38:39]
	v_fmamk_f32 v129, v129, 0x3fb504f3, v118
	v_sub_f32_e32 v118, v138, v226
	v_mul_f32_e32 v118, v128, v118
	v_fma_f32 v118, v75, v118, v79
	v_lshlrev_b32_e32 v139, 16, v170
	v_cndmask_b32_e64 v118, v118, v138, s[38:39]
	v_fmac_f32_e32 v119, 0x3fb504f3, v118
	v_sub_f32_e32 v118, v139, v226
	v_mul_f32_e32 v118, v128, v118
	v_fma_f32 v118, v64, v118, v68
	v_and_b32_e32 v140, 0xffff0000, v170
	v_cndmask_b32_e64 v118, v118, v139, s[38:39]
	v_fmamk_f32 v136, v118, 0x3fb504f3, v112
	v_sub_f32_e32 v112, v140, v226
	v_mul_f32_e32 v112, v128, v112
	v_fma_f32 v112, v65, v112, v69
	v_lshlrev_b32_e32 v141, 16, v171
	v_cndmask_b32_e64 v112, v112, v140, s[38:39]
	v_fmamk_f32 v137, v112, 0x3fb504f3, v113
	v_sub_f32_e32 v112, v141, v226
	v_mul_f32_e32 v112, v128, v112
	v_fma_f32 v112, v66, v112, v70
	v_and_b32_e32 v142, 0xffff0000, v171
	v_cndmask_b32_e64 v112, v112, v141, s[38:39]
	v_fmamk_f32 v138, v112, 0x3fb504f3, v114
	v_sub_f32_e32 v112, v142, v226
	v_mul_f32_e32 v112, v128, v112
	v_fma_f32 v112, v67, v112, v71
	v_cndmask_b32_e64 v112, v112, v142, s[38:39]
	v_fmac_f32_e32 v115, 0x3fb504f3, v112
	v_mul_f32_e32 v114, v125, v125
	v_add_f32_e32 v112, 0, v124
	v_fmac_f32_e32 v114, v124, v124
	v_add_f32_e32 v112, v125, v112
	v_fmac_f32_e32 v114, v126, v126
	v_add_f32_e32 v112, v126, v112
	v_fmac_f32_e32 v114, v127, v127
	v_add_f32_e32 v112, v127, v112
	v_fmac_f32_e32 v114, v120, v120
	v_add_f32_e32 v112, v120, v112
	v_fmac_f32_e32 v114, v121, v121
	v_add_f32_e32 v112, v121, v112
	v_fmac_f32_e32 v114, v122, v122
	v_add_f32_e32 v112, v122, v112
	v_fmac_f32_e32 v114, v123, v123
	v_add_f32_e32 v112, v123, v112
	v_fmac_f32_e32 v114, v116, v116
	v_add_f32_e32 v112, v116, v112
	v_fmac_f32_e32 v114, v117, v117
	v_add_f32_e32 v112, v117, v112
	v_fmac_f32_e32 v114, v129, v129
	v_add_f32_e32 v112, v129, v112
	v_fmac_f32_e32 v114, v119, v119
	v_add_f32_e32 v112, v119, v112
	v_fmac_f32_e32 v114, v136, v136
	v_add_f32_e32 v112, v136, v112
	v_fmac_f32_e32 v114, v137, v137
	v_add_f32_e32 v112, v137, v112
	v_fmac_f32_e32 v114, v138, v138
	v_add_f32_e32 v112, v138, v112
	v_add_f32_e32 v112, v115, v112
	v_fmac_f32_e32 v114, v115, v115
	v_cvt_pk_bf16_f32 v130, v124, v125
	v_cvt_pk_bf16_f32 v131, v126, v127
	v_cvt_pk_bf16_f32 v132, v120, v121
	ds_bpermute_b32 v113, v152, v112
	ds_bpermute_b32 v120, v152, v114
	v_lshl_add_u64 v[134:135], v[212:213], 0, v[228:229]
	v_cvt_pk_bf16_f32 v133, v122, v123
	global_store_dwordx4 v[134:135], v[130:133], off sc1
	s_waitcnt lgkmcnt(1)
	v_add_f32_e32 v112, v112, v113
	s_waitcnt lgkmcnt(0)
	v_add_f32_e32 v114, v114, v120
	v_cvt_pk_bf16_f32 v118, v116, v117
	ds_bpermute_b32 v113, v153, v112
	ds_bpermute_b32 v116, v153, v114
	v_cvt_pk_bf16_f32 v119, v129, v119
	v_cvt_pk_bf16_f32 v120, v136, v137
	v_cvt_pk_bf16_f32 v121, v138, v115
	global_store_dwordx4 v[134:135], v[118:121], off offset:256 sc1
	s_and_saveexec_b64 s[2:3], s[40:41]
	s_cbranch_execz .LBB0_994
	s_waitcnt lgkmcnt(1)
	v_add_f32_e32 v115, v112, v113
	v_lshl_add_u64 v[112:113], v[224:225], 3, s[54:55]
	s_waitcnt lgkmcnt(0)
	v_add_f32_e32 v114, v114, v116
	global_atomic_add_f32 v[112:113], v115, off
	global_atomic_add_f32 v[112:113], v114, off offset:4

.LBB0_997:
	s_waitcnt lgkmcnt(1)
	v_lshlrev_b32_e32 v113, 16, v164
	v_sub_f32_e32 v123, v113, v216
	v_mul_f32_e32 v123, v112, v123
	v_fma_f32 v123, v88, v123, v92
	v_and_b32_e32 v114, 0xffff0000, v164
	v_cndmask_b32_e64 v113, v123, v113, s[38:39]
	v_fmamk_f32 v108, v113, 0x3fb504f3, v108
	v_sub_f32_e32 v113, v114, v216
	v_mul_f32_e32 v113, v112, v113
	v_fma_f32 v113, v89, v113, v93
	v_lshlrev_b32_e32 v115, 16, v165
	v_cndmask_b32_e64 v113, v113, v114, s[38:39]
	v_fmamk_f32 v109, v113, 0x3fb504f3, v109
	v_sub_f32_e32 v113, v115, v216
	v_mul_f32_e32 v113, v112, v113
	v_fma_f32 v113, v90, v113, v94
	s_waitcnt lgkmcnt(0)
	v_and_b32_e32 v116, 0xffff0000, v165
	v_cndmask_b32_e64 v113, v113, v115, s[38:39]
	v_fmamk_f32 v110, v113, 0x3fb504f3, v110
	v_sub_f32_e32 v113, v116, v216
	v_mul_f32_e32 v113, v112, v113
	v_fma_f32 v113, v91, v113, v95
	v_lshlrev_b32_e32 v117, 16, v166
	v_cndmask_b32_e64 v113, v113, v116, s[38:39]
	v_fmac_f32_e32 v111, 0x3fb504f3, v113
	v_sub_f32_e32 v113, v117, v216
	v_mul_f32_e32 v113, v112, v113
	v_fma_f32 v113, v80, v113, v84
	v_and_b32_e32 v120, 0xffff0000, v166
	v_cndmask_b32_e64 v113, v113, v117, s[38:39]
	v_fmamk_f32 v104, v113, 0x3fb504f3, v104
	v_sub_f32_e32 v113, v120, v216
	v_mul_f32_e32 v113, v112, v113
	v_fma_f32 v113, v81, v113, v85
	v_lshlrev_b32_e32 v121, 16, v167
	v_cndmask_b32_e64 v113, v113, v120, s[38:39]
	v_fmamk_f32 v105, v113, 0x3fb504f3, v105
	v_sub_f32_e32 v113, v121, v216
	v_mul_f32_e32 v113, v112, v113
	v_fma_f32 v113, v82, v113, v86
	v_and_b32_e32 v122, 0xffff0000, v167
	v_cndmask_b32_e64 v113, v113, v121, s[38:39]
	v_fmamk_f32 v106, v113, 0x3fb504f3, v106
	v_sub_f32_e32 v113, v122, v216
	v_mul_f32_e32 v113, v112, v113
	v_fma_f32 v113, v83, v113, v87
	v_cndmask_b32_e64 v113, v113, v122, s[38:39]
	v_fmac_f32_e32 v107, 0x3fb504f3, v113
	v_lshlrev_b32_e32 v113, 16, v160
	v_sub_f32_e32 v127, v113, v216
	v_mul_f32_e32 v127, v112, v127
	v_fma_f32 v127, v72, v127, v76
	v_and_b32_e32 v120, 0xffff0000, v160
	v_cndmask_b32_e64 v113, v127, v113, s[38:39]
	v_fmamk_f32 v100, v113, 0x3fb504f3, v100
	v_sub_f32_e32 v113, v120, v216
	v_mul_f32_e32 v113, v112, v113
	v_fma_f32 v113, v73, v113, v77
	v_lshlrev_b32_e32 v121, 16, v161
	v_cndmask_b32_e64 v113, v113, v120, s[38:39]
	v_fmamk_f32 v101, v113, 0x3fb504f3, v101
	v_sub_f32_e32 v113, v121, v216
	v_mul_f32_e32 v113, v112, v113
	v_fma_f32 v113, v74, v113, v78
	v_and_b32_e32 v122, 0xffff0000, v161
	v_cndmask_b32_e64 v113, v113, v121, s[38:39]
	v_fmamk_f32 v113, v113, 0x3fb504f3, v102
	v_sub_f32_e32 v102, v122, v216
	v_mul_f32_e32 v102, v112, v102
	v_fma_f32 v102, v75, v102, v79
	v_lshlrev_b32_e32 v123, 16, v162
	v_cndmask_b32_e64 v102, v102, v122, s[38:39]
	v_fmac_f32_e32 v103, 0x3fb504f3, v102
	v_sub_f32_e32 v102, v123, v216
	v_mul_f32_e32 v102, v112, v102
	v_fma_f32 v102, v64, v102, v68
	v_and_b32_e32 v124, 0xffff0000, v162
	v_cndmask_b32_e64 v102, v102, v123, s[38:39]
	v_fmamk_f32 v120, v102, 0x3fb504f3, v96
	v_sub_f32_e32 v96, v124, v216
	v_mul_f32_e32 v96, v112, v96
	v_fma_f32 v96, v65, v96, v69
	v_lshlrev_b32_e32 v125, 16, v163
	v_cndmask_b32_e64 v96, v96, v124, s[38:39]
	v_fmamk_f32 v121, v96, 0x3fb504f3, v97
	v_sub_f32_e32 v96, v125, v216
	v_mul_f32_e32 v96, v112, v96
	v_fma_f32 v96, v66, v96, v70
	v_and_b32_e32 v126, 0xffff0000, v163
	v_cndmask_b32_e64 v96, v96, v125, s[38:39]
	v_fmamk_f32 v122, v96, 0x3fb504f3, v98
	v_sub_f32_e32 v96, v126, v216
	v_mul_f32_e32 v96, v112, v96
	v_fma_f32 v96, v67, v96, v71
	v_cndmask_b32_e64 v96, v96, v126, s[38:39]
	v_fmac_f32_e32 v99, 0x3fb504f3, v96
	v_mul_f32_e32 v98, v109, v109
	v_add_f32_e32 v96, 0, v108
	v_fmac_f32_e32 v98, v108, v108
	v_add_f32_e32 v96, v109, v96
	v_fmac_f32_e32 v98, v110, v110
	v_add_f32_e32 v96, v110, v96
	v_fmac_f32_e32 v98, v111, v111
	v_add_f32_e32 v96, v111, v96
	v_fmac_f32_e32 v98, v104, v104
	v_add_f32_e32 v96, v104, v96
	v_fmac_f32_e32 v98, v105, v105
	v_add_f32_e32 v96, v105, v96
	v_fmac_f32_e32 v98, v106, v106
	v_add_f32_e32 v96, v106, v96
	v_fmac_f32_e32 v98, v107, v107
	v_add_f32_e32 v96, v107, v96
	v_fmac_f32_e32 v98, v100, v100
	v_add_f32_e32 v96, v100, v96
	v_fmac_f32_e32 v98, v101, v101
	v_add_f32_e32 v96, v101, v96
	v_fmac_f32_e32 v98, v113, v113
	v_add_f32_e32 v96, v113, v96
	v_fmac_f32_e32 v98, v103, v103
	v_add_f32_e32 v96, v103, v96
	v_fmac_f32_e32 v98, v120, v120
	v_add_f32_e32 v96, v120, v96
	v_fmac_f32_e32 v98, v121, v121
	v_add_f32_e32 v96, v121, v96
	v_fmac_f32_e32 v98, v122, v122
	v_add_f32_e32 v96, v122, v96
	v_add_f32_e32 v96, v99, v96
	v_fmac_f32_e32 v98, v99, v99
	v_cvt_pk_bf16_f32 v114, v108, v109
	v_cvt_pk_bf16_f32 v115, v110, v111
	v_cvt_pk_bf16_f32 v116, v104, v105
	ds_bpermute_b32 v97, v152, v96
	ds_bpermute_b32 v104, v152, v98
	v_lshl_add_u64 v[118:119], v[212:213], 0, v[222:223]
	v_cvt_pk_bf16_f32 v117, v106, v107
	global_store_dwordx4 v[118:119], v[114:117], off sc1
	s_waitcnt lgkmcnt(1)
	v_add_f32_e32 v96, v96, v97
	s_waitcnt lgkmcnt(0)
	v_add_f32_e32 v98, v98, v104
	v_cvt_pk_bf16_f32 v102, v100, v101
	ds_bpermute_b32 v97, v153, v96
	ds_bpermute_b32 v100, v153, v98
	v_cvt_pk_bf16_f32 v103, v113, v103
	v_cvt_pk_bf16_f32 v104, v120, v121
	v_cvt_pk_bf16_f32 v105, v122, v99
	global_store_dwordx4 v[118:119], v[102:105], off offset:256 sc1
	s_and_saveexec_b64 s[2:3], s[40:41]
	s_cbranch_execz .LBB0_999
	s_waitcnt lgkmcnt(1)
	v_add_f32_e32 v99, v96, v97
	v_lshl_add_u64 v[96:97], v[220:221], 3, s[54:55]
	s_waitcnt lgkmcnt(0)
	v_add_f32_e32 v98, v98, v100
	global_atomic_add_f32 v[96:97], v99, off
	global_atomic_add_f32 v[96:97], v98, off offset:4

.LBB0_1003:
	v_lshlrev_b32_e32 v150, 16, v124
	v_sub_f32_e32 v158, v150, v154
	v_mul_f32_e32 v158, v155, v158
	v_fma_f32 v158, v88, v158, v92
	v_and_b32_e32 v124, 0xffff0000, v124
	v_cndmask_b32_e64 v150, v158, v150, s[38:39]
	v_fmamk_f32 v60, v150, 0x3fb504f3, v60
	v_sub_f32_e32 v150, v124, v154
	v_mul_f32_e32 v150, v155, v150
	v_fma_f32 v150, v89, v150, v93
	v_cndmask_b32_e64 v124, v150, v124, s[38:39]
	v_lshlrev_b32_e32 v150, 16, v120
	v_sub_f32_e32 v158, v150, v154
	v_mul_f32_e32 v158, v155, v158
	v_fma_f32 v158, v72, v158, v76
	v_lshlrev_b32_e32 v151, 16, v125
	v_and_b32_e32 v120, 0xffff0000, v120
	v_cndmask_b32_e64 v150, v158, v150, s[38:39]
	v_fmamk_f32 v61, v124, 0x3fb504f3, v61
	v_sub_f32_e32 v124, v151, v154
	v_fmamk_f32 v52, v150, 0x3fb504f3, v52
	v_sub_f32_e32 v150, v120, v154
	v_mul_f32_e32 v124, v155, v124
	v_mul_f32_e32 v150, v155, v150
	v_fma_f32 v124, v90, v124, v94
	v_fma_f32 v150, v73, v150, v77
	v_and_b32_e32 v125, 0xffff0000, v125
	v_cndmask_b32_e64 v124, v124, v151, s[38:39]
	v_lshlrev_b32_e32 v151, 16, v121
	v_cndmask_b32_e64 v120, v150, v120, s[38:39]
	v_fmamk_f32 v62, v124, 0x3fb504f3, v62
	v_sub_f32_e32 v124, v125, v154
	v_fmamk_f32 v53, v120, 0x3fb504f3, v53
	v_sub_f32_e32 v120, v151, v154
	v_mul_f32_e32 v124, v155, v124
	v_mul_f32_e32 v120, v155, v120
	v_fma_f32 v124, v91, v124, v95
	v_fma_f32 v120, v74, v120, v78
	v_lshlrev_b32_e32 v156, 16, v126
	v_cndmask_b32_e64 v124, v124, v125, s[38:39]
	v_and_b32_e32 v121, 0xffff0000, v121
	v_cndmask_b32_e64 v120, v120, v151, s[38:39]
	v_fmac_f32_e32 v63, 0x3fb504f3, v124
	v_sub_f32_e32 v124, v156, v154
	v_fmamk_f32 v120, v120, 0x3fb504f3, v54
	v_sub_f32_e32 v54, v121, v154
	v_mul_f32_e32 v124, v155, v124
	v_mul_f32_e32 v54, v155, v54
	v_fma_f32 v124, v80, v124, v84
	v_fma_f32 v54, v75, v54, v79
	v_and_b32_e32 v126, 0xffff0000, v126
	v_cndmask_b32_e64 v124, v124, v156, s[38:39]
	v_lshlrev_b32_e32 v156, 16, v122
	v_cndmask_b32_e64 v54, v54, v121, s[38:39]
	v_fmamk_f32 v56, v124, 0x3fb504f3, v56
	v_sub_f32_e32 v124, v126, v154
	v_fmac_f32_e32 v55, 0x3fb504f3, v54
	v_sub_f32_e32 v54, v156, v154
	v_mul_f32_e32 v124, v155, v124
	v_mul_f32_e32 v54, v155, v54
	v_fma_f32 v124, v81, v124, v85
	v_fma_f32 v54, v64, v54, v68
	v_lshlrev_b32_e32 v157, 16, v127
	v_cndmask_b32_e64 v124, v124, v126, s[38:39]
	v_and_b32_e32 v122, 0xffff0000, v122
	v_cndmask_b32_e64 v54, v54, v156, s[38:39]
	v_fmamk_f32 v57, v124, 0x3fb504f3, v57
	v_sub_f32_e32 v124, v157, v154
	v_fmamk_f32 v121, v54, 0x3fb504f3, v48
	v_sub_f32_e32 v48, v122, v154
	v_mul_f32_e32 v124, v155, v124
	v_mul_f32_e32 v48, v155, v48
	v_fma_f32 v124, v82, v124, v86
	v_fma_f32 v48, v65, v48, v69
	v_cndmask_b32_e64 v124, v124, v157, s[38:39]
	v_lshlrev_b32_e32 v157, 16, v123
	v_cndmask_b32_e64 v48, v48, v122, s[38:39]
	v_fmamk_f32 v122, v48, 0x3fb504f3, v49
	v_sub_f32_e32 v48, v157, v154
	v_mul_f32_e32 v48, v155, v48
	v_fma_f32 v48, v66, v48, v70
	v_and_b32_e32 v123, 0xffff0000, v123
	v_cndmask_b32_e64 v48, v48, v157, s[38:39]
	v_fmamk_f32 v150, v48, 0x3fb504f3, v50
	v_sub_f32_e32 v48, v123, v154
	v_mul_f32_e32 v48, v155, v48
	v_fma_f32 v48, v67, v48, v71
	v_cndmask_b32_e64 v48, v48, v123, s[38:39]
	v_fmac_f32_e32 v51, 0x3fb504f3, v48
	v_mul_f32_e32 v50, v61, v61
	v_add_f32_e32 v48, 0, v60
	v_and_b32_e32 v127, 0xffff0000, v127
	v_fmac_f32_e32 v50, v60, v60
	v_add_f32_e32 v48, v61, v48
	v_fmamk_f32 v58, v124, 0x3fb504f3, v58
	v_sub_f32_e32 v124, v127, v154
	v_fmac_f32_e32 v50, v62, v62
	v_add_f32_e32 v48, v62, v48
	v_mul_f32_e32 v124, v155, v124
	v_fmac_f32_e32 v50, v63, v63
	v_add_f32_e32 v48, v63, v48
	v_fma_f32 v124, v83, v124, v87
	v_fmac_f32_e32 v50, v56, v56
	v_add_f32_e32 v48, v56, v48
	v_cndmask_b32_e64 v124, v124, v127, s[38:39]
	v_fmac_f32_e32 v50, v57, v57
	v_add_f32_e32 v48, v57, v48
	v_fmac_f32_e32 v59, 0x3fb504f3, v124
	v_fmac_f32_e32 v50, v58, v58
	v_add_f32_e32 v48, v58, v48
	v_fmac_f32_e32 v50, v59, v59
	v_add_f32_e32 v48, v59, v48
	v_fmac_f32_e32 v50, v52, v52
	v_add_f32_e32 v48, v52, v48
	v_fmac_f32_e32 v50, v53, v53
	v_add_f32_e32 v48, v53, v48
	v_fmac_f32_e32 v50, v120, v120
	v_add_f32_e32 v48, v120, v48
	v_fmac_f32_e32 v50, v55, v55
	v_add_f32_e32 v48, v55, v48
	v_fmac_f32_e32 v50, v121, v121
	v_add_f32_e32 v48, v121, v48
	v_fmac_f32_e32 v50, v122, v122
	v_add_f32_e32 v48, v122, v48
	v_fmac_f32_e32 v50, v150, v150
	v_add_f32_e32 v48, v150, v48
	v_add_f32_e32 v48, v51, v48
	v_fmac_f32_e32 v50, v51, v51
	v_cvt_pk_bf16_f32 v124, v60, v61
	v_cvt_pk_bf16_f32 v125, v62, v63
	v_cvt_pk_bf16_f32 v126, v56, v57
	ds_bpermute_b32 v49, v152, v48
	ds_bpermute_b32 v56, v152, v50
	v_lshl_add_u64 v[148:149], v[212:213], 0, v[148:149]
	v_cvt_pk_bf16_f32 v127, v58, v59
	global_store_dwordx4 v[148:149], v[124:127], off sc1
	s_waitcnt lgkmcnt(1)
	v_add_f32_e32 v48, v48, v49
	s_waitcnt lgkmcnt(0)
	v_add_f32_e32 v50, v50, v56
	v_cvt_pk_bf16_f32 v54, v52, v53
	ds_bpermute_b32 v49, v153, v48
	ds_bpermute_b32 v52, v153, v50
	v_cvt_pk_bf16_f32 v55, v120, v55
	v_cvt_pk_bf16_f32 v56, v121, v122
	v_cvt_pk_bf16_f32 v57, v150, v51
	global_store_dwordx4 v[148:149], v[54:57], off offset:256 sc1
	s_and_saveexec_b64 s[2:3], s[40:41]
	s_cbranch_execz .LBB0_1005
	s_waitcnt lgkmcnt(1)
	v_add_f32_e32 v51, v48, v49
	v_lshl_add_u64 v[48:49], v[146:147], 3, s[54:55]
	s_waitcnt lgkmcnt(0)
	v_add_f32_e32 v50, v50, v52
	global_atomic_add_f32 v[48:49], v51, off
	global_atomic_add_f32 v[48:49], v50, off offset:4

.LBB0_1008:
	s_waitcnt lgkmcnt(1)
	v_lshlrev_b32_e32 v49, 16, v116
	v_sub_f32_e32 v59, v49, v142
	v_mul_f32_e32 v59, v48, v59
	v_fma_f32 v59, v88, v59, v92
	v_and_b32_e32 v50, 0xffff0000, v116
	v_cndmask_b32_e64 v49, v59, v49, s[38:39]
	v_fmamk_f32 v44, v49, 0x3fb504f3, v44
	v_sub_f32_e32 v49, v50, v142
	v_mul_f32_e32 v49, v48, v49
	v_fma_f32 v49, v89, v49, v93
	v_lshlrev_b32_e32 v51, 16, v117
	v_cndmask_b32_e64 v49, v49, v50, s[38:39]
	v_fmamk_f32 v45, v49, 0x3fb504f3, v45
	v_sub_f32_e32 v49, v51, v142
	v_mul_f32_e32 v49, v48, v49
	v_fma_f32 v49, v90, v49, v94
	s_waitcnt lgkmcnt(0)
	v_and_b32_e32 v52, 0xffff0000, v117
	v_cndmask_b32_e64 v49, v49, v51, s[38:39]
	v_fmamk_f32 v46, v49, 0x3fb504f3, v46
	v_sub_f32_e32 v49, v52, v142
	v_mul_f32_e32 v49, v48, v49
	v_fma_f32 v49, v91, v49, v95
	v_lshlrev_b32_e32 v53, 16, v118
	v_cndmask_b32_e64 v49, v49, v52, s[38:39]
	v_fmac_f32_e32 v47, 0x3fb504f3, v49
	v_sub_f32_e32 v49, v53, v142
	v_mul_f32_e32 v49, v48, v49
	v_fma_f32 v49, v80, v49, v84
	v_and_b32_e32 v56, 0xffff0000, v118
	v_cndmask_b32_e64 v49, v49, v53, s[38:39]
	v_fmamk_f32 v40, v49, 0x3fb504f3, v40
	v_sub_f32_e32 v49, v56, v142
	v_mul_f32_e32 v49, v48, v49
	v_fma_f32 v49, v81, v49, v85
	v_lshlrev_b32_e32 v57, 16, v119
	v_cndmask_b32_e64 v49, v49, v56, s[38:39]
	v_fmamk_f32 v41, v49, 0x3fb504f3, v41
	v_sub_f32_e32 v49, v57, v142
	v_mul_f32_e32 v49, v48, v49
	v_fma_f32 v49, v82, v49, v86
	v_and_b32_e32 v58, 0xffff0000, v119
	v_cndmask_b32_e64 v49, v49, v57, s[38:39]
	v_fmamk_f32 v42, v49, 0x3fb504f3, v42
	v_sub_f32_e32 v49, v58, v142
	v_mul_f32_e32 v49, v48, v49
	v_fma_f32 v49, v83, v49, v87
	v_cndmask_b32_e64 v49, v49, v58, s[38:39]
	v_fmac_f32_e32 v43, 0x3fb504f3, v49
	v_lshlrev_b32_e32 v49, 16, v112
	v_sub_f32_e32 v63, v49, v142
	v_mul_f32_e32 v63, v48, v63
	v_fma_f32 v63, v72, v63, v76
	v_and_b32_e32 v56, 0xffff0000, v112
	v_cndmask_b32_e64 v49, v63, v49, s[38:39]
	v_fmamk_f32 v36, v49, 0x3fb504f3, v36
	v_sub_f32_e32 v49, v56, v142
	v_mul_f32_e32 v49, v48, v49
	v_fma_f32 v49, v73, v49, v77
	v_lshlrev_b32_e32 v57, 16, v113
	v_cndmask_b32_e64 v49, v49, v56, s[38:39]
	v_fmamk_f32 v37, v49, 0x3fb504f3, v37
	v_sub_f32_e32 v49, v57, v142
	v_mul_f32_e32 v49, v48, v49
	v_fma_f32 v49, v74, v49, v78
	v_and_b32_e32 v58, 0xffff0000, v113
	v_cndmask_b32_e64 v49, v49, v57, s[38:39]
	v_fmamk_f32 v49, v49, 0x3fb504f3, v38
	v_sub_f32_e32 v38, v58, v142
	v_mul_f32_e32 v38, v48, v38
	v_fma_f32 v38, v75, v38, v79
	v_lshlrev_b32_e32 v59, 16, v114
	v_cndmask_b32_e64 v38, v38, v58, s[38:39]
	v_fmac_f32_e32 v39, 0x3fb504f3, v38
	v_sub_f32_e32 v38, v59, v142
	v_mul_f32_e32 v38, v48, v38
	v_fma_f32 v38, v64, v38, v68
	v_and_b32_e32 v60, 0xffff0000, v114
	v_cndmask_b32_e64 v38, v38, v59, s[38:39]
	v_fmamk_f32 v56, v38, 0x3fb504f3, v32
	v_sub_f32_e32 v32, v60, v142
	v_mul_f32_e32 v32, v48, v32
	v_fma_f32 v32, v65, v32, v69
	v_lshlrev_b32_e32 v61, 16, v115
	v_cndmask_b32_e64 v32, v32, v60, s[38:39]
	v_fmamk_f32 v57, v32, 0x3fb504f3, v33
	v_sub_f32_e32 v32, v61, v142
	v_mul_f32_e32 v32, v48, v32
	v_fma_f32 v32, v66, v32, v70
	v_and_b32_e32 v62, 0xffff0000, v115
	v_cndmask_b32_e64 v32, v32, v61, s[38:39]
	v_fmamk_f32 v58, v32, 0x3fb504f3, v34
	v_sub_f32_e32 v32, v62, v142
	v_mul_f32_e32 v32, v48, v32
	v_fma_f32 v32, v67, v32, v71
	v_cndmask_b32_e64 v32, v32, v62, s[38:39]
	v_fmac_f32_e32 v35, 0x3fb504f3, v32
	v_mul_f32_e32 v34, v45, v45
	v_add_f32_e32 v32, 0, v44
	v_fmac_f32_e32 v34, v44, v44
	v_add_f32_e32 v32, v45, v32
	v_fmac_f32_e32 v34, v46, v46
	v_add_f32_e32 v32, v46, v32
	v_fmac_f32_e32 v34, v47, v47
	v_add_f32_e32 v32, v47, v32
	v_fmac_f32_e32 v34, v40, v40
	v_add_f32_e32 v32, v40, v32
	v_fmac_f32_e32 v34, v41, v41
	v_add_f32_e32 v32, v41, v32
	v_fmac_f32_e32 v34, v42, v42
	v_add_f32_e32 v32, v42, v32
	v_fmac_f32_e32 v34, v43, v43
	v_add_f32_e32 v32, v43, v32
	v_fmac_f32_e32 v34, v36, v36
	v_add_f32_e32 v32, v36, v32
	v_fmac_f32_e32 v34, v37, v37
	v_add_f32_e32 v32, v37, v32
	v_fmac_f32_e32 v34, v49, v49
	v_add_f32_e32 v32, v49, v32
	v_fmac_f32_e32 v34, v39, v39
	v_add_f32_e32 v32, v39, v32
	v_fmac_f32_e32 v34, v56, v56
	v_add_f32_e32 v32, v56, v32
	v_fmac_f32_e32 v34, v57, v57
	v_add_f32_e32 v32, v57, v32
	v_fmac_f32_e32 v34, v58, v58
	v_add_f32_e32 v32, v58, v32
	v_add_f32_e32 v32, v35, v32
	v_fmac_f32_e32 v34, v35, v35
	v_cvt_pk_bf16_f32 v50, v44, v45
	v_cvt_pk_bf16_f32 v51, v46, v47
	v_cvt_pk_bf16_f32 v52, v40, v41
	ds_bpermute_b32 v33, v152, v32
	ds_bpermute_b32 v40, v152, v34
	v_lshl_add_u64 v[54:55], v[212:213], 0, v[144:145]
	v_cvt_pk_bf16_f32 v53, v42, v43
	global_store_dwordx4 v[54:55], v[50:53], off sc1
	s_waitcnt lgkmcnt(1)
	v_add_f32_e32 v32, v32, v33
	s_waitcnt lgkmcnt(0)
	v_add_f32_e32 v34, v34, v40
	v_cvt_pk_bf16_f32 v38, v36, v37
	ds_bpermute_b32 v33, v153, v32
	ds_bpermute_b32 v36, v153, v34
	v_cvt_pk_bf16_f32 v39, v49, v39
	v_cvt_pk_bf16_f32 v40, v56, v57
	v_cvt_pk_bf16_f32 v41, v58, v35
	global_store_dwordx4 v[54:55], v[38:41], off offset:256 sc1
	s_and_saveexec_b64 s[2:3], s[40:41]
	s_cbranch_execz .LBB0_1010
	s_waitcnt lgkmcnt(1)
	v_add_f32_e32 v35, v32, v33
	v_lshl_add_u64 v[32:33], v[140:141], 3, s[54:55]
	s_waitcnt lgkmcnt(0)
	v_add_f32_e32 v34, v34, v36
	global_atomic_add_f32 v[32:33], v35, off
	global_atomic_add_f32 v[32:33], v34, off offset:4

.LBB0_1013:
	s_waitcnt lgkmcnt(1)
	v_lshlrev_b32_e32 v33, 16, v108
	v_sub_f32_e32 v43, v33, v136
	v_mul_f32_e32 v43, v32, v43
	v_fma_f32 v43, v88, v43, v92
	v_and_b32_e32 v34, 0xffff0000, v108
	v_cndmask_b32_e64 v33, v43, v33, s[38:39]
	v_fmamk_f32 v28, v33, 0x3fb504f3, v28
	v_sub_f32_e32 v33, v34, v136
	v_mul_f32_e32 v33, v32, v33
	v_fma_f32 v33, v89, v33, v93
	v_lshlrev_b32_e32 v35, 16, v109
	v_cndmask_b32_e64 v33, v33, v34, s[38:39]
	v_fmamk_f32 v29, v33, 0x3fb504f3, v29
	v_sub_f32_e32 v33, v35, v136
	v_mul_f32_e32 v33, v32, v33
	v_fma_f32 v33, v90, v33, v94
	s_waitcnt lgkmcnt(0)
	v_and_b32_e32 v36, 0xffff0000, v109
	v_cndmask_b32_e64 v33, v33, v35, s[38:39]
	v_fmamk_f32 v30, v33, 0x3fb504f3, v30
	v_sub_f32_e32 v33, v36, v136
	v_mul_f32_e32 v33, v32, v33
	v_fma_f32 v33, v91, v33, v95
	v_lshlrev_b32_e32 v37, 16, v110
	v_cndmask_b32_e64 v33, v33, v36, s[38:39]
	v_fmac_f32_e32 v31, 0x3fb504f3, v33
	v_sub_f32_e32 v33, v37, v136
	v_mul_f32_e32 v33, v32, v33
	v_fma_f32 v33, v80, v33, v84
	v_and_b32_e32 v40, 0xffff0000, v110
	v_cndmask_b32_e64 v33, v33, v37, s[38:39]
	v_fmamk_f32 v24, v33, 0x3fb504f3, v24
	v_sub_f32_e32 v33, v40, v136
	v_mul_f32_e32 v33, v32, v33
	v_fma_f32 v33, v81, v33, v85
	v_lshlrev_b32_e32 v41, 16, v111
	v_cndmask_b32_e64 v33, v33, v40, s[38:39]
	v_fmamk_f32 v25, v33, 0x3fb504f3, v25
	v_sub_f32_e32 v33, v41, v136
	v_mul_f32_e32 v33, v32, v33
	v_fma_f32 v33, v82, v33, v86
	v_and_b32_e32 v42, 0xffff0000, v111
	v_cndmask_b32_e64 v33, v33, v41, s[38:39]
	v_fmamk_f32 v26, v33, 0x3fb504f3, v26
	v_sub_f32_e32 v33, v42, v136
	v_mul_f32_e32 v33, v32, v33
	v_fma_f32 v33, v83, v33, v87
	v_cndmask_b32_e64 v33, v33, v42, s[38:39]
	v_fmac_f32_e32 v27, 0x3fb504f3, v33
	v_lshlrev_b32_e32 v33, 16, v104
	v_sub_f32_e32 v47, v33, v136
	v_mul_f32_e32 v47, v32, v47
	v_fma_f32 v47, v72, v47, v76
	v_and_b32_e32 v40, 0xffff0000, v104
	v_cndmask_b32_e64 v33, v47, v33, s[38:39]
	v_fmamk_f32 v20, v33, 0x3fb504f3, v20
	v_sub_f32_e32 v33, v40, v136
	v_mul_f32_e32 v33, v32, v33
	v_fma_f32 v33, v73, v33, v77
	v_lshlrev_b32_e32 v41, 16, v105
	v_cndmask_b32_e64 v33, v33, v40, s[38:39]
	v_fmamk_f32 v21, v33, 0x3fb504f3, v21
	v_sub_f32_e32 v33, v41, v136
	v_mul_f32_e32 v33, v32, v33
	v_fma_f32 v33, v74, v33, v78
	v_and_b32_e32 v42, 0xffff0000, v105
	v_cndmask_b32_e64 v33, v33, v41, s[38:39]
	v_fmamk_f32 v33, v33, 0x3fb504f3, v22
	v_sub_f32_e32 v22, v42, v136
	v_mul_f32_e32 v22, v32, v22
	v_fma_f32 v22, v75, v22, v79
	v_lshlrev_b32_e32 v43, 16, v106
	v_cndmask_b32_e64 v22, v22, v42, s[38:39]
	v_fmac_f32_e32 v23, 0x3fb504f3, v22
	v_sub_f32_e32 v22, v43, v136
	v_mul_f32_e32 v22, v32, v22
	v_fma_f32 v22, v64, v22, v68
	v_and_b32_e32 v44, 0xffff0000, v106
	v_cndmask_b32_e64 v22, v22, v43, s[38:39]
	v_fmamk_f32 v40, v22, 0x3fb504f3, v16
	v_sub_f32_e32 v16, v44, v136
	v_mul_f32_e32 v16, v32, v16
	v_fma_f32 v16, v65, v16, v69
	v_lshlrev_b32_e32 v45, 16, v107
	v_cndmask_b32_e64 v16, v16, v44, s[38:39]
	v_fmamk_f32 v41, v16, 0x3fb504f3, v17
	v_sub_f32_e32 v16, v45, v136
	v_mul_f32_e32 v16, v32, v16
	v_fma_f32 v16, v66, v16, v70
	v_and_b32_e32 v46, 0xffff0000, v107
	v_cndmask_b32_e64 v16, v16, v45, s[38:39]
	v_fmamk_f32 v42, v16, 0x3fb504f3, v18
	v_sub_f32_e32 v16, v46, v136
	v_mul_f32_e32 v16, v32, v16
	v_fma_f32 v16, v67, v16, v71
	v_cndmask_b32_e64 v16, v16, v46, s[38:39]
	v_fmac_f32_e32 v19, 0x3fb504f3, v16
	v_mul_f32_e32 v18, v29, v29
	v_add_f32_e32 v16, 0, v28
	v_fmac_f32_e32 v18, v28, v28
	v_add_f32_e32 v16, v29, v16
	v_fmac_f32_e32 v18, v30, v30
	v_add_f32_e32 v16, v30, v16
	v_fmac_f32_e32 v18, v31, v31
	v_add_f32_e32 v16, v31, v16
	v_fmac_f32_e32 v18, v24, v24
	v_add_f32_e32 v16, v24, v16
	v_fmac_f32_e32 v18, v25, v25
	v_add_f32_e32 v16, v25, v16
	v_fmac_f32_e32 v18, v26, v26
	v_add_f32_e32 v16, v26, v16
	v_fmac_f32_e32 v18, v27, v27
	v_add_f32_e32 v16, v27, v16
	v_fmac_f32_e32 v18, v20, v20
	v_add_f32_e32 v16, v20, v16
	v_fmac_f32_e32 v18, v21, v21
	v_add_f32_e32 v16, v21, v16
	v_fmac_f32_e32 v18, v33, v33
	v_add_f32_e32 v16, v33, v16
	v_fmac_f32_e32 v18, v23, v23
	v_add_f32_e32 v16, v23, v16
	v_fmac_f32_e32 v18, v40, v40
	v_add_f32_e32 v16, v40, v16
	v_fmac_f32_e32 v18, v41, v41
	v_add_f32_e32 v16, v41, v16
	v_fmac_f32_e32 v18, v42, v42
	v_add_f32_e32 v16, v42, v16
	v_add_f32_e32 v16, v19, v16
	v_fmac_f32_e32 v18, v19, v19
	v_cvt_pk_bf16_f32 v34, v28, v29
	v_cvt_pk_bf16_f32 v35, v30, v31
	v_cvt_pk_bf16_f32 v36, v24, v25
	ds_bpermute_b32 v17, v152, v16
	ds_bpermute_b32 v24, v152, v18
	v_lshl_add_u64 v[38:39], v[212:213], 0, v[138:139]
	v_cvt_pk_bf16_f32 v37, v26, v27
	global_store_dwordx4 v[38:39], v[34:37], off sc1
	s_waitcnt lgkmcnt(1)
	v_add_f32_e32 v16, v16, v17
	s_waitcnt lgkmcnt(0)
	v_add_f32_e32 v18, v18, v24
	v_cvt_pk_bf16_f32 v22, v20, v21
	ds_bpermute_b32 v17, v153, v16
	ds_bpermute_b32 v20, v153, v18
	v_cvt_pk_bf16_f32 v23, v33, v23
	v_cvt_pk_bf16_f32 v24, v40, v41
	v_cvt_pk_bf16_f32 v25, v42, v19
	global_store_dwordx4 v[38:39], v[22:25], off offset:256 sc1
	s_and_saveexec_b64 s[2:3], s[40:41]
	s_cbranch_execz .LBB0_1015
	s_waitcnt lgkmcnt(1)
	v_add_f32_e32 v19, v16, v17
	v_lshl_add_u64 v[16:17], v[134:135], 3, s[54:55]
	s_waitcnt lgkmcnt(0)
	v_add_f32_e32 v18, v18, v20
	global_atomic_add_f32 v[16:17], v19, off
	global_atomic_add_f32 v[16:17], v18, off offset:4

.LBB0_1018:
	s_waitcnt lgkmcnt(1)
	v_lshlrev_b32_e32 v17, 16, v100
	v_sub_f32_e32 v27, v17, v130
	v_mul_f32_e32 v27, v16, v27
	v_fmac_f32_e32 v92, v88, v27
	v_and_b32_e32 v18, 0xffff0000, v100
	v_cndmask_b32_e64 v17, v92, v17, s[38:39]
	v_fmamk_f32 v12, v17, 0x3fb504f3, v12
	v_sub_f32_e32 v17, v18, v130
	v_mul_f32_e32 v17, v16, v17
	v_fmac_f32_e32 v93, v89, v17
	v_lshlrev_b32_e32 v19, 16, v101
	v_cndmask_b32_e64 v17, v93, v18, s[38:39]
	v_fmamk_f32 v13, v17, 0x3fb504f3, v13
	v_sub_f32_e32 v17, v19, v130
	v_mul_f32_e32 v17, v16, v17
	v_fmac_f32_e32 v94, v90, v17
	s_waitcnt lgkmcnt(0)
	v_and_b32_e32 v20, 0xffff0000, v101
	v_cndmask_b32_e64 v17, v94, v19, s[38:39]
	v_fmamk_f32 v14, v17, 0x3fb504f3, v14
	v_sub_f32_e32 v17, v20, v130
	v_mul_f32_e32 v17, v16, v17
	v_fmac_f32_e32 v95, v91, v17
	v_lshlrev_b32_e32 v21, 16, v102
	v_cndmask_b32_e64 v17, v95, v20, s[38:39]
	v_fmac_f32_e32 v15, 0x3fb504f3, v17
	v_sub_f32_e32 v17, v21, v130
	v_mul_f32_e32 v17, v16, v17
	v_fmac_f32_e32 v84, v80, v17
	v_and_b32_e32 v24, 0xffff0000, v102
	v_cndmask_b32_e64 v17, v84, v21, s[38:39]
	v_fmamk_f32 v8, v17, 0x3fb504f3, v8
	v_sub_f32_e32 v17, v24, v130
	v_mul_f32_e32 v17, v16, v17
	v_fmac_f32_e32 v85, v81, v17
	v_lshlrev_b32_e32 v25, 16, v103
	v_cndmask_b32_e64 v17, v85, v24, s[38:39]
	v_fmamk_f32 v9, v17, 0x3fb504f3, v9
	v_sub_f32_e32 v17, v25, v130
	v_mul_f32_e32 v17, v16, v17
	v_fmac_f32_e32 v86, v82, v17
	v_and_b32_e32 v26, 0xffff0000, v103
	v_cndmask_b32_e64 v17, v86, v25, s[38:39]
	v_fmamk_f32 v10, v17, 0x3fb504f3, v10
	v_sub_f32_e32 v17, v26, v130
	v_mul_f32_e32 v17, v16, v17
	v_fmac_f32_e32 v87, v83, v17
	v_cndmask_b32_e64 v17, v87, v26, s[38:39]
	v_fmac_f32_e32 v11, 0x3fb504f3, v17
	v_lshlrev_b32_e32 v17, 16, v96
	v_sub_f32_e32 v31, v17, v130
	v_mul_f32_e32 v31, v16, v31
	v_fmac_f32_e32 v76, v72, v31
	v_and_b32_e32 v24, 0xffff0000, v96
	v_cndmask_b32_e64 v17, v76, v17, s[38:39]
	v_fmamk_f32 v4, v17, 0x3fb504f3, v4
	v_sub_f32_e32 v17, v24, v130
	v_mul_f32_e32 v17, v16, v17
	v_fmac_f32_e32 v77, v73, v17
	v_lshlrev_b32_e32 v25, 16, v97
	v_cndmask_b32_e64 v17, v77, v24, s[38:39]
	v_fmamk_f32 v5, v17, 0x3fb504f3, v5
	v_sub_f32_e32 v17, v25, v130
	v_mul_f32_e32 v17, v16, v17
	v_fmac_f32_e32 v78, v74, v17
	v_and_b32_e32 v26, 0xffff0000, v97
	v_cndmask_b32_e64 v17, v78, v25, s[38:39]
	v_fmamk_f32 v17, v17, 0x3fb504f3, v6
	v_sub_f32_e32 v6, v26, v130
	v_mul_f32_e32 v6, v16, v6
	v_fmac_f32_e32 v79, v75, v6
	v_lshlrev_b32_e32 v27, 16, v98
	v_cndmask_b32_e64 v6, v79, v26, s[38:39]
	v_fmac_f32_e32 v7, 0x3fb504f3, v6
	v_sub_f32_e32 v6, v27, v130
	v_mul_f32_e32 v6, v16, v6
	v_fmac_f32_e32 v68, v64, v6
	v_and_b32_e32 v28, 0xffff0000, v98
	v_cndmask_b32_e64 v6, v68, v27, s[38:39]
	v_fmamk_f32 v24, v6, 0x3fb504f3, v0
	v_sub_f32_e32 v0, v28, v130
	v_mul_f32_e32 v0, v16, v0
	v_fmac_f32_e32 v69, v65, v0
	v_lshlrev_b32_e32 v29, 16, v99
	v_cndmask_b32_e64 v0, v69, v28, s[38:39]
	v_fmamk_f32 v25, v0, 0x3fb504f3, v1
	v_sub_f32_e32 v0, v29, v130
	v_mul_f32_e32 v0, v16, v0
	v_fmac_f32_e32 v70, v66, v0
	v_and_b32_e32 v30, 0xffff0000, v99
	v_cndmask_b32_e64 v0, v70, v29, s[38:39]
	v_fmamk_f32 v26, v0, 0x3fb504f3, v2
	v_sub_f32_e32 v0, v30, v130
	v_mul_f32_e32 v0, v16, v0
	v_fmac_f32_e32 v71, v67, v0
	v_cndmask_b32_e64 v0, v71, v30, s[38:39]
	v_fmac_f32_e32 v3, 0x3fb504f3, v0
	v_mul_f32_e32 v2, v13, v13
	v_add_f32_e32 v0, 0, v12
	v_fmac_f32_e32 v2, v12, v12
	v_add_f32_e32 v0, v13, v0
	v_fmac_f32_e32 v2, v14, v14
	v_add_f32_e32 v0, v14, v0
	v_fmac_f32_e32 v2, v15, v15
	v_add_f32_e32 v0, v15, v0
	v_fmac_f32_e32 v2, v8, v8
	v_add_f32_e32 v0, v8, v0
	v_fmac_f32_e32 v2, v9, v9
	v_add_f32_e32 v0, v9, v0
	v_fmac_f32_e32 v2, v10, v10
	v_add_f32_e32 v0, v10, v0
	v_fmac_f32_e32 v2, v11, v11
	v_add_f32_e32 v0, v11, v0
	v_fmac_f32_e32 v2, v4, v4
	v_add_f32_e32 v0, v4, v0
	v_fmac_f32_e32 v2, v5, v5
	v_add_f32_e32 v0, v5, v0
	v_fmac_f32_e32 v2, v17, v17
	v_add_f32_e32 v0, v17, v0
	v_fmac_f32_e32 v2, v7, v7
	v_add_f32_e32 v0, v7, v0
	v_fmac_f32_e32 v2, v24, v24
	v_add_f32_e32 v0, v24, v0
	v_fmac_f32_e32 v2, v25, v25
	v_add_f32_e32 v0, v25, v0
	v_fmac_f32_e32 v2, v26, v26
	v_add_f32_e32 v0, v26, v0
	v_add_f32_e32 v0, v3, v0
	v_fmac_f32_e32 v2, v3, v3
	v_cvt_pk_bf16_f32 v18, v12, v13
	v_cvt_pk_bf16_f32 v19, v14, v15
	v_cvt_pk_bf16_f32 v20, v8, v9
	ds_bpermute_b32 v1, v152, v0
	ds_bpermute_b32 v8, v152, v2
	v_lshl_add_u64 v[22:23], v[212:213], 0, v[132:133]
	v_cvt_pk_bf16_f32 v21, v10, v11
	global_store_dwordx4 v[22:23], v[18:21], off sc1
	s_waitcnt lgkmcnt(1)
	v_add_f32_e32 v0, v0, v1
	s_waitcnt lgkmcnt(0)
	v_add_f32_e32 v2, v2, v8
	v_cvt_pk_bf16_f32 v6, v4, v5
	ds_bpermute_b32 v1, v153, v0
	ds_bpermute_b32 v4, v153, v2
	v_cvt_pk_bf16_f32 v7, v17, v7
	v_cvt_pk_bf16_f32 v8, v24, v25
	v_cvt_pk_bf16_f32 v9, v26, v3
	global_store_dwordx4 v[22:23], v[6:9], off offset:256 sc1
	s_and_saveexec_b64 s[2:3], s[40:41]
	s_cbranch_execz .LBB0_966
	s_waitcnt lgkmcnt(1)
	v_add_f32_e32 v3, v0, v1
	v_lshl_add_u64 v[0:1], v[128:129], 3, s[54:55]
	s_waitcnt lgkmcnt(0)
	v_add_f32_e32 v2, v2, v4
	global_atomic_add_f32 v[0:1], v3, off
	global_atomic_add_f32 v[0:1], v2, off offset:4
	s_branch .LBB0_966

.LBB0_1168:
	s_add_u32 s2, s42, 0xffe00080
	s_addc_u32 s3, s43, -1
	s_add_i32 s87, 0, 0x10000
	v_add_u32_e32 v76, s87, v235
	ds_read_b128 v[64:67], v76
	ds_read_b128 v[68:71], v76 offset:1024
	ds_read_b128 v[72:75], v76 offset:2048
	ds_read_b128 v[76:79], v76 offset:3072
	s_cmpk_eq_i32 s86, 0x7c
	s_cselect_b32 s21, s18, s3
	s_cselect_b32 s20, s19, s2
	s_cselect_b32 s3, s34, s61
	s_cselect_b32 s2, s35, s59
	v_lshl_add_u64 v[176:177], s[42:43], 0, v[204:205]
	s_add_i32 m0, s16, 0xc000
	ds_read_b128 v[80:83], v237
	ds_read_b128 v[84:87], v237 offset:1024
	ds_read_b128 v[88:91], v237 offset:2048
	ds_read_b128 v[92:95], v237 offset:3072
	ds_read_b128 v[160:163], v237 offset:4096
	ds_read_b128 v[164:167], v237 offset:5120
	ds_read_b128 v[168:171], v237 offset:6144
	ds_read_b128 v[172:175], v237 offset:7168
	global_load_lds_dwordx4 v[176:177], off
	v_lshl_add_u64 v[176:177], s[42:43], 0, v[206:207]
	s_add_i32 m0, s16, 0xe000
	s_nop 0
	global_load_lds_dwordx4 v[176:177], off
	s_waitcnt lgkmcnt(8)
	s_barrier
	s_waitcnt lgkmcnt(0)
	s_setprio 1
	s_waitcnt lgkmcnt(0)
	v_mfma_f32_16x16x32_bf16 v[156:159], v[64:67], v[80:83], v[156:159]
	v_mfma_f32_16x16x32_bf16 v[152:155], v[72:75], v[80:83], v[152:155]
	v_mfma_f32_16x16x32_bf16 v[140:143], v[64:67], v[88:91], v[140:143]
	v_mfma_f32_16x16x32_bf16 v[136:139], v[72:75], v[88:91], v[136:139]
	v_mfma_f32_16x16x32_bf16 v[124:127], v[64:67], v[160:163], v[124:127]
	v_mfma_f32_16x16x32_bf16 v[120:123], v[72:75], v[160:163], v[120:123]
	v_mfma_f32_16x16x32_bf16 v[108:111], v[64:67], v[168:171], v[108:111]
	v_mfma_f32_16x16x32_bf16 v[104:107], v[72:75], v[168:171], v[104:107]
	v_mfma_f32_16x16x32_bf16 v[156:159], v[68:71], v[84:87], v[156:159]
	v_mfma_f32_16x16x32_bf16 v[152:155], v[76:79], v[84:87], v[152:155]
	v_mfma_f32_16x16x32_bf16 v[140:143], v[68:71], v[92:95], v[140:143]
	v_mfma_f32_16x16x32_bf16 v[136:139], v[76:79], v[92:95], v[136:139]
	v_mfma_f32_16x16x32_bf16 v[124:127], v[68:71], v[164:167], v[124:127]
	v_mfma_f32_16x16x32_bf16 v[120:123], v[76:79], v[164:167], v[120:123]
	v_mfma_f32_16x16x32_bf16 v[108:111], v[68:71], v[172:175], v[108:111]
	v_mfma_f32_16x16x32_bf16 v[104:107], v[76:79], v[172:175], v[104:107]
	s_setprio 0
	s_barrier
	s_add_i32 s90, 0, 0x14000
	s_add_i32 s87, s87, s11
	v_add_u32_e32 v208, s90, v235
	v_lshl_add_u64 v[220:221], s[2:3], 0, v[194:195]
	s_mov_b32 m0, s87
	ds_read_b128 v[176:179], v208
	ds_read_b128 v[180:183], v208 offset:1024
	ds_read_b128 v[184:187], v208 offset:2048
	ds_read_b128 v[208:211], v208 offset:3072
	global_load_lds_dwordx4 v[220:221], off
	v_lshl_add_u64 v[222:223], s[2:3], 0, v[202:203]
	s_add_i32 m0, s87, 0x2000
	s_nop 0
	global_load_lds_dwordx4 v[222:223], off
	s_barrier
	s_waitcnt lgkmcnt(0)
	s_setprio 1
	s_waitcnt lgkmcnt(0)
	v_mfma_f32_16x16x32_bf16 v[148:151], v[176:179], v[80:83], v[148:151]
	v_mfma_f32_16x16x32_bf16 v[80:83], v[184:187], v[80:83], v[144:147]
	v_mfma_f32_16x16x32_bf16 v[148:151], v[180:183], v[84:87], v[148:151]
	v_mfma_f32_16x16x32_bf16 v[80:83], v[208:211], v[84:87], v[80:83]
	v_mfma_f32_16x16x32_bf16 v[84:87], v[176:179], v[88:91], v[132:135]
	v_mfma_f32_16x16x32_bf16 v[88:91], v[184:187], v[88:91], v[128:131]
	v_mfma_f32_16x16x32_bf16 v[112:115], v[184:187], v[160:163], v[112:115]
	v_mfma_f32_16x16x32_bf16 v[100:103], v[176:179], v[168:171], v[100:103]
	v_mfma_f32_16x16x32_bf16 v[96:99], v[184:187], v[168:171], v[96:99]
	v_mfma_f32_16x16x32_bf16 v[84:87], v[180:183], v[92:95], v[84:87]
	v_mfma_f32_16x16x32_bf16 v[88:91], v[208:211], v[92:95], v[88:91]
	v_mfma_f32_16x16x32_bf16 v[92:95], v[176:179], v[160:163], v[116:119]
	v_mfma_f32_16x16x32_bf16 v[112:115], v[208:211], v[164:167], v[112:115]
	v_mfma_f32_16x16x32_bf16 v[100:103], v[180:183], v[172:175], v[100:103]
	v_mfma_f32_16x16x32_bf16 v[96:99], v[208:211], v[172:175], v[96:99]
	v_mfma_f32_16x16x32_bf16 v[92:95], v[180:183], v[164:167], v[92:95]
	s_setprio 0
	s_mov_b32 m0, s16
	v_lshl_add_u64 v[224:225], s[20:21], 0, v[188:189]
	s_barrier
	ds_read_b128 v[116:119], v237 offset:16384
	ds_read_b128 v[128:131], v237 offset:17408
	ds_read_b128 v[132:135], v237 offset:18432
	ds_read_b128 v[144:147], v237 offset:19456
	ds_read_b128 v[160:163], v237 offset:20480
	ds_read_b128 v[164:167], v237 offset:21504
	ds_read_b128 v[168:171], v237 offset:22528
	ds_read_b128 v[172:175], v237 offset:23552
	global_load_lds_dwordx4 v[224:225], off
	v_lshl_add_u64 v[226:227], s[20:21], 0, v[190:191]
	s_mov_b32 m0, s53
	s_nop 0
	global_load_lds_dwordx4 v[226:227], off
	s_barrier
	s_waitcnt lgkmcnt(0)
	s_setprio 1
	s_waitcnt lgkmcnt(0)
	v_mfma_f32_16x16x32_bf16 v[60:63], v[64:67], v[116:119], v[60:63]
	v_mfma_f32_16x16x32_bf16 v[56:59], v[72:75], v[116:119], v[56:59]
	v_mfma_f32_16x16x32_bf16 v[44:47], v[64:67], v[132:135], v[44:47]
	v_mfma_f32_16x16x32_bf16 v[40:43], v[72:75], v[132:135], v[40:43]
	v_mfma_f32_16x16x32_bf16 v[28:31], v[64:67], v[160:163], v[28:31]
	v_mfma_f32_16x16x32_bf16 v[24:27], v[72:75], v[160:163], v[24:27]
	v_mfma_f32_16x16x32_bf16 v[12:15], v[64:67], v[168:171], v[12:15]
	v_mfma_f32_16x16x32_bf16 v[8:11], v[72:75], v[168:171], v[8:11]
	v_mfma_f32_16x16x32_bf16 v[60:63], v[68:71], v[128:131], v[60:63]
	v_mfma_f32_16x16x32_bf16 v[56:59], v[76:79], v[128:131], v[56:59]
	v_mfma_f32_16x16x32_bf16 v[44:47], v[68:71], v[144:147], v[44:47]
	v_mfma_f32_16x16x32_bf16 v[40:43], v[76:79], v[144:147], v[40:43]
	v_mfma_f32_16x16x32_bf16 v[28:31], v[68:71], v[164:167], v[28:31]
	v_mfma_f32_16x16x32_bf16 v[24:27], v[76:79], v[164:167], v[24:27]
	v_mfma_f32_16x16x32_bf16 v[12:15], v[68:71], v[172:175], v[12:15]
	v_mfma_f32_16x16x32_bf16 v[8:11], v[76:79], v[172:175], v[8:11]
	s_setprio 0
	s_barrier
	s_add_u32 s88, s2, 0x200000
	s_addc_u32 s89, s3, 0
	s_add_i32 s87, s90, s11
	v_lshl_add_u64 v[64:65], s[88:89], 0, v[194:195]
	s_mov_b32 m0, s87
	s_nop 0
	global_load_lds_dwordx4 v[64:65], off
	v_lshl_add_u64 v[64:65], s[88:89], 0, v[202:203]
	s_add_i32 m0, s87, 0x2000
	s_nop 0
	global_load_lds_dwordx4 v[64:65], off
	s_waitcnt vmcnt(6)
	s_barrier
	s_setprio 1
	v_mfma_f32_16x16x32_bf16 v[52:55], v[176:179], v[116:119], v[52:55]
	v_mfma_f32_16x16x32_bf16 v[48:51], v[184:187], v[116:119], v[48:51]
	v_mfma_f32_16x16x32_bf16 v[36:39], v[176:179], v[132:135], v[36:39]
	v_mfma_f32_16x16x32_bf16 v[32:35], v[184:187], v[132:135], v[32:35]
	v_mfma_f32_16x16x32_bf16 v[20:23], v[176:179], v[160:163], v[20:23]
	v_mfma_f32_16x16x32_bf16 v[16:19], v[184:187], v[160:163], v[16:19]
	v_mfma_f32_16x16x32_bf16 v[4:7], v[176:179], v[168:171], v[4:7]
	v_mfma_f32_16x16x32_bf16 v[0:3], v[184:187], v[168:171], v[0:3]
	v_mfma_f32_16x16x32_bf16 v[52:55], v[180:183], v[128:131], v[52:55]
	v_mfma_f32_16x16x32_bf16 v[48:51], v[208:211], v[128:131], v[48:51]
	v_mfma_f32_16x16x32_bf16 v[36:39], v[180:183], v[144:147], v[36:39]
	v_mfma_f32_16x16x32_bf16 v[32:35], v[208:211], v[144:147], v[32:35]
	v_mfma_f32_16x16x32_bf16 v[20:23], v[180:183], v[164:167], v[20:23]
	v_mfma_f32_16x16x32_bf16 v[16:19], v[208:211], v[164:167], v[16:19]
	v_mfma_f32_16x16x32_bf16 v[4:7], v[180:183], v[172:175], v[4:7]
	v_mfma_f32_16x16x32_bf16 v[0:3], v[208:211], v[172:175], v[0:3]
	s_setprio 0
	s_add_i32 s87, 0, 0x18000
	v_add_u32_e32 v76, s87, v235
	s_barrier
	ds_read_b128 v[64:67], v76
	ds_read_b128 v[68:71], v76 offset:1024
	ds_read_b128 v[72:75], v76 offset:2048
	ds_read_b128 v[76:79], v76 offset:3072
	s_add_u32 s20, s20, 0x200000
	s_addc_u32 s21, s21, 0
	s_mov_b32 m0, s67
	v_lshl_add_u64 v[132:133], s[20:21], 0, v[188:189]
	ds_read_b128 v[116:119], v237 offset:32768
	ds_read_b128 v[128:131], v237 offset:33792
	ds_read_b128 v[160:163], v237 offset:34816
	ds_read_b128 v[164:167], v237 offset:35840
	ds_read_b128 v[168:171], v237 offset:36864
	ds_read_b128 v[172:175], v237 offset:37888
	ds_read_b128 v[176:179], v237 offset:38912
	ds_read_b128 v[180:183], v237 offset:39936
	global_load_lds_dwordx4 v[132:133], off
	v_lshl_add_u64 v[132:133], s[20:21], 0, v[190:191]
	s_mov_b32 m0, s68
	s_nop 0
	global_load_lds_dwordx4 v[132:133], off
	s_waitcnt lgkmcnt(8)
	s_barrier
	s_waitcnt lgkmcnt(0)
	s_setprio 1
	s_waitcnt lgkmcnt(0)
	v_mfma_f32_16x16x32_bf16 v[132:135], v[64:67], v[116:119], v[156:159]
	v_mfma_f32_16x16x32_bf16 v[156:159], v[68:71], v[128:131], v[132:135]
	v_mfma_f32_16x16x32_bf16 v[132:135], v[72:75], v[116:119], v[152:155]
	v_mfma_f32_16x16x32_bf16 v[152:155], v[76:79], v[128:131], v[132:135]
	v_mfma_f32_16x16x32_bf16 v[132:135], v[64:67], v[160:163], v[140:143]
	v_mfma_f32_16x16x32_bf16 v[140:143], v[68:71], v[164:167], v[132:135]
	v_mfma_f32_16x16x32_bf16 v[132:135], v[72:75], v[160:163], v[136:139]
	v_mfma_f32_16x16x32_bf16 v[124:127], v[64:67], v[168:171], v[124:127]
	v_mfma_f32_16x16x32_bf16 v[120:123], v[72:75], v[168:171], v[120:123]
	v_mfma_f32_16x16x32_bf16 v[108:111], v[64:67], v[176:179], v[108:111]
	v_mfma_f32_16x16x32_bf16 v[104:107], v[72:75], v[176:179], v[104:107]
	v_mfma_f32_16x16x32_bf16 v[136:139], v[76:79], v[164:167], v[132:135]
	v_mfma_f32_16x16x32_bf16 v[124:127], v[68:71], v[172:175], v[124:127]
	v_mfma_f32_16x16x32_bf16 v[120:123], v[76:79], v[172:175], v[120:123]
	v_mfma_f32_16x16x32_bf16 v[108:111], v[68:71], v[180:183], v[108:111]
	v_mfma_f32_16x16x32_bf16 v[104:107], v[76:79], v[180:183], v[104:107]
	s_setprio 0
	s_barrier
	s_add_i32 s20, 0, 0x1c000
	v_add_u32_e32 v132, s20, v235
	s_add_i32 s21, s87, s11
	ds_read_b128 v[184:187], v132
	ds_read_b128 v[208:211], v132 offset:1024
	ds_read_b128 v[212:215], v132 offset:2048
	ds_read_b128 v[216:219], v132 offset:3072
	v_lshl_add_u64 v[132:133], v[220:221], 0, s[26:27]
	s_mov_b32 m0, s21
	s_nop 0
	global_load_lds_dwordx4 v[132:133], off
	v_lshl_add_u64 v[132:133], v[222:223], 0, s[26:27]
	s_add_i32 m0, s21, 0x2000
	s_nop 0
	global_load_lds_dwordx4 v[132:133], off
	s_barrier
	s_waitcnt lgkmcnt(0)
	s_setprio 1
	s_waitcnt lgkmcnt(0)
	v_mfma_f32_16x16x32_bf16 v[80:83], v[212:215], v[116:119], v[80:83]
	v_mfma_f32_16x16x32_bf16 v[132:135], v[184:187], v[116:119], v[148:151]
	v_mfma_f32_16x16x32_bf16 v[144:147], v[216:219], v[128:131], v[80:83]
	v_mfma_f32_16x16x32_bf16 v[80:83], v[184:187], v[160:163], v[84:87]
	v_mfma_f32_16x16x32_bf16 v[148:151], v[208:211], v[128:131], v[132:135]
	v_mfma_f32_16x16x32_bf16 v[132:135], v[208:211], v[164:167], v[80:83]
	v_mfma_f32_16x16x32_bf16 v[80:83], v[212:215], v[160:163], v[88:91]
	v_mfma_f32_16x16x32_bf16 v[128:131], v[216:219], v[164:167], v[80:83]
	v_mfma_f32_16x16x32_bf16 v[80:83], v[184:187], v[168:171], v[92:95]
	v_mfma_f32_16x16x32_bf16 v[116:119], v[208:211], v[172:175], v[80:83]
	v_mfma_f32_16x16x32_bf16 v[80:83], v[212:215], v[168:171], v[112:115]
	v_mfma_f32_16x16x32_bf16 v[112:115], v[216:219], v[172:175], v[80:83]
	v_mfma_f32_16x16x32_bf16 v[80:83], v[184:187], v[176:179], v[100:103]
	v_mfma_f32_16x16x32_bf16 v[100:103], v[208:211], v[180:183], v[80:83]
	v_mfma_f32_16x16x32_bf16 v[80:83], v[212:215], v[176:179], v[96:99]
	v_mfma_f32_16x16x32_bf16 v[96:99], v[216:219], v[180:183], v[80:83]
	s_setprio 0
	s_mov_b32 m0, s22
	v_lshl_add_u64 v[176:177], v[224:225], 0, s[26:27]
	s_barrier
	s_nop 2
	ds_read_b128 v[80:83], v237 offset:49152
	ds_read_b128 v[84:87], v237 offset:50176
	ds_read_b128 v[88:91], v237 offset:51200
	ds_read_b128 v[92:95], v237 offset:52224
	ds_read_b128 v[160:163], v237 offset:53248
	ds_read_b128 v[164:167], v237 offset:54272
	ds_read_b128 v[168:171], v237 offset:55296
	ds_read_b128 v[172:175], v237 offset:56320
	global_load_lds_dwordx4 v[176:177], off
	v_lshl_add_u64 v[176:177], v[226:227], 0, s[26:27]
	s_mov_b32 m0, s71
	s_nop 0
	global_load_lds_dwordx4 v[176:177], off
	s_barrier
	s_waitcnt lgkmcnt(0)
	s_setprio 1
	s_waitcnt lgkmcnt(0)
	v_mfma_f32_16x16x32_bf16 v[60:63], v[64:67], v[80:83], v[60:63]
	v_mfma_f32_16x16x32_bf16 v[56:59], v[72:75], v[80:83], v[56:59]
	v_mfma_f32_16x16x32_bf16 v[44:47], v[64:67], v[88:91], v[44:47]
	v_mfma_f32_16x16x32_bf16 v[40:43], v[72:75], v[88:91], v[40:43]
	v_mfma_f32_16x16x32_bf16 v[28:31], v[64:67], v[160:163], v[28:31]
	v_mfma_f32_16x16x32_bf16 v[24:27], v[72:75], v[160:163], v[24:27]
	v_mfma_f32_16x16x32_bf16 v[12:15], v[64:67], v[168:171], v[12:15]
	v_mfma_f32_16x16x32_bf16 v[8:11], v[72:75], v[168:171], v[8:11]
	v_mfma_f32_16x16x32_bf16 v[60:63], v[68:71], v[84:87], v[60:63]
	v_mfma_f32_16x16x32_bf16 v[56:59], v[76:79], v[84:87], v[56:59]
	v_mfma_f32_16x16x32_bf16 v[44:47], v[68:71], v[92:95], v[44:47]
	v_mfma_f32_16x16x32_bf16 v[40:43], v[76:79], v[92:95], v[40:43]
	v_mfma_f32_16x16x32_bf16 v[28:31], v[68:71], v[164:167], v[28:31]
	v_mfma_f32_16x16x32_bf16 v[24:27], v[76:79], v[164:167], v[24:27]
	v_mfma_f32_16x16x32_bf16 v[12:15], v[68:71], v[172:175], v[12:15]
	v_mfma_f32_16x16x32_bf16 v[8:11], v[76:79], v[172:175], v[8:11]
	s_setprio 0
	s_barrier
	s_add_u32 s2, s2, 0x200080
	s_addc_u32 s3, s3, 0
	s_add_i32 s20, s20, s11
	v_lshl_add_u64 v[64:65], s[2:3], 0, v[194:195]
	s_mov_b32 m0, s20
	s_nop 0
	global_load_lds_dwordx4 v[64:65], off
	v_lshl_add_u64 v[64:65], s[2:3], 0, v[202:203]
	s_add_i32 m0, s20, 0x2000
	s_nop 0
	global_load_lds_dwordx4 v[64:65], off
	s_waitcnt vmcnt(6)
	s_barrier
	s_setprio 1
	v_mfma_f32_16x16x32_bf16 v[52:55], v[184:187], v[80:83], v[52:55]
	v_mfma_f32_16x16x32_bf16 v[48:51], v[212:215], v[80:83], v[48:51]
	v_mfma_f32_16x16x32_bf16 v[36:39], v[184:187], v[88:91], v[36:39]
	v_mfma_f32_16x16x32_bf16 v[32:35], v[212:215], v[88:91], v[32:35]
	v_mfma_f32_16x16x32_bf16 v[20:23], v[184:187], v[160:163], v[20:23]
	v_mfma_f32_16x16x32_bf16 v[16:19], v[212:215], v[160:163], v[16:19]
	v_mfma_f32_16x16x32_bf16 v[4:7], v[184:187], v[168:171], v[4:7]
	v_mfma_f32_16x16x32_bf16 v[0:3], v[212:215], v[168:171], v[0:3]
	v_mfma_f32_16x16x32_bf16 v[52:55], v[208:211], v[84:87], v[52:55]
	v_mfma_f32_16x16x32_bf16 v[48:51], v[216:219], v[84:87], v[48:51]
	v_mfma_f32_16x16x32_bf16 v[36:39], v[208:211], v[92:95], v[36:39]
	v_mfma_f32_16x16x32_bf16 v[32:35], v[216:219], v[92:95], v[32:35]
	v_mfma_f32_16x16x32_bf16 v[20:23], v[208:211], v[164:167], v[20:23]
	v_mfma_f32_16x16x32_bf16 v[16:19], v[216:219], v[164:167], v[16:19]
	v_mfma_f32_16x16x32_bf16 v[4:7], v[208:211], v[172:175], v[4:7]
	v_mfma_f32_16x16x32_bf16 v[0:3], v[216:219], v[172:175], v[0:3]
	s_setprio 0
	s_add_i32 s86, s86, 2
	s_add_u32 s42, s42, 0x100
	s_addc_u32 s43, s43, 0
	s_add_u32 s59, s59, 0x100
	s_addc_u32 s61, s61, 0
	s_cmpk_gt_u32 s86, 0x7d
	s_barrier
	s_cbranch_scc0 .LBB0_1168
	v_lshl_or_b32 v160, s66, 8, v236
	v_ashrrev_i32_e32 v161, 31, v160
	v_lshlrev_b64 v[64:65], 2, v[160:161]
	v_lshl_add_u32 v210, s70, 8, v234
	v_lshl_add_u64 v[68:69], s[50:51], 0, v[64:65]
	v_lshl_add_u64 v[76:77], s[54:55], 0, v[64:65]
	global_load_dwordx4 v[80:83], v[68:69], off offset:16
	global_load_dwordx4 v[88:91], v[68:69], off
	global_load_dwordx4 v[84:87], v[76:77], off offset:16
	global_load_dwordx4 v[92:95], v[76:77], off
	global_load_dwordx4 v[64:67], v[68:69], off offset:528
	global_load_dwordx4 v[72:75], v[68:69], off offset:512
	s_nop 0
	global_load_dwordx4 v[68:71], v[76:77], off offset:528
	s_nop 0
	global_load_dwordx4 v[76:79], v[76:77], off offset:512
	v_lshlrev_b64 v[160:161], 1, v[160:161]
	v_ashrrev_i32_e32 v211, 31, v210
	v_add_u32_e32 v214, 16, v210
	v_lshl_add_u64 v[212:213], s[46:47], 0, v[160:161]
	v_lshlrev_b64 v[238:239], 12, v[210:211]
	v_ashrrev_i32_e32 v215, 31, v214
	v_add_u32_e32 v218, 32, v210
	v_lshl_add_u64 v[208:209], s[44:45], 0, v[160:161]
	v_lshl_add_u64 v[160:161], v[212:213], 0, v[238:239]
	v_lshlrev_b64 v[228:229], 12, v[214:215]
	v_ashrrev_i32_e32 v219, 31, v218
	v_add_u32_e32 v220, 48, v210
	v_lshlrev_b64 v[222:223], 12, v[218:219]
	v_ashrrev_i32_e32 v221, 31, v220
	v_lshlrev_b64 v[216:217], 12, v[220:221]
	v_lshlrev_b64 v[230:231], 3, v[210:211]
	v_lshlrev_b64 v[224:225], 3, v[214:215]
	v_lshlrev_b64 v[218:219], 3, v[218:219]
	v_lshlrev_b64 v[214:215], 3, v[220:221]
	v_lshl_add_u64 v[250:251], s[48:49], 0, v[230:231]
	v_lshl_add_u64 v[232:233], s[48:49], 0, v[224:225]
	v_lshl_add_u64 v[226:227], s[48:49], 0, v[218:219]
	v_lshl_add_u64 v[220:221], s[48:49], 0, v[214:215]
	v_lshl_add_u64 v[238:239], v[208:209], 0, v[238:239]
	v_readlane_b32 s2, v255, 32
	v_readlane_b32 s3, v255, 33
	s_waitcnt vmcnt(0)
	global_load_dwordx4 v[246:249], v[160:161], off
	global_load_dwordx4 v[184:187], v[160:161], off offset:256
	v_lshl_add_u64 v[160:161], v[212:213], 0, v[228:229]
	global_load_dwordx4 v[180:183], v[160:161], off
	global_load_dwordx4 v[176:179], v[160:161], off offset:256
	v_lshl_add_u64 v[160:161], v[212:213], 0, v[222:223]
	global_load_dwordx4 v[172:175], v[160:161], off
	global_load_dwordx4 v[168:171], v[160:161], off offset:256
	v_lshl_add_u64 v[160:161], v[212:213], 0, v[216:217]
	global_load_dwordx4 v[164:167], v[160:161], off
	s_nop 0
	global_load_dwordx4 v[160:163], v[160:161], off offset:256
	s_nop 0
	global_load_dwordx2 v[220:221], v[220:221], off
	s_nop 0
	global_load_dwordx2 v[226:227], v[226:227], off
	s_nop 0
	global_load_dwordx2 v[232:233], v[232:233], off
	s_nop 0
	global_load_dwordx2 v[250:251], v[250:251], off
	s_waitcnt vmcnt(0)
	s_nop 0
	v_pk_mul_f32 v[250:251], v[250:251], s[28:29] op_sel_hi:[1,0]
	s_nop 0
	v_fma_f32 v211, -v250, v250, v251
	v_max_f32_e32 v211, 0, v211
	v_add_f32_e32 v211, 0x3727c5ac, v211
	v_cmp_gt_f32_e32 vcc, s13, v211
	v_mul_f32_e32 v240, 0x4b800000, v211
	v_lshlrev_b32_e32 v251, 16, v247
	v_cndmask_b32_e32 v211, v211, v240, vcc
	v_rsq_f32_e32 v211, v211
	v_and_b32_e32 v247, 0xffff0000, v247
	v_lshlrev_b32_e32 v252, 16, v248
	v_and_b32_e32 v248, 0xffff0000, v248
	v_mul_f32_e32 v240, 0x45800000, v211
	v_cndmask_b32_e32 v211, v211, v240, vcc
	v_lshlrev_b32_e32 v240, 16, v246
	v_sub_f32_e32 v240, v240, v250
	v_mul_f32_e32 v240, v240, v211
	v_and_b32_e32 v246, 0xffff0000, v246
	v_fma_f32 v240, v88, v240, v92
	v_fmamk_f32 v156, v240, 0x3fb504f3, v156
	v_sub_f32_e32 v240, v246, v250
	v_mul_f32_e32 v240, v240, v211
	v_fma_f32 v240, v89, v240, v93
	v_fmamk_f32 v157, v240, 0x3fb504f3, v157
	v_sub_f32_e32 v240, v251, v250
	v_mul_f32_e32 v240, v240, v211
	v_fma_f32 v240, v90, v240, v94
	v_fmamk_f32 v158, v240, 0x3fb504f3, v158
	v_sub_f32_e32 v240, v247, v250
	v_mul_f32_e32 v240, v240, v211
	v_fma_f32 v240, v91, v240, v95
	v_fmac_f32_e32 v159, 0x3fb504f3, v240
	v_sub_f32_e32 v240, v252, v250
	v_mul_f32_e32 v240, v240, v211
	v_fma_f32 v240, v80, v240, v84
	v_fmamk_f32 v152, v240, 0x3fb504f3, v152
	v_sub_f32_e32 v240, v248, v250
	v_mul_f32_e32 v240, v240, v211
	v_lshlrev_b32_e32 v253, 16, v249
	v_fma_f32 v240, v81, v240, v85
	v_fmamk_f32 v153, v240, 0x3fb504f3, v153
	v_sub_f32_e32 v240, v253, v250
	v_mul_f32_e32 v240, v240, v211
	v_and_b32_e32 v249, 0xffff0000, v249
	v_fma_f32 v240, v82, v240, v86
	v_fmamk_f32 v154, v240, 0x3fb504f3, v154
	v_sub_f32_e32 v240, v249, v250
	v_mul_f32_e32 v240, v240, v211
	v_fma_f32 v240, v83, v240, v87
	v_fmac_f32_e32 v155, 0x3fb504f3, v240
	v_lshlrev_b32_e32 v240, 16, v184
	v_and_b32_e32 v184, 0xffff0000, v184
	v_sub_f32_e32 v184, v184, v250
	v_cvt_pk_bf16_f32 v246, v156, v157
	v_mul_f32_e32 v184, v184, v211
	v_cvt_pk_bf16_f32 v247, v158, v159
	v_cvt_pk_bf16_f32 v248, v152, v153
	v_cvt_pk_bf16_f32 v249, v154, v155
	global_store_dwordx4 v[238:239], v[246:249], off sc1
	v_fma_f32 v184, v73, v184, v77
	v_fmamk_f32 v149, v184, 0x3fb504f3, v149
	v_lshlrev_b32_e32 v246, 16, v185
	v_sub_f32_e32 v184, v246, v250
	v_mul_f32_e32 v184, v184, v211
	v_and_b32_e32 v185, 0xffff0000, v185
	v_fma_f32 v184, v74, v184, v78
	v_fmamk_f32 v150, v184, 0x3fb504f3, v150
	v_sub_f32_e32 v184, v185, v250
	v_mul_f32_e32 v184, v184, v211
	v_lshlrev_b32_e32 v247, 16, v186
	v_fma_f32 v184, v75, v184, v79
	v_fmac_f32_e32 v151, 0x3fb504f3, v184
	v_sub_f32_e32 v184, v247, v250
	v_mul_f32_e32 v184, v184, v211
	v_and_b32_e32 v186, 0xffff0000, v186
	v_fma_f32 v184, v64, v184, v68
	v_fmamk_f32 v144, v184, 0x3fb504f3, v144
	v_sub_f32_e32 v184, v186, v250
	v_mul_f32_e32 v184, v184, v211
	v_lshlrev_b32_e32 v248, 16, v187
	v_fma_f32 v184, v65, v184, v69
	v_fmamk_f32 v145, v184, 0x3fb504f3, v145
	v_sub_f32_e32 v184, v248, v250
	v_mul_f32_e32 v184, v184, v211
	v_and_b32_e32 v187, 0xffff0000, v187
	v_fma_f32 v184, v66, v184, v70
	v_sub_f32_e32 v240, v240, v250
	v_fmamk_f32 v146, v184, 0x3fb504f3, v146
	v_sub_f32_e32 v184, v187, v250
	v_mul_f32_e32 v240, v240, v211
	v_mul_f32_e32 v184, v184, v211
	v_fma_f32 v240, v72, v240, v76
	v_fma_f32 v184, v67, v184, v71
	v_fmamk_f32 v148, v240, 0x3fb504f3, v148
	v_fmac_f32_e32 v147, 0x3fb504f3, v184
	v_cvt_pk_bf16_f32 v184, v148, v149
	v_cvt_pk_bf16_f32 v185, v150, v151
	v_cvt_pk_bf16_f32 v186, v144, v145
	v_cvt_pk_bf16_f32 v187, v146, v147
	global_store_dwordx4 v[238:239], v[184:187], off offset:256 sc1
	s_andn2_b64 vcc, exec, s[2:3]
	s_nop 0
	v_cndmask_b32_e64 v184, 0, 1, s[2:3]
	v_cmp_ne_u32_e64 s[42:43], 1, v184
	s_cbranch_vccnz .LBB0_1173
	v_mul_f32_e32 v184, v157, v157
	v_fmac_f32_e32 v184, v156, v156
	v_add_f32_e32 v156, 0, v156
	v_add_f32_e32 v156, v157, v156
	v_fmac_f32_e32 v184, v158, v158
	v_add_f32_e32 v156, v158, v156
	v_fmac_f32_e32 v184, v159, v159
	v_add_f32_e32 v156, v159, v156
	v_fmac_f32_e32 v184, v152, v152
	v_add_f32_e32 v152, v152, v156
	v_fmac_f32_e32 v184, v153, v153
	v_add_f32_e32 v152, v153, v152
	v_fmac_f32_e32 v184, v154, v154
	v_add_f32_e32 v152, v154, v152
	v_fmac_f32_e32 v184, v155, v155
	v_add_f32_e32 v152, v155, v152
	v_fmac_f32_e32 v184, v148, v148
	v_add_f32_e32 v148, v148, v152
	v_fmac_f32_e32 v184, v149, v149
	v_add_f32_e32 v148, v149, v148
	v_fmac_f32_e32 v184, v150, v150
	v_add_f32_e32 v148, v150, v148
	v_fmac_f32_e32 v184, v151, v151
	v_add_f32_e32 v148, v151, v148
	v_and_b32_e32 v150, 64, v242
	v_add_f32_e32 v148, v144, v148
	v_xor_b32_e32 v149, 16, v242
	v_add_u32_e32 v150, 64, v150
	v_fmac_f32_e32 v184, v144, v144
	v_add_f32_e32 v148, v145, v148
	v_cmp_lt_i32_e32 vcc, v149, v150
	v_fmac_f32_e32 v184, v145, v145
	v_add_f32_e32 v148, v146, v148
	v_cndmask_b32_e32 v149, v242, v149, vcc
	v_fmac_f32_e32 v184, v146, v146
	v_add_f32_e32 v148, v147, v148
	v_lshlrev_b32_e32 v149, 2, v149
	v_fmac_f32_e32 v184, v147, v147
	ds_bpermute_b32 v151, v149, v148
	ds_bpermute_b32 v146, v149, v184
	v_xor_b32_e32 v145, 32, v242
	v_cmp_lt_i32_e32 vcc, v145, v150
	s_waitcnt lgkmcnt(0)
	v_add_f32_e32 v144, v148, v151
	v_cndmask_b32_e32 v145, v242, v145, vcc
	v_lshlrev_b32_e32 v147, 2, v145
	v_add_f32_e32 v146, v184, v146
	ds_bpermute_b32 v145, v147, v144
	ds_bpermute_b32 v147, v147, v146
	s_and_saveexec_b64 s[2:3], s[38:39]
	s_cbranch_execz .LBB0_1172
	s_waitcnt lgkmcnt(0)
	v_add_f32_e32 v146, v146, v147
	v_add_f32_e32 v147, v144, v145
	v_lshl_add_u64 v[144:145], s[56:57], 0, v[230:231]
	global_atomic_add_f32 v[144:145], v147, off
	global_atomic_add_f32 v[144:145], v146, off offset:4

.LBB0_1173:
	v_pk_mul_f32 v[148:149], v[232:233], s[28:29] op_sel_hi:[1,0]
	s_waitcnt lgkmcnt(0)
	v_and_b32_e32 v147, 0xffff0000, v181
	v_fma_f32 v144, -v148, v148, v149
	v_max_f32_e32 v144, 0, v144
	v_add_f32_e32 v144, 0x3727c5ac, v144
	v_mul_f32_e32 v145, 0x4b800000, v144
	v_cmp_gt_f32_e32 vcc, s13, v144
	v_lshlrev_b32_e32 v152, 16, v182
	v_and_b32_e32 v153, 0xffff0000, v182
	v_cndmask_b32_e32 v144, v144, v145, vcc
	v_rsq_f32_e32 v144, v144
	v_lshlrev_b32_e32 v154, 16, v183
	v_lshlrev_b32_e32 v145, 16, v180
	v_and_b32_e32 v155, 0xffff0000, v183
	v_mul_f32_e32 v146, 0x45800000, v144
	v_cndmask_b32_e32 v149, v144, v146, vcc
	v_and_b32_e32 v144, 0xffff0000, v180
	v_sub_f32_e32 v144, v144, v148
	v_mul_f32_e32 v144, v144, v149
	v_lshlrev_b32_e32 v146, 16, v181
	v_fma_f32 v144, v89, v144, v93
	v_fmamk_f32 v141, v144, 0x3fb504f3, v141
	v_sub_f32_e32 v144, v146, v148
	v_mul_f32_e32 v144, v144, v149
	v_fma_f32 v144, v90, v144, v94
	v_fmamk_f32 v142, v144, 0x3fb504f3, v142
	v_sub_f32_e32 v144, v147, v148
	v_mul_f32_e32 v144, v144, v149
	v_fma_f32 v144, v91, v144, v95
	v_fmac_f32_e32 v143, 0x3fb504f3, v144
	v_sub_f32_e32 v144, v152, v148
	v_mul_f32_e32 v144, v144, v149
	v_fma_f32 v144, v80, v144, v84
	v_fmamk_f32 v136, v144, 0x3fb504f3, v136
	v_sub_f32_e32 v144, v153, v148
	v_mul_f32_e32 v144, v144, v149
	v_fma_f32 v144, v81, v144, v85
	v_fmamk_f32 v137, v144, 0x3fb504f3, v137
	v_sub_f32_e32 v144, v154, v148
	v_mul_f32_e32 v144, v144, v149
	v_fma_f32 v144, v82, v144, v86
	v_sub_f32_e32 v145, v145, v148
	v_fmamk_f32 v138, v144, 0x3fb504f3, v138
	v_sub_f32_e32 v144, v155, v148
	v_mul_f32_e32 v145, v145, v149
	v_mul_f32_e32 v144, v144, v149
	v_fma_f32 v145, v88, v145, v92
	v_fma_f32 v144, v83, v144, v87
	v_lshl_add_u64 v[150:151], v[208:209], 0, v[228:229]
	v_fmamk_f32 v140, v145, 0x3fb504f3, v140
	v_fmac_f32_e32 v139, 0x3fb504f3, v144
	v_cvt_pk_bf16_f32 v144, v140, v141
	v_cvt_pk_bf16_f32 v145, v142, v143
	v_cvt_pk_bf16_f32 v146, v136, v137
	v_cvt_pk_bf16_f32 v147, v138, v139
	global_store_dwordx4 v[150:151], v[144:147], off sc1
	v_lshlrev_b32_e32 v152, 16, v178
	v_and_b32_e32 v153, 0xffff0000, v178
	v_lshlrev_b32_e32 v144, 16, v176
	v_sub_f32_e32 v144, v144, v148
	v_mul_f32_e32 v144, v144, v149
	v_and_b32_e32 v145, 0xffff0000, v176
	v_fma_f32 v144, v72, v144, v76
	v_fmamk_f32 v132, v144, 0x3fb504f3, v132
	v_sub_f32_e32 v144, v145, v148
	v_mul_f32_e32 v144, v144, v149
	v_lshlrev_b32_e32 v146, 16, v177
	v_fma_f32 v144, v73, v144, v77
	v_fmamk_f32 v133, v144, 0x3fb504f3, v133
	v_sub_f32_e32 v144, v146, v148
	v_mul_f32_e32 v144, v144, v149
	v_and_b32_e32 v147, 0xffff0000, v177
	v_fma_f32 v144, v74, v144, v78
	v_fmamk_f32 v134, v144, 0x3fb504f3, v134
	v_sub_f32_e32 v144, v147, v148
	v_mul_f32_e32 v144, v144, v149
	v_fma_f32 v144, v75, v144, v79
	v_fmac_f32_e32 v135, 0x3fb504f3, v144
	v_sub_f32_e32 v144, v152, v148
	v_mul_f32_e32 v144, v144, v149
	v_fma_f32 v144, v64, v144, v68
	v_fmamk_f32 v128, v144, 0x3fb504f3, v128
	v_sub_f32_e32 v144, v153, v148
	v_mul_f32_e32 v144, v144, v149
	v_lshlrev_b32_e32 v154, 16, v179
	v_fma_f32 v144, v65, v144, v69
	v_fmamk_f32 v129, v144, 0x3fb504f3, v129
	v_sub_f32_e32 v144, v154, v148
	v_mul_f32_e32 v144, v144, v149
	v_and_b32_e32 v155, 0xffff0000, v179
	v_fma_f32 v144, v66, v144, v70
	v_fmamk_f32 v130, v144, 0x3fb504f3, v130
	v_sub_f32_e32 v144, v155, v148
	v_mul_f32_e32 v144, v144, v149
	v_fma_f32 v144, v67, v144, v71
	v_fmac_f32_e32 v131, 0x3fb504f3, v144
	s_and_b64 vcc, exec, s[42:43]
	v_cvt_pk_bf16_f32 v144, v132, v133
	v_cvt_pk_bf16_f32 v145, v134, v135
	v_cvt_pk_bf16_f32 v146, v128, v129
	v_cvt_pk_bf16_f32 v147, v130, v131
	global_store_dwordx4 v[150:151], v[144:147], off offset:256 sc1
	s_cbranch_vccnz .LBB0_1177
	s_nop 0
	v_mul_f32_e32 v144, v141, v141
	v_fmac_f32_e32 v144, v140, v140
	v_add_f32_e32 v140, 0, v140
	v_add_f32_e32 v140, v141, v140
	v_fmac_f32_e32 v144, v142, v142
	v_add_f32_e32 v140, v142, v140
	v_fmac_f32_e32 v144, v143, v143
	v_add_f32_e32 v140, v143, v140
	v_fmac_f32_e32 v144, v136, v136
	v_add_f32_e32 v136, v136, v140
	v_fmac_f32_e32 v144, v137, v137
	v_add_f32_e32 v136, v137, v136
	v_fmac_f32_e32 v144, v138, v138
	v_add_f32_e32 v136, v138, v136
	v_fmac_f32_e32 v144, v139, v139
	v_add_f32_e32 v136, v139, v136
	v_fmac_f32_e32 v144, v132, v132
	v_add_f32_e32 v132, v132, v136
	v_fmac_f32_e32 v144, v133, v133
	v_add_f32_e32 v132, v133, v132
	v_fmac_f32_e32 v144, v134, v134
	v_add_f32_e32 v132, v134, v132
	v_fmac_f32_e32 v144, v135, v135
	v_add_f32_e32 v132, v135, v132
	v_and_b32_e32 v134, 64, v242
	v_add_f32_e32 v132, v128, v132
	v_xor_b32_e32 v133, 16, v242
	v_add_u32_e32 v134, 64, v134
	v_fmac_f32_e32 v144, v128, v128
	v_add_f32_e32 v132, v129, v132
	v_cmp_lt_i32_e32 vcc, v133, v134
	v_fmac_f32_e32 v144, v129, v129
	v_add_f32_e32 v132, v130, v132
	v_cndmask_b32_e32 v133, v242, v133, vcc
	v_fmac_f32_e32 v144, v130, v130
	v_add_f32_e32 v132, v131, v132
	v_lshlrev_b32_e32 v133, 2, v133
	v_fmac_f32_e32 v144, v131, v131
	ds_bpermute_b32 v135, v133, v132
	ds_bpermute_b32 v130, v133, v144
	v_xor_b32_e32 v129, 32, v242
	v_cmp_lt_i32_e32 vcc, v129, v134
	s_waitcnt lgkmcnt(1)
	v_add_f32_e32 v128, v132, v135
	v_cndmask_b32_e32 v129, v242, v129, vcc
	v_lshlrev_b32_e32 v131, 2, v129
	s_waitcnt lgkmcnt(0)
	v_add_f32_e32 v130, v144, v130
	ds_bpermute_b32 v129, v131, v128
	ds_bpermute_b32 v131, v131, v130
	s_and_saveexec_b64 s[2:3], s[38:39]
	s_cbranch_execz .LBB0_1176
	s_waitcnt lgkmcnt(0)
	v_add_f32_e32 v130, v130, v131
	v_add_f32_e32 v131, v128, v129
	v_lshl_add_u64 v[128:129], s[56:57], 0, v[224:225]
	global_atomic_add_f32 v[128:129], v131, off
	global_atomic_add_f32 v[128:129], v130, off offset:4

.LBB0_1177:
	v_pk_mul_f32 v[132:133], v[226:227], s[28:29] op_sel_hi:[1,0]
	s_waitcnt lgkmcnt(0)
	v_and_b32_e32 v131, 0xffff0000, v173
	v_fma_f32 v128, -v132, v132, v133
	v_max_f32_e32 v128, 0, v128
	v_add_f32_e32 v128, 0x3727c5ac, v128
	v_mul_f32_e32 v129, 0x4b800000, v128
	v_cmp_gt_f32_e32 vcc, s13, v128
	v_lshlrev_b32_e32 v136, 16, v174
	v_and_b32_e32 v137, 0xffff0000, v174
	v_cndmask_b32_e32 v128, v128, v129, vcc
	v_rsq_f32_e32 v128, v128
	v_lshlrev_b32_e32 v138, 16, v175
	v_lshlrev_b32_e32 v129, 16, v172
	v_and_b32_e32 v139, 0xffff0000, v175
	v_mul_f32_e32 v130, 0x45800000, v128
	v_cndmask_b32_e32 v133, v128, v130, vcc
	v_and_b32_e32 v128, 0xffff0000, v172
	v_sub_f32_e32 v128, v128, v132
	v_mul_f32_e32 v128, v128, v133
	v_lshlrev_b32_e32 v130, 16, v173
	v_fma_f32 v128, v89, v128, v93
	v_fmamk_f32 v125, v128, 0x3fb504f3, v125
	v_sub_f32_e32 v128, v130, v132
	v_mul_f32_e32 v128, v128, v133
	v_fma_f32 v128, v90, v128, v94
	v_fmamk_f32 v126, v128, 0x3fb504f3, v126
	v_sub_f32_e32 v128, v131, v132
	v_mul_f32_e32 v128, v128, v133
	v_fma_f32 v128, v91, v128, v95
	v_fmac_f32_e32 v127, 0x3fb504f3, v128
	v_sub_f32_e32 v128, v136, v132
	v_mul_f32_e32 v128, v128, v133
	v_fma_f32 v128, v80, v128, v84
	v_fmamk_f32 v120, v128, 0x3fb504f3, v120
	v_sub_f32_e32 v128, v137, v132
	v_mul_f32_e32 v128, v128, v133
	v_fma_f32 v128, v81, v128, v85
	v_fmamk_f32 v121, v128, 0x3fb504f3, v121
	v_sub_f32_e32 v128, v138, v132
	v_mul_f32_e32 v128, v128, v133
	v_fma_f32 v128, v82, v128, v86
	v_sub_f32_e32 v129, v129, v132
	v_fmamk_f32 v122, v128, 0x3fb504f3, v122
	v_sub_f32_e32 v128, v139, v132
	v_mul_f32_e32 v129, v129, v133
	v_mul_f32_e32 v128, v128, v133
	v_fma_f32 v129, v88, v129, v92
	v_fma_f32 v128, v83, v128, v87
	v_lshl_add_u64 v[134:135], v[208:209], 0, v[222:223]
	v_fmamk_f32 v124, v129, 0x3fb504f3, v124
	v_fmac_f32_e32 v123, 0x3fb504f3, v128
	v_cvt_pk_bf16_f32 v128, v124, v125
	v_cvt_pk_bf16_f32 v129, v126, v127
	v_cvt_pk_bf16_f32 v130, v120, v121
	v_cvt_pk_bf16_f32 v131, v122, v123
	global_store_dwordx4 v[134:135], v[128:131], off sc1
	v_lshlrev_b32_e32 v136, 16, v170
	v_and_b32_e32 v137, 0xffff0000, v170
	v_lshlrev_b32_e32 v128, 16, v168
	v_sub_f32_e32 v128, v128, v132
	v_mul_f32_e32 v128, v128, v133
	v_and_b32_e32 v129, 0xffff0000, v168
	v_fma_f32 v128, v72, v128, v76
	v_fmamk_f32 v116, v128, 0x3fb504f3, v116
	v_sub_f32_e32 v128, v129, v132
	v_mul_f32_e32 v128, v128, v133
	v_lshlrev_b32_e32 v130, 16, v169
	v_fma_f32 v128, v73, v128, v77
	v_fmamk_f32 v117, v128, 0x3fb504f3, v117
	v_sub_f32_e32 v128, v130, v132
	v_mul_f32_e32 v128, v128, v133
	v_and_b32_e32 v131, 0xffff0000, v169
	v_fma_f32 v128, v74, v128, v78
	v_fmamk_f32 v118, v128, 0x3fb504f3, v118
	v_sub_f32_e32 v128, v131, v132
	v_mul_f32_e32 v128, v128, v133
	v_fma_f32 v128, v75, v128, v79
	v_fmac_f32_e32 v119, 0x3fb504f3, v128
	v_sub_f32_e32 v128, v136, v132
	v_mul_f32_e32 v128, v128, v133
	v_fma_f32 v128, v64, v128, v68
	v_fmamk_f32 v112, v128, 0x3fb504f3, v112
	v_sub_f32_e32 v128, v137, v132
	v_mul_f32_e32 v128, v128, v133
	v_lshlrev_b32_e32 v138, 16, v171
	v_fma_f32 v128, v65, v128, v69
	v_fmamk_f32 v113, v128, 0x3fb504f3, v113
	v_sub_f32_e32 v128, v138, v132
	v_mul_f32_e32 v128, v128, v133
	v_and_b32_e32 v139, 0xffff0000, v171
	v_fma_f32 v128, v66, v128, v70
	v_fmamk_f32 v114, v128, 0x3fb504f3, v114
	v_sub_f32_e32 v128, v139, v132
	v_mul_f32_e32 v128, v128, v133
	v_fma_f32 v128, v67, v128, v71
	v_fmac_f32_e32 v115, 0x3fb504f3, v128
	s_and_b64 vcc, exec, s[42:43]
	v_cvt_pk_bf16_f32 v128, v116, v117
	v_cvt_pk_bf16_f32 v129, v118, v119
	v_cvt_pk_bf16_f32 v130, v112, v113
	v_cvt_pk_bf16_f32 v131, v114, v115
	global_store_dwordx4 v[134:135], v[128:131], off offset:256 sc1
	s_cbranch_vccnz .LBB0_1181
	s_nop 0
	v_mul_f32_e32 v128, v125, v125
	v_fmac_f32_e32 v128, v124, v124
	v_add_f32_e32 v124, 0, v124
	v_add_f32_e32 v124, v125, v124
	v_fmac_f32_e32 v128, v126, v126
	v_add_f32_e32 v124, v126, v124
	v_fmac_f32_e32 v128, v127, v127
	v_add_f32_e32 v124, v127, v124
	v_fmac_f32_e32 v128, v120, v120
	v_add_f32_e32 v120, v120, v124
	v_fmac_f32_e32 v128, v121, v121
	v_add_f32_e32 v120, v121, v120
	v_fmac_f32_e32 v128, v122, v122
	v_add_f32_e32 v120, v122, v120
	v_fmac_f32_e32 v128, v123, v123
	v_add_f32_e32 v120, v123, v120
	v_fmac_f32_e32 v128, v116, v116
	v_add_f32_e32 v116, v116, v120
	v_fmac_f32_e32 v128, v117, v117
	v_add_f32_e32 v116, v117, v116
	v_fmac_f32_e32 v128, v118, v118
	v_add_f32_e32 v116, v118, v116
	v_fmac_f32_e32 v128, v119, v119
	v_add_f32_e32 v116, v119, v116
	v_and_b32_e32 v118, 64, v242
	v_add_f32_e32 v116, v112, v116
	v_xor_b32_e32 v117, 16, v242
	v_add_u32_e32 v118, 64, v118
	v_fmac_f32_e32 v128, v112, v112
	v_add_f32_e32 v116, v113, v116
	v_cmp_lt_i32_e32 vcc, v117, v118
	v_fmac_f32_e32 v128, v113, v113
	v_add_f32_e32 v116, v114, v116
	v_cndmask_b32_e32 v117, v242, v117, vcc
	v_fmac_f32_e32 v128, v114, v114
	v_add_f32_e32 v116, v115, v116
	v_lshlrev_b32_e32 v117, 2, v117
	v_fmac_f32_e32 v128, v115, v115
	ds_bpermute_b32 v119, v117, v116
	ds_bpermute_b32 v114, v117, v128
	v_xor_b32_e32 v113, 32, v242
	v_cmp_lt_i32_e32 vcc, v113, v118
	s_waitcnt lgkmcnt(1)
	v_add_f32_e32 v112, v116, v119
	v_cndmask_b32_e32 v113, v242, v113, vcc
	v_lshlrev_b32_e32 v115, 2, v113
	s_waitcnt lgkmcnt(0)
	v_add_f32_e32 v114, v128, v114
	ds_bpermute_b32 v113, v115, v112
	ds_bpermute_b32 v115, v115, v114
	s_and_saveexec_b64 s[2:3], s[38:39]
	s_cbranch_execz .LBB0_1180
	s_waitcnt lgkmcnt(0)
	v_add_f32_e32 v114, v114, v115
	v_add_f32_e32 v115, v112, v113
	v_lshl_add_u64 v[112:113], s[56:57], 0, v[218:219]
	global_atomic_add_f32 v[112:113], v115, off
	global_atomic_add_f32 v[112:113], v114, off offset:4

.LBB0_1181:
	v_pk_mul_f32 v[116:117], v[220:221], s[28:29] op_sel_hi:[1,0]
	s_waitcnt lgkmcnt(0)
	v_and_b32_e32 v115, 0xffff0000, v165
	v_fma_f32 v112, -v116, v116, v117
	v_max_f32_e32 v112, 0, v112
	v_add_f32_e32 v112, 0x3727c5ac, v112
	v_mul_f32_e32 v113, 0x4b800000, v112
	v_cmp_gt_f32_e32 vcc, s13, v112
	v_lshlrev_b32_e32 v120, 16, v166
	v_and_b32_e32 v121, 0xffff0000, v166
	v_cndmask_b32_e32 v112, v112, v113, vcc
	v_rsq_f32_e32 v112, v112
	v_lshlrev_b32_e32 v122, 16, v167
	v_lshlrev_b32_e32 v113, 16, v164
	v_and_b32_e32 v123, 0xffff0000, v167
	v_mul_f32_e32 v114, 0x45800000, v112
	v_cndmask_b32_e32 v117, v112, v114, vcc
	v_and_b32_e32 v112, 0xffff0000, v164
	v_sub_f32_e32 v112, v112, v116
	v_mul_f32_e32 v112, v112, v117
	v_lshlrev_b32_e32 v114, 16, v165
	v_fma_f32 v112, v89, v112, v93
	v_fmamk_f32 v109, v112, 0x3fb504f3, v109
	v_sub_f32_e32 v112, v114, v116
	v_mul_f32_e32 v112, v112, v117
	v_fma_f32 v112, v90, v112, v94
	v_fmamk_f32 v110, v112, 0x3fb504f3, v110
	v_sub_f32_e32 v112, v115, v116
	v_mul_f32_e32 v112, v112, v117
	v_fma_f32 v112, v91, v112, v95
	v_fmac_f32_e32 v111, 0x3fb504f3, v112
	v_sub_f32_e32 v112, v120, v116
	v_mul_f32_e32 v112, v112, v117
	v_fma_f32 v112, v80, v112, v84
	v_fmamk_f32 v104, v112, 0x3fb504f3, v104
	v_sub_f32_e32 v112, v121, v116
	v_mul_f32_e32 v112, v112, v117
	v_fma_f32 v112, v81, v112, v85
	v_fmamk_f32 v105, v112, 0x3fb504f3, v105
	v_sub_f32_e32 v112, v122, v116
	v_mul_f32_e32 v112, v112, v117
	v_fma_f32 v112, v82, v112, v86
	v_sub_f32_e32 v113, v113, v116
	v_fmamk_f32 v106, v112, 0x3fb504f3, v106
	v_sub_f32_e32 v112, v123, v116
	v_mul_f32_e32 v113, v113, v117
	v_mul_f32_e32 v112, v112, v117
	v_fma_f32 v113, v88, v113, v92
	v_fma_f32 v112, v83, v112, v87
	v_lshl_add_u64 v[118:119], v[208:209], 0, v[216:217]
	v_fmamk_f32 v108, v113, 0x3fb504f3, v108
	v_fmac_f32_e32 v107, 0x3fb504f3, v112
	v_cvt_pk_bf16_f32 v112, v108, v109
	v_cvt_pk_bf16_f32 v113, v110, v111
	v_cvt_pk_bf16_f32 v114, v104, v105
	v_cvt_pk_bf16_f32 v115, v106, v107
	global_store_dwordx4 v[118:119], v[112:115], off sc1
	v_lshlrev_b32_e32 v120, 16, v162
	v_and_b32_e32 v121, 0xffff0000, v162
	v_lshlrev_b32_e32 v112, 16, v160
	v_sub_f32_e32 v112, v112, v116
	v_mul_f32_e32 v112, v112, v117
	v_and_b32_e32 v113, 0xffff0000, v160
	v_fma_f32 v112, v72, v112, v76
	v_fmamk_f32 v100, v112, 0x3fb504f3, v100
	v_sub_f32_e32 v112, v113, v116
	v_mul_f32_e32 v112, v112, v117
	v_lshlrev_b32_e32 v114, 16, v161
	v_fma_f32 v112, v73, v112, v77
	v_fmamk_f32 v101, v112, 0x3fb504f3, v101
	v_sub_f32_e32 v112, v114, v116
	v_mul_f32_e32 v112, v112, v117
	v_and_b32_e32 v115, 0xffff0000, v161
	v_fma_f32 v112, v74, v112, v78
	v_fmamk_f32 v102, v112, 0x3fb504f3, v102
	v_sub_f32_e32 v112, v115, v116
	v_mul_f32_e32 v112, v112, v117
	v_fma_f32 v112, v75, v112, v79
	v_fmac_f32_e32 v103, 0x3fb504f3, v112
	v_sub_f32_e32 v112, v120, v116
	v_mul_f32_e32 v112, v112, v117
	v_fma_f32 v112, v64, v112, v68
	v_fmamk_f32 v96, v112, 0x3fb504f3, v96
	v_sub_f32_e32 v112, v121, v116
	v_mul_f32_e32 v112, v112, v117
	v_lshlrev_b32_e32 v122, 16, v163
	v_fma_f32 v112, v65, v112, v69
	v_fmamk_f32 v97, v112, 0x3fb504f3, v97
	v_sub_f32_e32 v112, v122, v116
	v_mul_f32_e32 v112, v112, v117
	v_and_b32_e32 v123, 0xffff0000, v163
	v_fma_f32 v112, v66, v112, v70
	v_fmamk_f32 v98, v112, 0x3fb504f3, v98
	v_sub_f32_e32 v112, v123, v116
	v_mul_f32_e32 v112, v112, v117
	v_fma_f32 v112, v67, v112, v71
	v_fmac_f32_e32 v99, 0x3fb504f3, v112
	s_and_b64 vcc, exec, s[42:43]
	v_cvt_pk_bf16_f32 v112, v100, v101
	v_cvt_pk_bf16_f32 v113, v102, v103
	v_cvt_pk_bf16_f32 v114, v96, v97
	v_cvt_pk_bf16_f32 v115, v98, v99
	global_store_dwordx4 v[118:119], v[112:115], off offset:256 sc1
	s_cbranch_vccnz .LBB0_1185
	s_nop 0
	v_mul_f32_e32 v112, v109, v109
	v_fmac_f32_e32 v112, v108, v108
	v_add_f32_e32 v108, 0, v108
	v_add_f32_e32 v108, v109, v108
	v_fmac_f32_e32 v112, v110, v110
	v_add_f32_e32 v108, v110, v108
	v_fmac_f32_e32 v112, v111, v111
	v_add_f32_e32 v108, v111, v108
	v_fmac_f32_e32 v112, v104, v104
	v_add_f32_e32 v104, v104, v108
	v_fmac_f32_e32 v112, v105, v105
	v_add_f32_e32 v104, v105, v104
	v_fmac_f32_e32 v112, v106, v106
	v_add_f32_e32 v104, v106, v104
	v_fmac_f32_e32 v112, v107, v107
	v_add_f32_e32 v104, v107, v104
	v_fmac_f32_e32 v112, v100, v100
	v_add_f32_e32 v100, v100, v104
	v_fmac_f32_e32 v112, v101, v101
	v_add_f32_e32 v100, v101, v100
	v_fmac_f32_e32 v112, v102, v102
	v_add_f32_e32 v100, v102, v100
	v_fmac_f32_e32 v112, v103, v103
	v_add_f32_e32 v100, v103, v100
	v_and_b32_e32 v102, 64, v242
	v_add_f32_e32 v100, v96, v100
	v_xor_b32_e32 v101, 16, v242
	v_add_u32_e32 v102, 64, v102
	v_fmac_f32_e32 v112, v96, v96
	v_add_f32_e32 v100, v97, v100
	v_cmp_lt_i32_e32 vcc, v101, v102
	v_fmac_f32_e32 v112, v97, v97
	v_add_f32_e32 v100, v98, v100
	v_cndmask_b32_e32 v101, v242, v101, vcc
	v_fmac_f32_e32 v112, v98, v98
	v_add_f32_e32 v100, v99, v100
	v_lshlrev_b32_e32 v101, 2, v101
	v_fmac_f32_e32 v112, v99, v99
	ds_bpermute_b32 v103, v101, v100
	ds_bpermute_b32 v98, v101, v112
	v_xor_b32_e32 v97, 32, v242
	v_cmp_lt_i32_e32 vcc, v97, v102
	s_waitcnt lgkmcnt(1)
	v_add_f32_e32 v96, v100, v103
	v_cndmask_b32_e32 v97, v242, v97, vcc
	v_lshlrev_b32_e32 v99, 2, v97
	s_waitcnt lgkmcnt(0)
	v_add_f32_e32 v98, v112, v98
	ds_bpermute_b32 v97, v99, v96
	ds_bpermute_b32 v99, v99, v98
	s_and_saveexec_b64 s[2:3], s[38:39]
	s_cbranch_execz .LBB0_1184
	s_waitcnt lgkmcnt(0)
	v_add_f32_e32 v98, v98, v99
	v_add_f32_e32 v99, v96, v97
	v_lshl_add_u64 v[96:97], s[56:57], 0, v[214:215]
	global_atomic_add_f32 v[96:97], v99, off
	global_atomic_add_f32 v[96:97], v98, off offset:4

.LBB0_1185:
	v_add_u32_e32 v124, 0x80, v210
	v_ashrrev_i32_e32 v125, 31, v124
	v_add_u32_e32 v128, 0x90, v210
	v_lshlrev_b64 v[144:145], 12, v[124:125]
	v_ashrrev_i32_e32 v129, 31, v128
	v_add_u32_e32 v130, 0xa0, v210
	s_waitcnt lgkmcnt(1)
	v_lshl_add_u64 v[96:97], v[212:213], 0, v[144:145]
	v_lshlrev_b64 v[138:139], 12, v[128:129]
	v_ashrrev_i32_e32 v131, 31, v130
	v_add_u32_e32 v134, 0xb0, v210
	global_load_dwordx4 v[148:151], v[96:97], off
	global_load_dwordx4 v[120:123], v[96:97], off offset:256
	v_lshl_add_u64 v[96:97], v[212:213], 0, v[138:139]
	v_lshlrev_b64 v[132:133], 12, v[130:131]
	v_ashrrev_i32_e32 v135, 31, v134
	global_load_dwordx4 v[116:119], v[96:97], off
	global_load_dwordx4 v[112:115], v[96:97], off offset:256
	v_lshl_add_u64 v[96:97], v[212:213], 0, v[132:133]
	v_lshlrev_b64 v[126:127], 12, v[134:135]
	v_lshlrev_b64 v[140:141], 3, v[124:125]
	v_lshlrev_b64 v[136:137], 3, v[128:129]
	v_lshlrev_b64 v[124:125], 3, v[134:135]
	global_load_dwordx4 v[108:111], v[96:97], off
	global_load_dwordx4 v[104:107], v[96:97], off offset:256
	v_lshl_add_u64 v[96:97], v[212:213], 0, v[126:127]
	v_lshl_add_u64 v[146:147], s[48:49], 0, v[140:141]
	v_lshl_add_u64 v[142:143], s[48:49], 0, v[136:137]
	v_lshlrev_b64 v[130:131], 3, v[130:131]
	v_lshl_add_u64 v[128:129], s[48:49], 0, v[124:125]
	global_load_dwordx4 v[100:103], v[96:97], off
	s_waitcnt lgkmcnt(0)
	global_load_dwordx4 v[96:99], v[96:97], off offset:256
	v_lshl_add_u64 v[152:153], s[48:49], 0, v[130:131]
	global_load_dwordx2 v[128:129], v[128:129], off
	s_nop 0
	global_load_dwordx2 v[134:135], v[152:153], off
	s_nop 0
	global_load_dwordx2 v[142:143], v[142:143], off
	s_nop 0
	global_load_dwordx2 v[146:147], v[146:147], off
	v_lshl_add_u64 v[144:145], v[208:209], 0, v[144:145]
	s_waitcnt vmcnt(0)
	s_nop 0
	v_pk_mul_f32 v[146:147], v[146:147], s[28:29] op_sel_hi:[1,0]
	s_nop 0
	v_fma_f32 v147, -v146, v146, v147
	v_max_f32_e32 v147, 0, v147
	v_add_f32_e32 v147, 0x3727c5ac, v147
	v_cmp_gt_f32_e32 vcc, s13, v147
	v_mul_f32_e32 v152, 0x4b800000, v147
	v_lshlrev_b32_e32 v153, 16, v149
	v_cndmask_b32_e32 v147, v147, v152, vcc
	v_rsq_f32_e32 v147, v147
	v_and_b32_e32 v149, 0xffff0000, v149
	v_lshlrev_b32_e32 v154, 16, v150
	v_and_b32_e32 v150, 0xffff0000, v150
	v_mul_f32_e32 v152, 0x45800000, v147
	v_cndmask_b32_e32 v147, v147, v152, vcc
	v_lshlrev_b32_e32 v152, 16, v148
	v_and_b32_e32 v148, 0xffff0000, v148
	v_sub_f32_e32 v148, v148, v146
	v_mul_f32_e32 v148, v148, v147
	v_fma_f32 v148, v89, v148, v93
	v_fmamk_f32 v61, v148, 0x3fb504f3, v61
	v_sub_f32_e32 v148, v153, v146
	v_mul_f32_e32 v148, v148, v147
	v_fma_f32 v148, v90, v148, v94
	v_fmamk_f32 v62, v148, 0x3fb504f3, v62
	v_sub_f32_e32 v148, v149, v146
	v_mul_f32_e32 v148, v148, v147
	v_fma_f32 v148, v91, v148, v95
	v_fmac_f32_e32 v63, 0x3fb504f3, v148
	v_sub_f32_e32 v148, v154, v146
	v_mul_f32_e32 v148, v148, v147
	v_fma_f32 v148, v80, v148, v84
	v_fmamk_f32 v56, v148, 0x3fb504f3, v56
	v_sub_f32_e32 v148, v150, v146
	v_mul_f32_e32 v148, v148, v147
	v_lshlrev_b32_e32 v155, 16, v151
	v_fma_f32 v148, v81, v148, v85
	v_fmamk_f32 v57, v148, 0x3fb504f3, v57
	v_sub_f32_e32 v148, v155, v146
	v_mul_f32_e32 v148, v148, v147
	v_and_b32_e32 v151, 0xffff0000, v151
	v_fma_f32 v148, v82, v148, v86
	v_sub_f32_e32 v152, v152, v146
	v_fmamk_f32 v58, v148, 0x3fb504f3, v58
	v_sub_f32_e32 v148, v151, v146
	v_mul_f32_e32 v152, v152, v147
	v_mul_f32_e32 v148, v148, v147
	v_fma_f32 v152, v88, v152, v92
	v_fma_f32 v148, v83, v148, v87
	v_fmamk_f32 v60, v152, 0x3fb504f3, v60
	v_fmac_f32_e32 v59, 0x3fb504f3, v148
	v_cvt_pk_bf16_f32 v148, v60, v61
	v_cvt_pk_bf16_f32 v149, v62, v63
	v_cvt_pk_bf16_f32 v150, v56, v57
	v_cvt_pk_bf16_f32 v151, v58, v59
	global_store_dwordx4 v[144:145], v[148:151], off sc1
	s_and_b64 vcc, exec, s[42:43]
	s_nop 0
	v_lshlrev_b32_e32 v148, 16, v120
	v_and_b32_e32 v120, 0xffff0000, v120
	v_sub_f32_e32 v120, v120, v146
	v_mul_f32_e32 v120, v120, v147
	v_lshlrev_b32_e32 v149, 16, v121
	v_fma_f32 v120, v73, v120, v77
	v_fmamk_f32 v53, v120, 0x3fb504f3, v53
	v_sub_f32_e32 v120, v149, v146
	v_mul_f32_e32 v120, v120, v147
	v_and_b32_e32 v121, 0xffff0000, v121
	v_fma_f32 v120, v74, v120, v78
	v_fmamk_f32 v54, v120, 0x3fb504f3, v54
	v_sub_f32_e32 v120, v121, v146
	v_mul_f32_e32 v120, v120, v147
	v_lshlrev_b32_e32 v150, 16, v122
	v_fma_f32 v120, v75, v120, v79
	v_fmac_f32_e32 v55, 0x3fb504f3, v120
	v_sub_f32_e32 v120, v150, v146
	v_mul_f32_e32 v120, v120, v147
	v_and_b32_e32 v122, 0xffff0000, v122
	v_fma_f32 v120, v64, v120, v68
	v_fmamk_f32 v48, v120, 0x3fb504f3, v48
	v_sub_f32_e32 v120, v122, v146
	v_mul_f32_e32 v120, v120, v147
	v_lshlrev_b32_e32 v151, 16, v123
	v_fma_f32 v120, v65, v120, v69
	v_fmamk_f32 v49, v120, 0x3fb504f3, v49
	v_sub_f32_e32 v120, v151, v146
	v_mul_f32_e32 v120, v120, v147
	v_and_b32_e32 v123, 0xffff0000, v123
	v_fma_f32 v120, v66, v120, v70
	v_sub_f32_e32 v148, v148, v146
	v_fmamk_f32 v50, v120, 0x3fb504f3, v50
	v_sub_f32_e32 v120, v123, v146
	v_mul_f32_e32 v148, v148, v147
	v_mul_f32_e32 v120, v120, v147
	v_fma_f32 v148, v72, v148, v76
	v_fma_f32 v120, v67, v120, v71
	v_fmamk_f32 v52, v148, 0x3fb504f3, v52
	v_fmac_f32_e32 v51, 0x3fb504f3, v120
	v_cvt_pk_bf16_f32 v120, v52, v53
	v_cvt_pk_bf16_f32 v121, v54, v55
	v_cvt_pk_bf16_f32 v122, v48, v49
	v_cvt_pk_bf16_f32 v123, v50, v51
	global_store_dwordx4 v[144:145], v[120:123], off offset:256 sc1
	s_cbranch_vccnz .LBB0_1189
	s_nop 0
	v_mul_f32_e32 v120, v61, v61
	v_fmac_f32_e32 v120, v60, v60
	v_add_f32_e32 v60, 0, v60
	v_add_f32_e32 v60, v61, v60
	v_fmac_f32_e32 v120, v62, v62
	v_add_f32_e32 v60, v62, v60
	v_fmac_f32_e32 v120, v63, v63
	v_add_f32_e32 v60, v63, v60
	v_fmac_f32_e32 v120, v56, v56
	v_add_f32_e32 v56, v56, v60
	v_fmac_f32_e32 v120, v57, v57
	v_add_f32_e32 v56, v57, v56
	v_fmac_f32_e32 v120, v58, v58
	v_add_f32_e32 v56, v58, v56
	v_fmac_f32_e32 v120, v59, v59
	v_add_f32_e32 v56, v59, v56
	v_fmac_f32_e32 v120, v52, v52
	v_add_f32_e32 v52, v52, v56
	v_fmac_f32_e32 v120, v53, v53
	v_add_f32_e32 v52, v53, v52
	v_fmac_f32_e32 v120, v54, v54
	v_add_f32_e32 v52, v54, v52
	v_fmac_f32_e32 v120, v55, v55
	v_add_f32_e32 v52, v55, v52
	v_and_b32_e32 v54, 64, v242
	v_add_f32_e32 v52, v48, v52
	v_xor_b32_e32 v53, 16, v242
	v_add_u32_e32 v54, 64, v54
	v_fmac_f32_e32 v120, v48, v48
	v_add_f32_e32 v52, v49, v52
	v_cmp_lt_i32_e32 vcc, v53, v54
	v_fmac_f32_e32 v120, v49, v49
	v_add_f32_e32 v52, v50, v52
	v_cndmask_b32_e32 v53, v242, v53, vcc
	v_fmac_f32_e32 v120, v50, v50
	v_add_f32_e32 v52, v51, v52
	v_lshlrev_b32_e32 v53, 2, v53
	v_fmac_f32_e32 v120, v51, v51
	ds_bpermute_b32 v55, v53, v52
	ds_bpermute_b32 v50, v53, v120
	v_xor_b32_e32 v49, 32, v242
	v_cmp_lt_i32_e32 vcc, v49, v54
	s_waitcnt lgkmcnt(1)
	v_add_f32_e32 v48, v52, v55
	v_cndmask_b32_e32 v49, v242, v49, vcc
	v_lshlrev_b32_e32 v51, 2, v49
	s_waitcnt lgkmcnt(0)
	v_add_f32_e32 v50, v120, v50
	ds_bpermute_b32 v49, v51, v48
	ds_bpermute_b32 v51, v51, v50
	s_and_saveexec_b64 s[2:3], s[38:39]
	s_cbranch_execz .LBB0_1188
	s_waitcnt lgkmcnt(0)
	v_add_f32_e32 v50, v50, v51
	v_add_f32_e32 v51, v48, v49
	v_lshl_add_u64 v[48:49], s[56:57], 0, v[140:141]
	global_atomic_add_f32 v[48:49], v51, off
	global_atomic_add_f32 v[48:49], v50, off offset:4

.LBB0_1189:
	v_pk_mul_f32 v[52:53], v[142:143], s[28:29] op_sel_hi:[1,0]
	s_waitcnt lgkmcnt(0)
	v_and_b32_e32 v51, 0xffff0000, v117
	v_fma_f32 v48, -v52, v52, v53
	v_max_f32_e32 v48, 0, v48
	v_add_f32_e32 v48, 0x3727c5ac, v48
	v_mul_f32_e32 v49, 0x4b800000, v48
	v_cmp_gt_f32_e32 vcc, s13, v48
	v_lshlrev_b32_e32 v56, 16, v118
	v_and_b32_e32 v57, 0xffff0000, v118
	v_cndmask_b32_e32 v48, v48, v49, vcc
	v_rsq_f32_e32 v48, v48
	v_lshlrev_b32_e32 v58, 16, v119
	v_lshlrev_b32_e32 v49, 16, v116
	v_and_b32_e32 v59, 0xffff0000, v119
	v_mul_f32_e32 v50, 0x45800000, v48
	v_cndmask_b32_e32 v53, v48, v50, vcc
	v_and_b32_e32 v48, 0xffff0000, v116
	v_sub_f32_e32 v48, v48, v52
	v_mul_f32_e32 v48, v48, v53
	v_lshlrev_b32_e32 v50, 16, v117
	v_fma_f32 v48, v89, v48, v93
	v_fmamk_f32 v45, v48, 0x3fb504f3, v45
	v_sub_f32_e32 v48, v50, v52
	v_mul_f32_e32 v48, v48, v53
	v_fma_f32 v48, v90, v48, v94
	v_fmamk_f32 v46, v48, 0x3fb504f3, v46
	v_sub_f32_e32 v48, v51, v52
	v_mul_f32_e32 v48, v48, v53
	v_fma_f32 v48, v91, v48, v95
	v_fmac_f32_e32 v47, 0x3fb504f3, v48
	v_sub_f32_e32 v48, v56, v52
	v_mul_f32_e32 v48, v48, v53
	v_fma_f32 v48, v80, v48, v84
	v_fmamk_f32 v40, v48, 0x3fb504f3, v40
	v_sub_f32_e32 v48, v57, v52
	v_mul_f32_e32 v48, v48, v53
	v_fma_f32 v48, v81, v48, v85
	v_fmamk_f32 v41, v48, 0x3fb504f3, v41
	v_sub_f32_e32 v48, v58, v52
	v_mul_f32_e32 v48, v48, v53
	v_fma_f32 v48, v82, v48, v86
	v_sub_f32_e32 v49, v49, v52
	v_fmamk_f32 v42, v48, 0x3fb504f3, v42
	v_sub_f32_e32 v48, v59, v52
	v_mul_f32_e32 v49, v49, v53
	v_mul_f32_e32 v48, v48, v53
	v_fma_f32 v49, v88, v49, v92
	v_fma_f32 v48, v83, v48, v87
	v_lshl_add_u64 v[54:55], v[208:209], 0, v[138:139]
	v_fmamk_f32 v44, v49, 0x3fb504f3, v44
	v_fmac_f32_e32 v43, 0x3fb504f3, v48
	v_cvt_pk_bf16_f32 v48, v44, v45
	v_cvt_pk_bf16_f32 v49, v46, v47
	v_cvt_pk_bf16_f32 v50, v40, v41
	v_cvt_pk_bf16_f32 v51, v42, v43
	global_store_dwordx4 v[54:55], v[48:51], off sc1
	v_lshlrev_b32_e32 v56, 16, v114
	v_and_b32_e32 v57, 0xffff0000, v114
	v_lshlrev_b32_e32 v48, 16, v112
	v_sub_f32_e32 v48, v48, v52
	v_mul_f32_e32 v48, v48, v53
	v_and_b32_e32 v49, 0xffff0000, v112
	v_fma_f32 v48, v72, v48, v76
	v_fmamk_f32 v36, v48, 0x3fb504f3, v36
	v_sub_f32_e32 v48, v49, v52
	v_mul_f32_e32 v48, v48, v53
	v_lshlrev_b32_e32 v50, 16, v113
	v_fma_f32 v48, v73, v48, v77
	v_fmamk_f32 v37, v48, 0x3fb504f3, v37
	v_sub_f32_e32 v48, v50, v52
	v_mul_f32_e32 v48, v48, v53
	v_and_b32_e32 v51, 0xffff0000, v113
	v_fma_f32 v48, v74, v48, v78
	v_fmamk_f32 v38, v48, 0x3fb504f3, v38
	v_sub_f32_e32 v48, v51, v52
	v_mul_f32_e32 v48, v48, v53
	v_fma_f32 v48, v75, v48, v79
	v_fmac_f32_e32 v39, 0x3fb504f3, v48
	v_sub_f32_e32 v48, v56, v52
	v_mul_f32_e32 v48, v48, v53
	v_fma_f32 v48, v64, v48, v68
	v_fmamk_f32 v32, v48, 0x3fb504f3, v32
	v_sub_f32_e32 v48, v57, v52
	v_mul_f32_e32 v48, v48, v53
	v_lshlrev_b32_e32 v58, 16, v115
	v_fma_f32 v48, v65, v48, v69
	v_fmamk_f32 v33, v48, 0x3fb504f3, v33
	v_sub_f32_e32 v48, v58, v52
	v_mul_f32_e32 v48, v48, v53
	v_and_b32_e32 v59, 0xffff0000, v115
	v_fma_f32 v48, v66, v48, v70
	v_fmamk_f32 v34, v48, 0x3fb504f3, v34
	v_sub_f32_e32 v48, v59, v52
	v_mul_f32_e32 v48, v48, v53
	v_fma_f32 v48, v67, v48, v71
	v_fmac_f32_e32 v35, 0x3fb504f3, v48
	s_and_b64 vcc, exec, s[42:43]
	v_cvt_pk_bf16_f32 v48, v36, v37
	v_cvt_pk_bf16_f32 v49, v38, v39
	v_cvt_pk_bf16_f32 v50, v32, v33
	v_cvt_pk_bf16_f32 v51, v34, v35
	global_store_dwordx4 v[54:55], v[48:51], off offset:256 sc1
	s_cbranch_vccnz .LBB0_1193
	s_nop 0
	v_mul_f32_e32 v48, v45, v45
	v_fmac_f32_e32 v48, v44, v44
	v_add_f32_e32 v44, 0, v44
	v_add_f32_e32 v44, v45, v44
	v_fmac_f32_e32 v48, v46, v46
	v_add_f32_e32 v44, v46, v44
	v_fmac_f32_e32 v48, v47, v47
	v_add_f32_e32 v44, v47, v44
	v_fmac_f32_e32 v48, v40, v40
	v_add_f32_e32 v40, v40, v44
	v_fmac_f32_e32 v48, v41, v41
	v_add_f32_e32 v40, v41, v40
	v_fmac_f32_e32 v48, v42, v42
	v_add_f32_e32 v40, v42, v40
	v_fmac_f32_e32 v48, v43, v43
	v_add_f32_e32 v40, v43, v40
	v_fmac_f32_e32 v48, v36, v36
	v_add_f32_e32 v36, v36, v40
	v_fmac_f32_e32 v48, v37, v37
	v_add_f32_e32 v36, v37, v36
	v_fmac_f32_e32 v48, v38, v38
	v_add_f32_e32 v36, v38, v36
	v_fmac_f32_e32 v48, v39, v39
	v_add_f32_e32 v36, v39, v36
	v_and_b32_e32 v38, 64, v242
	v_add_f32_e32 v36, v32, v36
	v_xor_b32_e32 v37, 16, v242
	v_add_u32_e32 v38, 64, v38
	v_fmac_f32_e32 v48, v32, v32
	v_add_f32_e32 v36, v33, v36
	v_cmp_lt_i32_e32 vcc, v37, v38
	v_fmac_f32_e32 v48, v33, v33
	v_add_f32_e32 v36, v34, v36
	v_cndmask_b32_e32 v37, v242, v37, vcc
	v_fmac_f32_e32 v48, v34, v34
	v_add_f32_e32 v36, v35, v36
	v_lshlrev_b32_e32 v37, 2, v37
	v_fmac_f32_e32 v48, v35, v35
	ds_bpermute_b32 v39, v37, v36
	ds_bpermute_b32 v34, v37, v48
	v_xor_b32_e32 v33, 32, v242
	v_cmp_lt_i32_e32 vcc, v33, v38
	s_waitcnt lgkmcnt(1)
	v_add_f32_e32 v32, v36, v39
	v_cndmask_b32_e32 v33, v242, v33, vcc
	v_lshlrev_b32_e32 v35, 2, v33
	s_waitcnt lgkmcnt(0)
	v_add_f32_e32 v34, v48, v34
	ds_bpermute_b32 v33, v35, v32
	ds_bpermute_b32 v35, v35, v34
	s_and_saveexec_b64 s[2:3], s[38:39]
	s_cbranch_execz .LBB0_1192
	s_waitcnt lgkmcnt(0)
	v_add_f32_e32 v34, v34, v35
	v_add_f32_e32 v35, v32, v33
	v_lshl_add_u64 v[32:33], s[56:57], 0, v[136:137]
	global_atomic_add_f32 v[32:33], v35, off
	global_atomic_add_f32 v[32:33], v34, off offset:4

.LBB0_1193:
	v_pk_mul_f32 v[36:37], v[134:135], s[28:29] op_sel_hi:[1,0]
	s_waitcnt lgkmcnt(0)
	v_and_b32_e32 v35, 0xffff0000, v109
	v_fma_f32 v32, -v36, v36, v37
	v_max_f32_e32 v32, 0, v32
	v_add_f32_e32 v32, 0x3727c5ac, v32
	v_mul_f32_e32 v33, 0x4b800000, v32
	v_cmp_gt_f32_e32 vcc, s13, v32
	v_lshlrev_b32_e32 v40, 16, v110
	v_and_b32_e32 v41, 0xffff0000, v110
	v_cndmask_b32_e32 v32, v32, v33, vcc
	v_rsq_f32_e32 v32, v32
	v_lshlrev_b32_e32 v42, 16, v111
	v_lshlrev_b32_e32 v33, 16, v108
	v_and_b32_e32 v43, 0xffff0000, v111
	v_mul_f32_e32 v34, 0x45800000, v32
	v_cndmask_b32_e32 v37, v32, v34, vcc
	v_and_b32_e32 v32, 0xffff0000, v108
	v_sub_f32_e32 v32, v32, v36
	v_mul_f32_e32 v32, v32, v37
	v_lshlrev_b32_e32 v34, 16, v109
	v_fma_f32 v32, v89, v32, v93
	v_fmamk_f32 v29, v32, 0x3fb504f3, v29
	v_sub_f32_e32 v32, v34, v36
	v_mul_f32_e32 v32, v32, v37
	v_fma_f32 v32, v90, v32, v94
	v_fmamk_f32 v30, v32, 0x3fb504f3, v30
	v_sub_f32_e32 v32, v35, v36
	v_mul_f32_e32 v32, v32, v37
	v_fma_f32 v32, v91, v32, v95
	v_fmac_f32_e32 v31, 0x3fb504f3, v32
	v_sub_f32_e32 v32, v40, v36
	v_mul_f32_e32 v32, v32, v37
	v_fma_f32 v32, v80, v32, v84
	v_fmamk_f32 v24, v32, 0x3fb504f3, v24
	v_sub_f32_e32 v32, v41, v36
	v_mul_f32_e32 v32, v32, v37
	v_fma_f32 v32, v81, v32, v85
	v_fmamk_f32 v25, v32, 0x3fb504f3, v25
	v_sub_f32_e32 v32, v42, v36
	v_mul_f32_e32 v32, v32, v37
	v_fma_f32 v32, v82, v32, v86
	v_sub_f32_e32 v33, v33, v36
	v_fmamk_f32 v26, v32, 0x3fb504f3, v26
	v_sub_f32_e32 v32, v43, v36
	v_mul_f32_e32 v33, v33, v37
	v_mul_f32_e32 v32, v32, v37
	v_fma_f32 v33, v88, v33, v92
	v_fma_f32 v32, v83, v32, v87
	v_lshl_add_u64 v[38:39], v[208:209], 0, v[132:133]
	v_fmamk_f32 v28, v33, 0x3fb504f3, v28
	v_fmac_f32_e32 v27, 0x3fb504f3, v32
	v_cvt_pk_bf16_f32 v32, v28, v29
	v_cvt_pk_bf16_f32 v33, v30, v31
	v_cvt_pk_bf16_f32 v34, v24, v25
	v_cvt_pk_bf16_f32 v35, v26, v27
	global_store_dwordx4 v[38:39], v[32:35], off sc1
	v_lshlrev_b32_e32 v40, 16, v106
	v_and_b32_e32 v41, 0xffff0000, v106
	v_lshlrev_b32_e32 v32, 16, v104
	v_sub_f32_e32 v32, v32, v36
	v_mul_f32_e32 v32, v32, v37
	v_and_b32_e32 v33, 0xffff0000, v104
	v_fma_f32 v32, v72, v32, v76
	v_fmamk_f32 v20, v32, 0x3fb504f3, v20
	v_sub_f32_e32 v32, v33, v36
	v_mul_f32_e32 v32, v32, v37
	v_lshlrev_b32_e32 v34, 16, v105
	v_fma_f32 v32, v73, v32, v77
	v_fmamk_f32 v21, v32, 0x3fb504f3, v21
	v_sub_f32_e32 v32, v34, v36
	v_mul_f32_e32 v32, v32, v37
	v_and_b32_e32 v35, 0xffff0000, v105
	v_fma_f32 v32, v74, v32, v78
	v_fmamk_f32 v22, v32, 0x3fb504f3, v22
	v_sub_f32_e32 v32, v35, v36
	v_mul_f32_e32 v32, v32, v37
	v_fma_f32 v32, v75, v32, v79
	v_fmac_f32_e32 v23, 0x3fb504f3, v32
	v_sub_f32_e32 v32, v40, v36
	v_mul_f32_e32 v32, v32, v37
	v_fma_f32 v32, v64, v32, v68
	v_fmamk_f32 v16, v32, 0x3fb504f3, v16
	v_sub_f32_e32 v32, v41, v36
	v_mul_f32_e32 v32, v32, v37
	v_lshlrev_b32_e32 v42, 16, v107
	v_fma_f32 v32, v65, v32, v69
	v_fmamk_f32 v17, v32, 0x3fb504f3, v17
	v_sub_f32_e32 v32, v42, v36
	v_mul_f32_e32 v32, v32, v37
	v_and_b32_e32 v43, 0xffff0000, v107
	v_fma_f32 v32, v66, v32, v70
	v_fmamk_f32 v18, v32, 0x3fb504f3, v18
	v_sub_f32_e32 v32, v43, v36
	v_mul_f32_e32 v32, v32, v37
	v_fma_f32 v32, v67, v32, v71
	v_fmac_f32_e32 v19, 0x3fb504f3, v32
	s_and_b64 vcc, exec, s[42:43]
	v_cvt_pk_bf16_f32 v32, v20, v21
	v_cvt_pk_bf16_f32 v33, v22, v23
	v_cvt_pk_bf16_f32 v34, v16, v17
	v_cvt_pk_bf16_f32 v35, v18, v19
	global_store_dwordx4 v[38:39], v[32:35], off offset:256 sc1
	s_cbranch_vccnz .LBB0_1197
	s_nop 0
	v_mul_f32_e32 v32, v29, v29
	v_fmac_f32_e32 v32, v28, v28
	v_add_f32_e32 v28, 0, v28
	v_add_f32_e32 v28, v29, v28
	v_fmac_f32_e32 v32, v30, v30
	v_add_f32_e32 v28, v30, v28
	v_fmac_f32_e32 v32, v31, v31
	v_add_f32_e32 v28, v31, v28
	v_fmac_f32_e32 v32, v24, v24
	v_add_f32_e32 v24, v24, v28
	v_fmac_f32_e32 v32, v25, v25
	v_add_f32_e32 v24, v25, v24
	v_fmac_f32_e32 v32, v26, v26
	v_add_f32_e32 v24, v26, v24
	v_fmac_f32_e32 v32, v27, v27
	v_add_f32_e32 v24, v27, v24
	v_fmac_f32_e32 v32, v20, v20
	v_add_f32_e32 v20, v20, v24
	v_fmac_f32_e32 v32, v21, v21
	v_add_f32_e32 v20, v21, v20
	v_fmac_f32_e32 v32, v22, v22
	v_add_f32_e32 v20, v22, v20
	v_fmac_f32_e32 v32, v23, v23
	v_add_f32_e32 v20, v23, v20
	v_and_b32_e32 v22, 64, v242
	v_add_f32_e32 v20, v16, v20
	v_xor_b32_e32 v21, 16, v242
	v_add_u32_e32 v22, 64, v22
	v_fmac_f32_e32 v32, v16, v16
	v_add_f32_e32 v20, v17, v20
	v_cmp_lt_i32_e32 vcc, v21, v22
	v_fmac_f32_e32 v32, v17, v17
	v_add_f32_e32 v20, v18, v20
	v_cndmask_b32_e32 v21, v242, v21, vcc
	v_fmac_f32_e32 v32, v18, v18
	v_add_f32_e32 v20, v19, v20
	v_lshlrev_b32_e32 v21, 2, v21
	v_fmac_f32_e32 v32, v19, v19
	ds_bpermute_b32 v23, v21, v20
	ds_bpermute_b32 v18, v21, v32
	v_xor_b32_e32 v17, 32, v242
	v_cmp_lt_i32_e32 vcc, v17, v22
	s_waitcnt lgkmcnt(1)
	v_add_f32_e32 v16, v20, v23
	v_cndmask_b32_e32 v17, v242, v17, vcc
	v_lshlrev_b32_e32 v19, 2, v17
	s_waitcnt lgkmcnt(0)
	v_add_f32_e32 v18, v32, v18
	ds_bpermute_b32 v17, v19, v16
	ds_bpermute_b32 v19, v19, v18
	s_and_saveexec_b64 s[2:3], s[38:39]
	s_cbranch_execz .LBB0_1196
	s_waitcnt lgkmcnt(0)
	v_add_f32_e32 v18, v18, v19
	v_add_f32_e32 v19, v16, v17
	v_lshl_add_u64 v[16:17], s[56:57], 0, v[130:131]
	global_atomic_add_f32 v[16:17], v19, off
	global_atomic_add_f32 v[16:17], v18, off offset:4

.LBB0_1197:
	v_pk_mul_f32 v[20:21], v[128:129], s[28:29] op_sel_hi:[1,0]
	s_waitcnt lgkmcnt(0)
	v_and_b32_e32 v19, 0xffff0000, v101
	v_fma_f32 v16, -v20, v20, v21
	v_max_f32_e32 v16, 0, v16
	v_add_f32_e32 v16, 0x3727c5ac, v16
	v_mul_f32_e32 v17, 0x4b800000, v16
	v_cmp_gt_f32_e32 vcc, s13, v16
	v_lshlrev_b32_e32 v24, 16, v102
	v_and_b32_e32 v25, 0xffff0000, v102
	v_cndmask_b32_e32 v16, v16, v17, vcc
	v_rsq_f32_e32 v16, v16
	v_lshlrev_b32_e32 v26, 16, v103
	v_lshlrev_b32_e32 v17, 16, v100
	v_and_b32_e32 v27, 0xffff0000, v103
	v_mul_f32_e32 v18, 0x45800000, v16
	v_cndmask_b32_e32 v21, v16, v18, vcc
	v_and_b32_e32 v16, 0xffff0000, v100
	v_sub_f32_e32 v16, v16, v20
	v_mul_f32_e32 v16, v16, v21
	v_lshlrev_b32_e32 v18, 16, v101
	v_fma_f32 v16, v89, v16, v93
	v_fmamk_f32 v13, v16, 0x3fb504f3, v13
	v_sub_f32_e32 v16, v18, v20
	v_mul_f32_e32 v16, v16, v21
	v_fma_f32 v16, v90, v16, v94
	v_fmamk_f32 v14, v16, 0x3fb504f3, v14
	v_sub_f32_e32 v16, v19, v20
	v_mul_f32_e32 v16, v16, v21
	v_fmac_f32_e32 v95, v91, v16
	v_sub_f32_e32 v16, v24, v20
	v_mul_f32_e32 v16, v16, v21
	v_fma_f32 v16, v80, v16, v84
	v_fmamk_f32 v8, v16, 0x3fb504f3, v8
	v_sub_f32_e32 v16, v25, v20
	v_mul_f32_e32 v16, v16, v21
	v_fma_f32 v16, v81, v16, v85
	v_fmamk_f32 v9, v16, 0x3fb504f3, v9
	v_sub_f32_e32 v16, v26, v20
	v_mul_f32_e32 v16, v16, v21
	v_sub_f32_e32 v17, v17, v20
	v_fma_f32 v16, v82, v16, v86
	v_mul_f32_e32 v17, v17, v21
	v_fmamk_f32 v10, v16, 0x3fb504f3, v10
	v_sub_f32_e32 v16, v27, v20
	v_fma_f32 v17, v88, v17, v92
	v_mul_f32_e32 v16, v16, v21
	v_lshl_add_u64 v[22:23], v[208:209], 0, v[126:127]
	v_fmamk_f32 v12, v17, 0x3fb504f3, v12
	v_fmac_f32_e32 v87, v83, v16
	v_cvt_pk_bf16_f32 v16, v12, v13
	v_fmac_f32_e32 v15, 0x3fb504f3, v95
	v_fmac_f32_e32 v11, 0x3fb504f3, v87
	v_cvt_pk_bf16_f32 v17, v14, v15
	v_cvt_pk_bf16_f32 v18, v8, v9
	v_cvt_pk_bf16_f32 v19, v10, v11
	global_store_dwordx4 v[22:23], v[16:19], off sc1
	v_lshlrev_b32_e32 v24, 16, v98
	v_and_b32_e32 v25, 0xffff0000, v98
	v_lshlrev_b32_e32 v16, 16, v96
	v_sub_f32_e32 v16, v16, v20
	v_mul_f32_e32 v16, v16, v21
	v_and_b32_e32 v17, 0xffff0000, v96
	v_fma_f32 v16, v72, v16, v76
	v_fmamk_f32 v4, v16, 0x3fb504f3, v4
	v_sub_f32_e32 v16, v17, v20
	v_mul_f32_e32 v16, v16, v21
	v_lshlrev_b32_e32 v18, 16, v97
	v_fma_f32 v16, v73, v16, v77
	v_fmamk_f32 v5, v16, 0x3fb504f3, v5
	v_sub_f32_e32 v16, v18, v20
	v_mul_f32_e32 v16, v16, v21
	v_and_b32_e32 v19, 0xffff0000, v97
	v_fma_f32 v16, v74, v16, v78
	v_fmamk_f32 v6, v16, 0x3fb504f3, v6
	v_sub_f32_e32 v16, v19, v20
	v_mul_f32_e32 v16, v16, v21
	v_fmac_f32_e32 v79, v75, v16
	v_sub_f32_e32 v16, v24, v20
	v_mul_f32_e32 v16, v16, v21
	v_fma_f32 v16, v64, v16, v68
	v_fmamk_f32 v0, v16, 0x3fb504f3, v0
	v_sub_f32_e32 v16, v25, v20
	v_mul_f32_e32 v16, v16, v21
	v_lshlrev_b32_e32 v26, 16, v99
	v_fma_f32 v16, v65, v16, v69
	v_fmamk_f32 v1, v16, 0x3fb504f3, v1
	v_sub_f32_e32 v16, v26, v20
	v_mul_f32_e32 v16, v16, v21
	v_and_b32_e32 v27, 0xffff0000, v99
	v_fma_f32 v16, v66, v16, v70
	v_fmamk_f32 v2, v16, 0x3fb504f3, v2
	v_sub_f32_e32 v16, v27, v20
	v_mul_f32_e32 v16, v16, v21
	v_fmac_f32_e32 v71, v67, v16
	v_fmac_f32_e32 v7, 0x3fb504f3, v79
	v_fmac_f32_e32 v3, 0x3fb504f3, v71
	s_and_b64 vcc, exec, s[42:43]
	v_cvt_pk_bf16_f32 v16, v4, v5
	v_cvt_pk_bf16_f32 v17, v6, v7
	v_cvt_pk_bf16_f32 v18, v0, v1
	v_cvt_pk_bf16_f32 v19, v2, v3
	global_store_dwordx4 v[22:23], v[16:19], off offset:256 sc1
	s_cbranch_vccnz .LBB0_1160
	s_nop 0
	v_mul_f32_e32 v16, v13, v13
	v_fmac_f32_e32 v16, v12, v12
	v_add_f32_e32 v12, 0, v12
	v_add_f32_e32 v12, v13, v12
	v_fmac_f32_e32 v16, v14, v14
	v_add_f32_e32 v12, v14, v12
	v_fmac_f32_e32 v16, v15, v15
	v_add_f32_e32 v12, v15, v12
	v_fmac_f32_e32 v16, v8, v8
	v_add_f32_e32 v8, v8, v12
	v_fmac_f32_e32 v16, v9, v9
	v_add_f32_e32 v8, v9, v8
	v_fmac_f32_e32 v16, v10, v10
	v_add_f32_e32 v8, v10, v8
	v_fmac_f32_e32 v16, v11, v11
	v_add_f32_e32 v8, v11, v8
	v_fmac_f32_e32 v16, v4, v4
	v_add_f32_e32 v4, v4, v8
	v_fmac_f32_e32 v16, v5, v5
	v_add_f32_e32 v4, v5, v4
	v_fmac_f32_e32 v16, v6, v6
	v_add_f32_e32 v4, v6, v4
	v_fmac_f32_e32 v16, v7, v7
	v_add_f32_e32 v4, v7, v4
	v_and_b32_e32 v6, 64, v242
	v_add_f32_e32 v4, v0, v4
	v_xor_b32_e32 v5, 16, v242
	v_add_u32_e32 v6, 64, v6
	v_fmac_f32_e32 v16, v0, v0
	v_add_f32_e32 v4, v1, v4
	v_cmp_lt_i32_e32 vcc, v5, v6
	v_fmac_f32_e32 v16, v1, v1
	v_add_f32_e32 v4, v2, v4
	v_cndmask_b32_e32 v5, v242, v5, vcc
	v_fmac_f32_e32 v16, v2, v2
	v_add_f32_e32 v4, v3, v4
	v_lshlrev_b32_e32 v5, 2, v5
	v_fmac_f32_e32 v16, v3, v3
	ds_bpermute_b32 v7, v5, v4
	ds_bpermute_b32 v2, v5, v16
	v_xor_b32_e32 v1, 32, v242
	v_cmp_lt_i32_e32 vcc, v1, v6
	s_waitcnt lgkmcnt(1)
	v_add_f32_e32 v0, v4, v7
	v_cndmask_b32_e32 v1, v242, v1, vcc
	v_lshlrev_b32_e32 v3, 2, v1
	s_waitcnt lgkmcnt(0)
	v_add_f32_e32 v2, v16, v2
	ds_bpermute_b32 v1, v3, v0
	ds_bpermute_b32 v3, v3, v2
	s_and_saveexec_b64 s[2:3], s[38:39]
	s_cbranch_execz .LBB0_1159
	s_waitcnt lgkmcnt(0)
	v_add_f32_e32 v2, v2, v3
	v_add_f32_e32 v3, v0, v1
	v_lshl_add_u64 v[0:1], s[56:57], 0, v[124:125]
	global_atomic_add_f32 v[0:1], v3, off
	global_atomic_add_f32 v[0:1], v2, off offset:4
	s_branch .LBB0_1159
